# rg backward scan output: token pairs packed by one cvt_pk, stored with short + short_d16_hi at offset 2048 (half the pointer steps)
# speedup vs baseline: 1.0038x; 1.0038x over previous
; #define LAS __attribute__((address_space(3)))
; template <bool FINAL>
; __device__ __forceinline__ void rg_item(PREF p, int l, int item, LAS unsigned char* wl, int lane) {
;     const bf16_t* __restrict__ P = (const bf16_t*)(p.ws + WS_GP);
;     const int h = item & 7, rest = item >> 3;
;     const int ci = rest < 512 ? 4 + (rest & 255) : ((rest - 512) & 3), b = rest < 512 ? (rest >> 8) : ((rest - 512) >> 2);
;     const int seq_row0 = ci < 4 ? TL + b * 256 : b * 16384;
;     const int t0 = ci < 4 ? ci * 64 : (ci - 4) * 64;
;     const int seqlen = ci < 4 ? 256 : 16384;
;     const int ch = h * 64 + lane;
;     LAS bf16_t* sXc = (LAS bf16_t*)wl;
;     LAS float* stg = (LAS float*)(wl + 9216);
;     {
;         const float cw0 = p.conv_w[(l * 4 + 0) * 512 + ch], cw1 = p.conv_w[(l * 4 + 1) * 512 + ch], cw2 = p.conv_w[(l * 4 + 2) * 512 + ch], cw3 = p.conv_w[(l * 4 + 3) * 512 + ch];
;         const float cb = p.conv_b[l * 512 + ch];
;         float xv[67]; unsigned xr_[67];
; #pragma unroll
;         for (int i = 0; i < 67; ++i) { const int t = t0 - 2 + i; const int tc = t < 0 ? 0 : (t >= seqlen ? seqlen - 1 : t);
;             xr_[i] = P[(size_t)(seq_row0 + tc) * PW + ch]; }
.Lrg7_dec:
	s_add_i32 s15, s11, s10
	s_mul_i32 s36, s9, 0x104
	s_add_i32 s36, s36, s8
	s_lshl_b32 s36, s36, 12
	s_cmp_eq_u32 s10, 0
	s_cselect_b32 s37, 0, -1
	s_add_i32 s38, s10, 64
	s_cmp_eq_u32 s38, s14
	s_cselect_b32 s38, 0, -1
	s_bfe_u32 s44, s44, 0x30006
	s_mul_i32 s44, s44, 0x4800
	v_lshl_or_b32 v234, s7, 6, v233
	v_lshlrev_b32_e32 v235, 2, v234
	v_lshlrev_b32_e32 v234, 1, v234
	v_and_b32_e32 v236, 15, v233
	v_lshrrev_b32_e32 v241, 4, v233
	s_movk_i32 s39, 0x90
	v_mul_u32_u24_e32 v237, 0x90, v236
	v_lshl_add_u32 v237, v241, 4, v237
	v_lshlrev_b32_e32 v238, 7, v236
	v_lshl_add_u32 v238, v241, 4, v238
	v_lshlrev_b32_e32 v239, 10, v241
	v_lshl_add_u32 v239, v236, 2, v239
	v_mov_b32_e32 v241, v238
	v_add_u32_e32 v236, s44, v237
	s_add_i32 s39, s44, 0x2400
	v_add_u32_e32 v237, s39, v239
	v_add_u32_e32 v238, 0x1000, v237
	v_lshl_add_u32 v239, v233, 2, s44
	v_lshl_add_u32 v240, v233, 1, s44
	s_add_i32 s39, s15, -2
	s_mul_hi_i32 s83, s39, 0x1600
	s_mul_i32 s82, s39, 0x1600
	s_waitcnt lgkmcnt(0)
	s_add_u32 s82, s82, s0
	s_addc_u32 s83, s83, s1
	s_add_u32 s82, s82, 0xbc00000
	s_addc_u32 s83, s83, 0
	global_load_ushort v158, v234, s[82:83]
	s_add_u32 s82, s82, 0x1600
	s_addc_u32 s83, s83, 0
	global_load_ushort v159, v234, s[82:83]
	s_add_u32 s82, s82, 0x1600
	s_addc_u32 s83, s83, 0
	global_load_ushort v160, v234, s[82:83]
	s_add_u32 s82, s82, 0x1600
	s_addc_u32 s83, s83, 0
	global_load_ushort v161, v234, s[82:83]
	s_add_u32 s82, s82, 0x1600
	s_addc_u32 s83, s83, 0
	global_load_ushort v162, v234, s[82:83]
	s_add_u32 s82, s82, 0x1600
	s_addc_u32 s83, s83, 0
	global_load_ushort v163, v234, s[82:83]
	s_add_u32 s82, s82, 0x1600
	s_addc_u32 s83, s83, 0
	global_load_ushort v164, v234, s[82:83]
	s_add_u32 s82, s82, 0x1600
	s_addc_u32 s83, s83, 0
	global_load_ushort v165, v234, s[82:83]
	s_add_u32 s82, s82, 0x1600
	s_addc_u32 s83, s83, 0
	global_load_ushort v166, v234, s[82:83]
	s_add_u32 s82, s82, 0x1600
	s_addc_u32 s83, s83, 0
	global_load_ushort v167, v234, s[82:83]
	s_add_u32 s82, s82, 0x1600
	s_addc_u32 s83, s83, 0
	global_load_ushort v168, v234, s[82:83]
	s_add_u32 s82, s82, 0x1600
	s_addc_u32 s83, s83, 0
	global_load_ushort v169, v234, s[82:83]
	s_add_u32 s82, s82, 0x1600
	s_addc_u32 s83, s83, 0
	global_load_ushort v170, v234, s[82:83]
	s_add_u32 s82, s82, 0x1600
	s_addc_u32 s83, s83, 0
	global_load_ushort v171, v234, s[82:83]
	s_add_u32 s82, s82, 0x1600
	s_addc_u32 s83, s83, 0
	global_load_ushort v172, v234, s[82:83]
	s_add_u32 s82, s82, 0x1600
	s_addc_u32 s83, s83, 0
	global_load_ushort v173, v234, s[82:83]
	s_add_u32 s82, s82, 0x1600
	s_addc_u32 s83, s83, 0
	global_load_ushort v174, v234, s[82:83]
	s_add_u32 s82, s82, 0x1600
	s_addc_u32 s83, s83, 0
	global_load_ushort v175, v234, s[82:83]
	s_add_u32 s82, s82, 0x1600
	s_addc_u32 s83, s83, 0
	global_load_ushort v176, v234, s[82:83]
	s_add_u32 s82, s82, 0x1600
	s_addc_u32 s83, s83, 0
	global_load_ushort v177, v234, s[82:83]
	s_add_u32 s82, s82, 0x1600
	s_addc_u32 s83, s83, 0
	global_load_ushort v178, v234, s[82:83]
	s_add_u32 s82, s82, 0x1600
	s_addc_u32 s83, s83, 0
	global_load_ushort v179, v234, s[82:83]
	s_add_u32 s82, s82, 0x1600
	s_addc_u32 s83, s83, 0
	global_load_ushort v180, v234, s[82:83]
	s_add_u32 s82, s82, 0x1600
	s_addc_u32 s83, s83, 0
	global_load_ushort v181, v234, s[82:83]
	s_add_u32 s82, s82, 0x1600
	s_addc_u32 s83, s83, 0
	global_load_ushort v182, v234, s[82:83]
	s_add_u32 s82, s82, 0x1600
	s_addc_u32 s83, s83, 0
	global_load_ushort v183, v234, s[82:83]
	s_add_u32 s82, s82, 0x1600
	s_addc_u32 s83, s83, 0
	global_load_ushort v184, v234, s[82:83]
	s_add_u32 s82, s82, 0x1600
	s_addc_u32 s83, s83, 0
	global_load_ushort v185, v234, s[82:83]
	s_add_u32 s82, s82, 0x1600
	s_addc_u32 s83, s83, 0
	global_load_ushort v186, v234, s[82:83]
	s_add_u32 s82, s82, 0x1600
	s_addc_u32 s83, s83, 0
	global_load_ushort v187, v234, s[82:83]
	s_add_u32 s82, s82, 0x1600
	s_addc_u32 s83, s83, 0
	global_load_ushort v188, v234, s[82:83]
	s_add_u32 s82, s82, 0x1600
	s_addc_u32 s83, s83, 0
	global_load_ushort v189, v234, s[82:83]
	s_add_u32 s82, s82, 0x1600
	s_addc_u32 s83, s83, 0
	global_load_ushort v190, v234, s[82:83]
	s_add_u32 s82, s82, 0x1600
	s_addc_u32 s83, s83, 0
	global_load_ushort v191, v234, s[82:83]
	s_add_u32 s82, s82, 0x1600
	s_addc_u32 s83, s83, 0
	global_load_ushort v192, v234, s[82:83]
	s_add_u32 s82, s82, 0x1600
	s_addc_u32 s83, s83, 0
	global_load_ushort v193, v234, s[82:83]
	s_add_u32 s82, s82, 0x1600
	s_addc_u32 s83, s83, 0
	global_load_ushort v194, v234, s[82:83]
	s_add_u32 s82, s82, 0x1600
	s_addc_u32 s83, s83, 0
	global_load_ushort v195, v234, s[82:83]
	s_add_u32 s82, s82, 0x1600
	s_addc_u32 s83, s83, 0
	global_load_ushort v196, v234, s[82:83]
	s_add_u32 s82, s82, 0x1600
	s_addc_u32 s83, s83, 0
	global_load_ushort v197, v234, s[82:83]
	s_add_u32 s82, s82, 0x1600
	s_addc_u32 s83, s83, 0
	global_load_ushort v198, v234, s[82:83]
	s_add_u32 s82, s82, 0x1600
	s_addc_u32 s83, s83, 0
	global_load_ushort v199, v234, s[82:83]
	s_add_u32 s82, s82, 0x1600
	s_addc_u32 s83, s83, 0
	global_load_ushort v200, v234, s[82:83]
	s_add_u32 s82, s82, 0x1600
	s_addc_u32 s83, s83, 0
	global_load_ushort v201, v234, s[82:83]
	s_add_u32 s82, s82, 0x1600
	s_addc_u32 s83, s83, 0
	global_load_ushort v202, v234, s[82:83]
	s_add_u32 s82, s82, 0x1600
	s_addc_u32 s83, s83, 0
	global_load_ushort v203, v234, s[82:83]
	s_add_u32 s82, s82, 0x1600
	s_addc_u32 s83, s83, 0
	global_load_ushort v204, v234, s[82:83]
	s_add_u32 s82, s82, 0x1600
	s_addc_u32 s83, s83, 0
	global_load_ushort v205, v234, s[82:83]
	s_add_u32 s82, s82, 0x1600
	s_addc_u32 s83, s83, 0
	global_load_ushort v206, v234, s[82:83]
	s_add_u32 s82, s82, 0x1600
; __device__ __forceinline__ float rcpf_(float x) { return __builtin_amdgcn_rcpf(x); }
; template <bool FINAL, int D>
; __device__ __forceinline__ void rg_dir(PREF p, int l, int h, int ch, int sidx, int rowbase  , LAS bf16_t* sXc, LAS float* stg, int lane) {
;     ...
;     const bf16_t* wr_ = WgT + (size_t)(((l * 2 + D) * 2 + 0) * 8 + h) * 4096; const bf16_t* wi_ = WgT + (size_t)(((l * 2 + D) * 2 + 1) * 8 + h) * 4096;
;     const float ba = p.rg_ba[(l * 2 + D) * 512 + ch], bi = p.rg_bi[(l * 2 + D) * 512 + ch], lam = p.rg_lam[(l * 2 + D) * 512 + ch];
;     const float e_ = __expf(-lam), u_ = 1.f + e_;
;     const float l1p = (u_ == 1.f) ? e_ : __logf(u_) * e_ * rcpf_(u_ - 1.f);
;     const float sp8 = -8.f * 1.4426950408889634f * l1p;
;     float hc = FINAL ? RGC[sidx] : 0.f, Ap = 1.f;
;     bf16x8 Br[4][2], Bi[4][2];
; #pragma unroll
;     for (int nt = 0; nt < 4; ++nt) { const int o0 = (nt * 16 + (lane & 15)) * 64 + (lane >> 4) * 8;
;         Br[nt][0] = *(const bf16x8*)(wr_ + o0); Br[nt][1] = *(const bf16x8*)(wr_ + o0 + 32); Bi[nt][0] = *(const bf16x8*)(wi_ + o0); Bi[nt][1] = *(const bf16x8*)(wi_ + o0 + 32); }
; template <bool FINAL>
; __device__ __forceinline__ void rg_item(PREF p, int l, int item, LAS unsigned char* wl, int lane) {
;     ...
;         const float cw0 = p.conv_w[(l * 4 + 0) * 512 + ch], cw1 = p.conv_w[(l * 4 + 1) * 512 + ch], cw2 = p.conv_w[(l * 4 + 2) * 512 + ch], cw3 = p.conv_w[(l * 4 + 3) * 512 + ch];
;         const float cb = p.conv_b[l * 512 + ch];
;         float xv[67]; unsigned xr_[67];
; #pragma unroll
;         for (int i = 0; i < 67; ++i) { const int t = t0 - 2 + i; const int tc = t < 0 ? 0 : (t >= seqlen ? seqlen - 1 : t);
;             xr_[i] = P[(size_t)(seq_row0 + tc) * PW + ch]; }
	s_addc_u32 s83, s83, 0
	global_load_ushort v207, v234, s[82:83]
	s_add_u32 s82, s82, 0x1600
	s_addc_u32 s83, s83, 0
	global_load_ushort v208, v234, s[82:83]
	s_add_u32 s82, s82, 0x1600
	s_addc_u32 s83, s83, 0
	global_load_ushort v209, v234, s[82:83]
	s_add_u32 s82, s82, 0x1600
	s_addc_u32 s83, s83, 0
	global_load_ushort v210, v234, s[82:83]
	s_add_u32 s82, s82, 0x1600
	s_addc_u32 s83, s83, 0
	global_load_ushort v211, v234, s[82:83]
	s_add_u32 s82, s82, 0x1600
	s_addc_u32 s83, s83, 0
	global_load_ushort v212, v234, s[82:83]
	s_add_u32 s82, s82, 0x1600
	s_addc_u32 s83, s83, 0
	global_load_ushort v213, v234, s[82:83]
	s_add_u32 s82, s82, 0x1600
	s_addc_u32 s83, s83, 0
	global_load_ushort v214, v234, s[82:83]
	s_add_u32 s82, s82, 0x1600
	s_addc_u32 s83, s83, 0
	global_load_ushort v215, v234, s[82:83]
	s_add_u32 s82, s82, 0x1600
	s_addc_u32 s83, s83, 0
	global_load_ushort v216, v234, s[82:83]
	s_add_u32 s82, s82, 0x1600
	s_addc_u32 s83, s83, 0
	global_load_ushort v217, v234, s[82:83]
	s_add_u32 s82, s82, 0x1600
	s_addc_u32 s83, s83, 0
	global_load_ushort v218, v234, s[82:83]
	s_add_u32 s82, s82, 0x1600
	s_addc_u32 s83, s83, 0
	global_load_ushort v219, v234, s[82:83]
	s_add_u32 s82, s82, 0x1600
	s_addc_u32 s83, s83, 0
	global_load_ushort v222, v234, s[82:83]
	s_add_u32 s82, s82, 0x1600
	s_addc_u32 s83, s83, 0
	global_load_ushort v223, v234, s[82:83]
	s_add_u32 s82, s82, 0x1600
	s_addc_u32 s83, s83, 0
	global_load_ushort v140, v234, s[82:83]
	s_add_u32 s82, s82, 0x1600
	s_addc_u32 s83, s83, 0
	global_load_ushort v141, v234, s[82:83]
	s_add_u32 s82, s82, 0x1600
	s_addc_u32 s83, s83, 0
	global_load_ushort v232, v234, s[82:83]
	s_lshl_b32 s39, s47, 13
	s_add_u32 s72, s72, s39
	s_addc_u32 s73, s73, 0
	global_load_dword v40, v235, s[72:73]
	global_load_dword v41, v235, s[72:73] offset:2048
	s_add_u32 s72, s72, 0x1000
	s_addc_u32 s73, s73, 0
	global_load_dword v42, v235, s[72:73]
	global_load_dword v43, v235, s[72:73] offset:2048
	s_lshl_b32 s39, s47, 11
	s_add_u32 s74, s74, s39
	s_addc_u32 s75, s75, 0
	global_load_dword v44, v235, s[74:75]
	s_lshl_b32 s39, s47, 12
	s_add_u32 s76, s76, s39
	s_addc_u32 s77, s77, 0
	s_add_u32 s78, s78, s39
	s_addc_u32 s79, s79, 0
	s_add_u32 s80, s80, s39
	s_addc_u32 s81, s81, 0
	s_add_u32 s96, s0, 0xa00000
	s_addc_u32 s97, s1, 0
	s_add_u32 s96, s96, s36
	s_addc_u32 s97, s97, 0
	s_lshl_b32 s39, s47, 5
	s_add_i32 s39, s39, s7
	s_lshl_b32 s39, s39, 13
	s_add_u32 s92, s0, 0x300000
	s_addc_u32 s93, s1, 0
	s_add_u32 s92, s92, s39
	s_addc_u32 s93, s93, 0
	global_load_dword v45, v235, s[76:77]
	global_load_dword v46, v235, s[78:79]
	global_load_dword v47, v235, s[80:81]
	global_load_dword v250, v235, s[96:97]
	s_add_u32 s90, s92, 0x0
	s_addc_u32 s91, s93, 0
	global_load_dwordx4 v[80:83], v241, s[90:91]
	global_load_dwordx4 v[84:87], v241, s[90:91] offset:64
	global_load_dwordx4 v[88:91], v241, s[90:91] offset:2048
	global_load_dwordx4 v[92:95], v241, s[90:91] offset:2112
	s_add_u32 s90, s92, 0x1000
	s_addc_u32 s91, s93, 0
	global_load_dwordx4 v[96:99], v241, s[90:91]
	global_load_dwordx4 v[100:103], v241, s[90:91] offset:64
	global_load_dwordx4 v[104:107], v241, s[90:91] offset:2048
	global_load_dwordx4 v[108:111], v241, s[90:91] offset:2112
	s_add_u32 s90, s92, 0x10000
	s_addc_u32 s91, s93, 0
	global_load_dwordx4 v[112:115], v241, s[90:91]
	global_load_dwordx4 v[116:119], v241, s[90:91] offset:64
	global_load_dwordx4 v[120:123], v241, s[90:91] offset:2048
	global_load_dwordx4 v[124:127], v241, s[90:91] offset:2112
	s_add_u32 s90, s92, 0x11000
	s_addc_u32 s91, s93, 0
	global_load_dwordx4 v[128:131], v241, s[90:91]
	global_load_dwordx4 v[132:135], v241, s[90:91] offset:64
	global_load_dwordx4 v[136:139], v241, s[90:91] offset:2048
	global_load_dwordx4 v[228:231], v241, s[90:91] offset:2112
	s_waitcnt vmcnt(20)
	v_lshlrev_b32_e32 v158, 16, v158
	v_lshlrev_b32_e32 v159, 16, v159
	v_lshlrev_b32_e32 v160, 16, v160
	v_lshlrev_b32_e32 v161, 16, v161
	v_lshlrev_b32_e32 v162, 16, v162
	v_lshlrev_b32_e32 v163, 16, v163
	v_lshlrev_b32_e32 v164, 16, v164
	v_lshlrev_b32_e32 v165, 16, v165
	v_lshlrev_b32_e32 v166, 16, v166
	v_lshlrev_b32_e32 v167, 16, v167
	v_lshlrev_b32_e32 v168, 16, v168
	v_lshlrev_b32_e32 v169, 16, v169
	v_lshlrev_b32_e32 v170, 16, v170
	v_lshlrev_b32_e32 v171, 16, v171
	v_lshlrev_b32_e32 v172, 16, v172
	v_lshlrev_b32_e32 v173, 16, v173
	v_lshlrev_b32_e32 v174, 16, v174
	v_lshlrev_b32_e32 v175, 16, v175
	v_lshlrev_b32_e32 v176, 16, v176
	v_lshlrev_b32_e32 v177, 16, v177
	v_lshlrev_b32_e32 v178, 16, v178
	v_lshlrev_b32_e32 v179, 16, v179
	v_lshlrev_b32_e32 v180, 16, v180
	v_lshlrev_b32_e32 v181, 16, v181
	v_lshlrev_b32_e32 v182, 16, v182
	v_lshlrev_b32_e32 v183, 16, v183
	v_lshlrev_b32_e32 v184, 16, v184
	v_lshlrev_b32_e32 v185, 16, v185
	v_lshlrev_b32_e32 v186, 16, v186
	v_lshlrev_b32_e32 v187, 16, v187
	v_lshlrev_b32_e32 v188, 16, v188
	v_lshlrev_b32_e32 v189, 16, v189
	v_lshlrev_b32_e32 v190, 16, v190
	v_lshlrev_b32_e32 v191, 16, v191
	v_lshlrev_b32_e32 v192, 16, v192
	v_lshlrev_b32_e32 v193, 16, v193
	v_lshlrev_b32_e32 v194, 16, v194
	v_lshlrev_b32_e32 v195, 16, v195
	v_lshlrev_b32_e32 v196, 16, v196
	v_lshlrev_b32_e32 v197, 16, v197
	v_lshlrev_b32_e32 v198, 16, v198
	v_lshlrev_b32_e32 v199, 16, v199
	v_lshlrev_b32_e32 v200, 16, v200
	v_lshlrev_b32_e32 v201, 16, v201
	v_lshlrev_b32_e32 v202, 16, v202
	v_lshlrev_b32_e32 v203, 16, v203
	v_lshlrev_b32_e32 v204, 16, v204
	v_lshlrev_b32_e32 v205, 16, v205
	v_lshlrev_b32_e32 v206, 16, v206
	v_lshlrev_b32_e32 v207, 16, v207
	v_lshlrev_b32_e32 v208, 16, v208
	v_lshlrev_b32_e32 v209, 16, v209
	v_lshlrev_b32_e32 v210, 16, v210
	v_lshlrev_b32_e32 v211, 16, v211
; __device__ __forceinline__ unsigned f2bf(float f) { unsigned r; asm("v_cvt_pk_bf16_f32 %0, %1, %1" : "=v"(r) : "v"(f)); return r & 0xffffu; }
; template <bool FINAL>
; __device__ __forceinline__ void rg_item(PREF p, int l, int item, LAS unsigned char* wl, int lane) {
;     ...
;         for (int i = 0; i < 67; ++i) { const int t = t0 - 2 + i; const int tc = t < 0 ? 0 : (t >= seqlen ? seqlen - 1 : t); xv[i] = (t == tc) ? bf2f(xr_[i]) : 0.f; }
; #pragma unroll
;         for (int tt = 0; tt < 64; ++tt) { const float xc = xv[tt] * cw0 + xv[tt + 1] * cw1 + xv[tt + 2] * cw2 + xv[tt + 3] * cw3 + cb; sXc[tt * 72 + lane] = (bf16_t)f2bf(xc); }
	v_lshlrev_b32_e32 v212, 16, v212
	v_lshlrev_b32_e32 v213, 16, v213
	v_lshlrev_b32_e32 v214, 16, v214
	v_lshlrev_b32_e32 v215, 16, v215
	v_lshlrev_b32_e32 v216, 16, v216
	v_lshlrev_b32_e32 v217, 16, v217
	v_lshlrev_b32_e32 v218, 16, v218
	v_lshlrev_b32_e32 v219, 16, v219
	v_lshlrev_b32_e32 v222, 16, v222
	v_lshlrev_b32_e32 v223, 16, v223
	v_lshlrev_b32_e32 v140, 16, v140
	v_lshlrev_b32_e32 v141, 16, v141
	v_lshlrev_b32_e32 v232, 16, v232
	v_and_b32_e32 v158, s37, v158
	v_and_b32_e32 v159, s37, v159
	v_and_b32_e32 v232, s38, v232
	v_mul_f32_e32 v32, v41, v159
	v_mul_f32_e32 v33, v41, v160
	v_mul_f32_e32 v34, v41, v161
	v_mul_f32_e32 v35, v41, v162
	v_mul_f32_e32 v36, v41, v163
	v_mul_f32_e32 v37, v41, v164
	v_mul_f32_e32 v38, v41, v165
	v_mul_f32_e32 v39, v41, v166
	v_fmac_f32_e32 v32, v40, v158
	v_fmac_f32_e32 v33, v40, v159
	v_fmac_f32_e32 v34, v40, v160
	v_fmac_f32_e32 v35, v40, v161
	v_fmac_f32_e32 v36, v40, v162
	v_fmac_f32_e32 v37, v40, v163
	v_fmac_f32_e32 v38, v40, v164
	v_fmac_f32_e32 v39, v40, v165
	v_fmac_f32_e32 v32, v42, v160
	v_fmac_f32_e32 v33, v42, v161
	v_fmac_f32_e32 v34, v42, v162
	v_fmac_f32_e32 v35, v42, v163
	v_fmac_f32_e32 v36, v42, v164
	v_fmac_f32_e32 v37, v42, v165
	v_fmac_f32_e32 v38, v42, v166
	v_fmac_f32_e32 v39, v42, v167
	v_fmac_f32_e32 v32, v43, v161
	v_fmac_f32_e32 v33, v43, v162
	v_fmac_f32_e32 v34, v43, v163
	v_fmac_f32_e32 v35, v43, v164
	v_fmac_f32_e32 v36, v43, v165
	v_fmac_f32_e32 v37, v43, v166
	v_fmac_f32_e32 v38, v43, v167
	v_fmac_f32_e32 v39, v43, v168
	v_add_f32_e32 v32, v44, v32
	v_add_f32_e32 v33, v44, v33
	v_add_f32_e32 v34, v44, v34
	v_add_f32_e32 v35, v44, v35
	v_add_f32_e32 v36, v44, v36
	v_add_f32_e32 v37, v44, v37
	v_add_f32_e32 v38, v44, v38
	v_add_f32_e32 v39, v44, v39
	v_cvt_pk_bf16_f32 v32, v32, v33
	v_cvt_pk_bf16_f32 v34, v34, v35
	v_cvt_pk_bf16_f32 v36, v36, v37
	v_cvt_pk_bf16_f32 v38, v38, v39
	ds_write_b16 v240, v32 offset:0
	ds_write_b16_d16_hi v240, v32 offset:144
	ds_write_b16 v240, v34 offset:288
	ds_write_b16_d16_hi v240, v34 offset:432
	ds_write_b16 v240, v36 offset:576
	ds_write_b16_d16_hi v240, v36 offset:720
	ds_write_b16 v240, v38 offset:864
	ds_write_b16_d16_hi v240, v38 offset:1008
	v_mul_f32_e32 v32, v41, v167
	v_mul_f32_e32 v33, v41, v168
	v_mul_f32_e32 v34, v41, v169
	v_mul_f32_e32 v35, v41, v170
	v_mul_f32_e32 v36, v41, v171
	v_mul_f32_e32 v37, v41, v172
	v_mul_f32_e32 v38, v41, v173
	v_mul_f32_e32 v39, v41, v174
	v_fmac_f32_e32 v32, v40, v166
	v_fmac_f32_e32 v33, v40, v167
	v_fmac_f32_e32 v34, v40, v168
	v_fmac_f32_e32 v35, v40, v169
	v_fmac_f32_e32 v36, v40, v170
	v_fmac_f32_e32 v37, v40, v171
	v_fmac_f32_e32 v38, v40, v172
	v_fmac_f32_e32 v39, v40, v173
	v_fmac_f32_e32 v32, v42, v168
	v_fmac_f32_e32 v33, v42, v169
	v_fmac_f32_e32 v34, v42, v170
	v_fmac_f32_e32 v35, v42, v171
	v_fmac_f32_e32 v36, v42, v172
	v_fmac_f32_e32 v37, v42, v173
	v_fmac_f32_e32 v38, v42, v174
	v_fmac_f32_e32 v39, v42, v175
	v_fmac_f32_e32 v32, v43, v169
	v_fmac_f32_e32 v33, v43, v170
	v_fmac_f32_e32 v34, v43, v171
	v_fmac_f32_e32 v35, v43, v172
	v_fmac_f32_e32 v36, v43, v173
	v_fmac_f32_e32 v37, v43, v174
	v_fmac_f32_e32 v38, v43, v175
	v_fmac_f32_e32 v39, v43, v176
	v_add_f32_e32 v32, v44, v32
	v_add_f32_e32 v33, v44, v33
	v_add_f32_e32 v34, v44, v34
	v_add_f32_e32 v35, v44, v35
	v_add_f32_e32 v36, v44, v36
	v_add_f32_e32 v37, v44, v37
	v_add_f32_e32 v38, v44, v38
	v_add_f32_e32 v39, v44, v39
	v_cvt_pk_bf16_f32 v32, v32, v33
	v_cvt_pk_bf16_f32 v34, v34, v35
	v_cvt_pk_bf16_f32 v36, v36, v37
	v_cvt_pk_bf16_f32 v38, v38, v39
	ds_write_b16 v240, v32 offset:1152
	ds_write_b16_d16_hi v240, v32 offset:1296
	ds_write_b16 v240, v34 offset:1440
	ds_write_b16_d16_hi v240, v34 offset:1584
	ds_write_b16 v240, v36 offset:1728
	ds_write_b16_d16_hi v240, v36 offset:1872
	ds_write_b16 v240, v38 offset:2016
	ds_write_b16_d16_hi v240, v38 offset:2160
	v_mul_f32_e32 v32, v41, v175
	v_mul_f32_e32 v33, v41, v176
	v_mul_f32_e32 v34, v41, v177
	v_mul_f32_e32 v35, v41, v178
	v_mul_f32_e32 v36, v41, v179
	v_mul_f32_e32 v37, v41, v180
	v_mul_f32_e32 v38, v41, v181
	v_mul_f32_e32 v39, v41, v182
	v_fmac_f32_e32 v32, v40, v174
	v_fmac_f32_e32 v33, v40, v175
	v_fmac_f32_e32 v34, v40, v176
	v_fmac_f32_e32 v35, v40, v177
	v_fmac_f32_e32 v36, v40, v178
	v_fmac_f32_e32 v37, v40, v179
	v_fmac_f32_e32 v38, v40, v180
	v_fmac_f32_e32 v39, v40, v181
	v_fmac_f32_e32 v32, v42, v176
	v_fmac_f32_e32 v33, v42, v177
	v_fmac_f32_e32 v34, v42, v178
	v_fmac_f32_e32 v35, v42, v179
	v_fmac_f32_e32 v36, v42, v180
	v_fmac_f32_e32 v37, v42, v181
	v_fmac_f32_e32 v38, v42, v182
	v_fmac_f32_e32 v39, v42, v183
	v_fmac_f32_e32 v32, v43, v177
	v_fmac_f32_e32 v33, v43, v178
	v_fmac_f32_e32 v34, v43, v179
	v_fmac_f32_e32 v35, v43, v180
	v_fmac_f32_e32 v36, v43, v181
	v_fmac_f32_e32 v37, v43, v182
	v_fmac_f32_e32 v38, v43, v183
	v_fmac_f32_e32 v39, v43, v184
	v_add_f32_e32 v32, v44, v32
	v_add_f32_e32 v33, v44, v33
	v_add_f32_e32 v34, v44, v34
	v_add_f32_e32 v35, v44, v35
	v_add_f32_e32 v36, v44, v36
	v_add_f32_e32 v37, v44, v37
	v_add_f32_e32 v38, v44, v38
	v_add_f32_e32 v39, v44, v39
	v_cvt_pk_bf16_f32 v32, v32, v33
	v_cvt_pk_bf16_f32 v34, v34, v35
	v_cvt_pk_bf16_f32 v36, v36, v37
	v_cvt_pk_bf16_f32 v38, v38, v39
	ds_write_b16 v240, v32 offset:2304
	ds_write_b16_d16_hi v240, v32 offset:2448
	ds_write_b16 v240, v34 offset:2592
	ds_write_b16_d16_hi v240, v34 offset:2736
	ds_write_b16 v240, v36 offset:2880
	ds_write_b16_d16_hi v240, v36 offset:3024
	ds_write_b16 v240, v38 offset:3168
	ds_write_b16_d16_hi v240, v38 offset:3312
	v_mul_f32_e32 v32, v41, v183
	v_mul_f32_e32 v33, v41, v184
	v_mul_f32_e32 v34, v41, v185
	v_mul_f32_e32 v35, v41, v186
; __device__ __forceinline__ unsigned f2bf(float f) { unsigned r; asm("v_cvt_pk_bf16_f32 %0, %1, %1" : "=v"(r) : "v"(f)); return r & 0xffffu; }
; template <bool FINAL>
; __device__ __forceinline__ void rg_item(PREF p, int l, int item, LAS unsigned char* wl, int lane) {
;     ...
;         for (int i = 0; i < 67; ++i) { const int t = t0 - 2 + i; const int tc = t < 0 ? 0 : (t >= seqlen ? seqlen - 1 : t); xv[i] = (t == tc) ? bf2f(xr_[i]) : 0.f; }
; #pragma unroll
;         for (int tt = 0; tt < 64; ++tt) { const float xc = xv[tt] * cw0 + xv[tt + 1] * cw1 + xv[tt + 2] * cw2 + xv[tt + 3] * cw3 + cb; sXc[tt * 72 + lane] = (bf16_t)f2bf(xc); }
	v_mul_f32_e32 v36, v41, v187
	v_mul_f32_e32 v37, v41, v188
	v_mul_f32_e32 v38, v41, v189
	v_mul_f32_e32 v39, v41, v190
	v_fmac_f32_e32 v32, v40, v182
	v_fmac_f32_e32 v33, v40, v183
	v_fmac_f32_e32 v34, v40, v184
	v_fmac_f32_e32 v35, v40, v185
	v_fmac_f32_e32 v36, v40, v186
	v_fmac_f32_e32 v37, v40, v187
	v_fmac_f32_e32 v38, v40, v188
	v_fmac_f32_e32 v39, v40, v189
	v_fmac_f32_e32 v32, v42, v184
	v_fmac_f32_e32 v33, v42, v185
	v_fmac_f32_e32 v34, v42, v186
	v_fmac_f32_e32 v35, v42, v187
	v_fmac_f32_e32 v36, v42, v188
	v_fmac_f32_e32 v37, v42, v189
	v_fmac_f32_e32 v38, v42, v190
	v_fmac_f32_e32 v39, v42, v191
	v_fmac_f32_e32 v32, v43, v185
	v_fmac_f32_e32 v33, v43, v186
	v_fmac_f32_e32 v34, v43, v187
	v_fmac_f32_e32 v35, v43, v188
	v_fmac_f32_e32 v36, v43, v189
	v_fmac_f32_e32 v37, v43, v190
	v_fmac_f32_e32 v38, v43, v191
	v_fmac_f32_e32 v39, v43, v192
	v_add_f32_e32 v32, v44, v32
	v_add_f32_e32 v33, v44, v33
	v_add_f32_e32 v34, v44, v34
	v_add_f32_e32 v35, v44, v35
	v_add_f32_e32 v36, v44, v36
	v_add_f32_e32 v37, v44, v37
	v_add_f32_e32 v38, v44, v38
	v_add_f32_e32 v39, v44, v39
	v_cvt_pk_bf16_f32 v32, v32, v33
	v_cvt_pk_bf16_f32 v34, v34, v35
	v_cvt_pk_bf16_f32 v36, v36, v37
	v_cvt_pk_bf16_f32 v38, v38, v39
	ds_write_b16 v240, v32 offset:3456
	ds_write_b16_d16_hi v240, v32 offset:3600
	ds_write_b16 v240, v34 offset:3744
	ds_write_b16_d16_hi v240, v34 offset:3888
	ds_write_b16 v240, v36 offset:4032
	ds_write_b16_d16_hi v240, v36 offset:4176
	ds_write_b16 v240, v38 offset:4320
	ds_write_b16_d16_hi v240, v38 offset:4464
	v_mul_f32_e32 v32, v41, v191
	v_mul_f32_e32 v33, v41, v192
	v_mul_f32_e32 v34, v41, v193
	v_mul_f32_e32 v35, v41, v194
	v_mul_f32_e32 v36, v41, v195
	v_mul_f32_e32 v37, v41, v196
	v_mul_f32_e32 v38, v41, v197
	v_mul_f32_e32 v39, v41, v198
	v_fmac_f32_e32 v32, v40, v190
	v_fmac_f32_e32 v33, v40, v191
	v_fmac_f32_e32 v34, v40, v192
	v_fmac_f32_e32 v35, v40, v193
	v_fmac_f32_e32 v36, v40, v194
	v_fmac_f32_e32 v37, v40, v195
	v_fmac_f32_e32 v38, v40, v196
	v_fmac_f32_e32 v39, v40, v197
	v_fmac_f32_e32 v32, v42, v192
	v_fmac_f32_e32 v33, v42, v193
	v_fmac_f32_e32 v34, v42, v194
	v_fmac_f32_e32 v35, v42, v195
	v_fmac_f32_e32 v36, v42, v196
	v_fmac_f32_e32 v37, v42, v197
	v_fmac_f32_e32 v38, v42, v198
	v_fmac_f32_e32 v39, v42, v199
	v_fmac_f32_e32 v32, v43, v193
	v_fmac_f32_e32 v33, v43, v194
	v_fmac_f32_e32 v34, v43, v195
	v_fmac_f32_e32 v35, v43, v196
	v_fmac_f32_e32 v36, v43, v197
	v_fmac_f32_e32 v37, v43, v198
	v_fmac_f32_e32 v38, v43, v199
	v_fmac_f32_e32 v39, v43, v200
	v_add_f32_e32 v32, v44, v32
	v_add_f32_e32 v33, v44, v33
	v_add_f32_e32 v34, v44, v34
	v_add_f32_e32 v35, v44, v35
	v_add_f32_e32 v36, v44, v36
	v_add_f32_e32 v37, v44, v37
	v_add_f32_e32 v38, v44, v38
	v_add_f32_e32 v39, v44, v39
	v_cvt_pk_bf16_f32 v32, v32, v33
	v_cvt_pk_bf16_f32 v34, v34, v35
	v_cvt_pk_bf16_f32 v36, v36, v37
	v_cvt_pk_bf16_f32 v38, v38, v39
	ds_write_b16 v240, v32 offset:4608
	ds_write_b16_d16_hi v240, v32 offset:4752
	ds_write_b16 v240, v34 offset:4896
	ds_write_b16_d16_hi v240, v34 offset:5040
	ds_write_b16 v240, v36 offset:5184
	ds_write_b16_d16_hi v240, v36 offset:5328
	ds_write_b16 v240, v38 offset:5472
	ds_write_b16_d16_hi v240, v38 offset:5616
	v_mul_f32_e32 v32, v41, v199
	v_mul_f32_e32 v33, v41, v200
	v_mul_f32_e32 v34, v41, v201
	v_mul_f32_e32 v35, v41, v202
	v_mul_f32_e32 v36, v41, v203
	v_mul_f32_e32 v37, v41, v204
	v_mul_f32_e32 v38, v41, v205
	v_mul_f32_e32 v39, v41, v206
	v_fmac_f32_e32 v32, v40, v198
	v_fmac_f32_e32 v33, v40, v199
	v_fmac_f32_e32 v34, v40, v200
	v_fmac_f32_e32 v35, v40, v201
	v_fmac_f32_e32 v36, v40, v202
	v_fmac_f32_e32 v37, v40, v203
	v_fmac_f32_e32 v38, v40, v204
	v_fmac_f32_e32 v39, v40, v205
	v_fmac_f32_e32 v32, v42, v200
	v_fmac_f32_e32 v33, v42, v201
	v_fmac_f32_e32 v34, v42, v202
	v_fmac_f32_e32 v35, v42, v203
	v_fmac_f32_e32 v36, v42, v204
	v_fmac_f32_e32 v37, v42, v205
	v_fmac_f32_e32 v38, v42, v206
	v_fmac_f32_e32 v39, v42, v207
	v_fmac_f32_e32 v32, v43, v201
	v_fmac_f32_e32 v33, v43, v202
	v_fmac_f32_e32 v34, v43, v203
	v_fmac_f32_e32 v35, v43, v204
	v_fmac_f32_e32 v36, v43, v205
	v_fmac_f32_e32 v37, v43, v206
	v_fmac_f32_e32 v38, v43, v207
	v_fmac_f32_e32 v39, v43, v208
	v_add_f32_e32 v32, v44, v32
	v_add_f32_e32 v33, v44, v33
	v_add_f32_e32 v34, v44, v34
	v_add_f32_e32 v35, v44, v35
	v_add_f32_e32 v36, v44, v36
	v_add_f32_e32 v37, v44, v37
	v_add_f32_e32 v38, v44, v38
	v_add_f32_e32 v39, v44, v39
	v_cvt_pk_bf16_f32 v32, v32, v33
	v_cvt_pk_bf16_f32 v34, v34, v35
	v_cvt_pk_bf16_f32 v36, v36, v37
	v_cvt_pk_bf16_f32 v38, v38, v39
	ds_write_b16 v240, v32 offset:5760
	ds_write_b16_d16_hi v240, v32 offset:5904
	ds_write_b16 v240, v34 offset:6048
	ds_write_b16_d16_hi v240, v34 offset:6192
	ds_write_b16 v240, v36 offset:6336
	ds_write_b16_d16_hi v240, v36 offset:6480
	ds_write_b16 v240, v38 offset:6624
	ds_write_b16_d16_hi v240, v38 offset:6768
	v_mul_f32_e32 v32, v41, v207
	v_mul_f32_e32 v33, v41, v208
	v_mul_f32_e32 v34, v41, v209
	v_mul_f32_e32 v35, v41, v210
	v_mul_f32_e32 v36, v41, v211
	v_mul_f32_e32 v37, v41, v212
	v_mul_f32_e32 v38, v41, v213
	v_mul_f32_e32 v39, v41, v214
	v_fmac_f32_e32 v32, v40, v206
	v_fmac_f32_e32 v33, v40, v207
	v_fmac_f32_e32 v34, v40, v208
	v_fmac_f32_e32 v35, v40, v209
	v_fmac_f32_e32 v36, v40, v210
	v_fmac_f32_e32 v37, v40, v211
	v_fmac_f32_e32 v38, v40, v212
	v_fmac_f32_e32 v39, v40, v213
	v_fmac_f32_e32 v32, v42, v208
	v_fmac_f32_e32 v33, v42, v209
	v_fmac_f32_e32 v34, v42, v210
	v_fmac_f32_e32 v35, v42, v211
	v_fmac_f32_e32 v36, v42, v212
	v_fmac_f32_e32 v37, v42, v213
	v_fmac_f32_e32 v38, v42, v214
	v_fmac_f32_e32 v39, v42, v215
	v_fmac_f32_e32 v32, v43, v209
; __device__ __forceinline__ unsigned f2bf(float f) { unsigned r; asm("v_cvt_pk_bf16_f32 %0, %1, %1" : "=v"(r) : "v"(f)); return r & 0xffffu; }
; __device__ __forceinline__ float rcpf_(float x) { return __builtin_amdgcn_rcpf(x); }
; template <bool FINAL, int D>
; __device__ __forceinline__ void rg_dir(PREF p, int l, int h, int ch, int sidx, int rowbase  , LAS bf16_t* sXc, LAS float* stg, int lane) {
;     ...
;     const float ba = p.rg_ba[(l * 2 + D) * 512 + ch], bi = p.rg_bi[(l * 2 + D) * 512 + ch], lam = p.rg_lam[(l * 2 + D) * 512 + ch];
;     const float e_ = __expf(-lam), u_ = 1.f + e_;
;     const float l1p = (u_ == 1.f) ? e_ : __logf(u_) * e_ * rcpf_(u_ - 1.f);
;     const float sp8 = -8.f * 1.4426950408889634f * l1p;
;     float hc = FINAL ? RGC[sidx] : 0.f, Ap = 1.f;
;     ...
;             for (int ti = 0; ti < 16; ++ti) { const size_t row = (size_t)(rowbase + mt * 16 + 15 - ti); grv[ti] = __builtin_bit_cast(float, (unsigned)P[row * PW + 512 + ch]); hfv[ti] = __builtin_bit_cast(float, (unsigned)TMP[row * 512 + ch]); }
; template <bool FINAL>
; __device__ __forceinline__ void rg_item(PREF p, int l, int item, LAS unsigned char* wl, int lane) {
;     ...
;         for (int i = 0; i < 67; ++i) { const int t = t0 - 2 + i; const int tc = t < 0 ? 0 : (t >= seqlen ? seqlen - 1 : t); xv[i] = (t == tc) ? bf2f(xr_[i]) : 0.f; }
; #pragma unroll
;         for (int tt = 0; tt < 64; ++tt) { const float xc = xv[tt] * cw0 + xv[tt + 1] * cw1 + xv[tt + 2] * cw2 + xv[tt + 3] * cw3 + cb; sXc[tt * 72 + lane] = (bf16_t)f2bf(xc); }
	v_fmac_f32_e32 v33, v43, v210
	v_fmac_f32_e32 v34, v43, v211
	v_fmac_f32_e32 v35, v43, v212
	v_fmac_f32_e32 v36, v43, v213
	v_fmac_f32_e32 v37, v43, v214
	v_fmac_f32_e32 v38, v43, v215
	v_fmac_f32_e32 v39, v43, v216
	v_add_f32_e32 v32, v44, v32
	v_add_f32_e32 v33, v44, v33
	v_add_f32_e32 v34, v44, v34
	v_add_f32_e32 v35, v44, v35
	v_add_f32_e32 v36, v44, v36
	v_add_f32_e32 v37, v44, v37
	v_add_f32_e32 v38, v44, v38
	v_add_f32_e32 v39, v44, v39
	v_cvt_pk_bf16_f32 v32, v32, v33
	v_cvt_pk_bf16_f32 v34, v34, v35
	v_cvt_pk_bf16_f32 v36, v36, v37
	v_cvt_pk_bf16_f32 v38, v38, v39
	ds_write_b16 v240, v32 offset:6912
	ds_write_b16_d16_hi v240, v32 offset:7056
	ds_write_b16 v240, v34 offset:7200
	ds_write_b16_d16_hi v240, v34 offset:7344
	ds_write_b16 v240, v36 offset:7488
	ds_write_b16_d16_hi v240, v36 offset:7632
	ds_write_b16 v240, v38 offset:7776
	ds_write_b16_d16_hi v240, v38 offset:7920
	v_mul_f32_e32 v32, v41, v215
	v_mul_f32_e32 v33, v41, v216
	v_mul_f32_e32 v34, v41, v217
	v_mul_f32_e32 v35, v41, v218
	v_mul_f32_e32 v36, v41, v219
	v_mul_f32_e32 v37, v41, v222
	v_mul_f32_e32 v38, v41, v223
	v_mul_f32_e32 v39, v41, v140
	v_fmac_f32_e32 v32, v40, v214
	v_fmac_f32_e32 v33, v40, v215
	v_fmac_f32_e32 v34, v40, v216
	v_fmac_f32_e32 v35, v40, v217
	v_fmac_f32_e32 v36, v40, v218
	v_fmac_f32_e32 v37, v40, v219
	v_fmac_f32_e32 v38, v40, v222
	v_fmac_f32_e32 v39, v40, v223
	v_fmac_f32_e32 v32, v42, v216
	v_fmac_f32_e32 v33, v42, v217
	v_fmac_f32_e32 v34, v42, v218
	v_fmac_f32_e32 v35, v42, v219
	v_fmac_f32_e32 v36, v42, v222
	v_fmac_f32_e32 v37, v42, v223
	v_fmac_f32_e32 v38, v42, v140
	v_fmac_f32_e32 v39, v42, v141
	v_fmac_f32_e32 v32, v43, v217
	v_fmac_f32_e32 v33, v43, v218
	v_fmac_f32_e32 v34, v43, v219
	v_fmac_f32_e32 v35, v43, v222
	v_fmac_f32_e32 v36, v43, v223
	v_fmac_f32_e32 v37, v43, v140
	v_fmac_f32_e32 v38, v43, v141
	v_fmac_f32_e32 v39, v43, v232
	v_add_f32_e32 v32, v44, v32
	v_add_f32_e32 v33, v44, v33
	v_add_f32_e32 v34, v44, v34
	v_add_f32_e32 v35, v44, v35
	v_add_f32_e32 v36, v44, v36
	v_add_f32_e32 v37, v44, v37
	v_add_f32_e32 v38, v44, v38
	v_add_f32_e32 v39, v44, v39
	v_cvt_pk_bf16_f32 v32, v32, v33
	v_cvt_pk_bf16_f32 v34, v34, v35
	v_cvt_pk_bf16_f32 v36, v36, v37
	v_cvt_pk_bf16_f32 v38, v38, v39
	ds_write_b16 v240, v32 offset:8064
	ds_write_b16_d16_hi v240, v32 offset:8208
	ds_write_b16 v240, v34 offset:8352
	ds_write_b16_d16_hi v240, v34 offset:8496
	ds_write_b16 v240, v36 offset:8640
	ds_write_b16_d16_hi v240, v36 offset:8784
	ds_write_b16 v240, v38 offset:8928
	ds_write_b16_d16_hi v240, v38 offset:9072
	v_mov_b32_e32 v248, 0xbfb8aa3b
	v_mov_b32_e32 v249, 0xbfb8aa3b
	v_mov_b32_e32 v140, 0x3d372713
	v_mov_b32_e32 v141, 0x3d372713
	s_waitcnt vmcnt(16)
	s_mov_b32 s8, 0x800000
	s_mov_b32 s9, 0x3f317217
	s_mov_b32 s14, 0x7f800000
	v_mul_f32_e32 v32, 0xbfb8aa3b, v45
	v_exp_f32_e32 v32, v32
	s_nop 0
	v_add_f32_e32 v33, 1.0, v32
	v_cmp_gt_f32_e32 vcc, s8, v33
	s_nop 1
	v_cndmask_b32_e64 v34, 0, 32, vcc
	v_ldexp_f32 v34, v33, v34
	v_log_f32_e32 v34, v34
	v_cndmask_b32_e32 v36, 0, v226, vcc
	v_cmp_eq_f32_e32 vcc, 1.0, v33
	v_mul_f32_e32 v35, 0x3f317217, v34
	v_fma_f32 v35, v34, s9, -v35
	v_fmac_f32_e32 v35, 0x3377d1cf, v34
	v_fmac_f32_e32 v35, 0x3f317217, v34
	v_cmp_lt_f32_e64 s[10:11], |v34|, s14
	s_nop 1
	v_cndmask_b32_e64 v34, v34, v35, s[10:11]
	v_add_f32_e32 v35, -1.0, v33
	v_rcp_f32_e32 v35, v35
	v_sub_f32_e32 v34, v34, v36
	v_mul_f32_e32 v34, v32, v34
	v_mul_f32_e32 v34, v34, v35
	v_cndmask_b32_e32 v32, v34, v32, vcc
	v_mul_f32_e32 v246, 0xc138aa3b, v32
	v_mov_b32_e32 v247, v246
	v_mul_f32_e32 v242, 0xbfb8aa3b, v46
	v_mul_f32_e32 v244, 0xbfb8aa3b, v47
	v_mov_b32_e32 v243, v242
	v_mov_b32_e32 v245, v244
	s_waitcnt vmcnt(0)
	s_add_i32 s39, s15, 48
	s_mul_hi_u32 s83, s39, 0x1600
	s_mul_i32 s82, s39, 0x1600
	s_add_u32 s82, s82, s0
	s_addc_u32 s83, s83, s1
	s_add_u32 s82, s82, 0xbc00400
	s_addc_u32 s83, s83, 0
	global_load_ushort v190, v234, s[82:83]
	s_add_u32 s82, s82, 0x1600
	s_addc_u32 s83, s83, 0
	global_load_ushort v191, v234, s[82:83]
	s_add_u32 s82, s82, 0x1600
	s_addc_u32 s83, s83, 0
	global_load_ushort v192, v234, s[82:83]
	s_add_u32 s82, s82, 0x1600
	s_addc_u32 s83, s83, 0
	global_load_ushort v193, v234, s[82:83]
	s_add_u32 s82, s82, 0x1600
	s_addc_u32 s83, s83, 0
	global_load_ushort v194, v234, s[82:83]
	s_add_u32 s82, s82, 0x1600
	s_addc_u32 s83, s83, 0
	global_load_ushort v195, v234, s[82:83]
	s_add_u32 s82, s82, 0x1600
	s_addc_u32 s83, s83, 0
	global_load_ushort v196, v234, s[82:83]
	s_add_u32 s82, s82, 0x1600
	s_addc_u32 s83, s83, 0
	global_load_ushort v197, v234, s[82:83]
	s_add_u32 s82, s82, 0x1600
	s_addc_u32 s83, s83, 0
	global_load_ushort v198, v234, s[82:83]
	s_add_u32 s82, s82, 0x1600
	s_addc_u32 s83, s83, 0
	global_load_ushort v199, v234, s[82:83]
	s_add_u32 s82, s82, 0x1600
	s_addc_u32 s83, s83, 0
	global_load_ushort v200, v234, s[82:83]
	s_add_u32 s82, s82, 0x1600
	s_addc_u32 s83, s83, 0
	global_load_ushort v201, v234, s[82:83]
	s_add_u32 s82, s82, 0x1600
	s_addc_u32 s83, s83, 0
	global_load_ushort v202, v234, s[82:83]
	s_add_u32 s82, s82, 0x1600
	s_addc_u32 s83, s83, 0
	global_load_ushort v203, v234, s[82:83]
	s_add_u32 s82, s82, 0x1600
	s_addc_u32 s83, s83, 0
	global_load_ushort v204, v234, s[82:83]
	s_add_u32 s82, s82, 0x1600
	s_addc_u32 s83, s83, 0
	global_load_ushort v205, v234, s[82:83]
	ds_read_b128 v[32:35], v236 offset:0
	ds_read_b128 v[36:39], v236 offset:64
	s_waitcnt lgkmcnt(0)
; #define LAS __attribute__((address_space(3)))
; #define WAVE_SYNC() asm volatile("s_waitcnt lgkmcnt(0)" ::: "memory")
; __device__ __forceinline__ float sigmoid_f(float x) { return rcpf_(1.f + __expf(-x)); }
; __device__ __forceinline__ f32x4 mfma16(bf16x8 a, bf16x8 b, f32x4 c) { return __builtin_amdgcn_mfma_f32_16x16x32_bf16(a, b, c, 0, 0, 0); }
; template <bool FINAL, int D>
; __device__ __forceinline__ void rg_dir(PREF p, int l, int h, int ch, int sidx, int rowbase  , LAS bf16_t* sXc, LAS float* stg, int lane) {
;     ...
;         const bf16x8 A0 = *(const LAS bf16x8*)(sXc + (mt * 16 + (lane & 15)) * 72 + (lane >> 4) * 8), A1 = *(const LAS bf16x8*)(sXc + (mt * 16 + (lane & 15)) * 72 + 32 + (lane >> 4) * 8);
;         f32x4 ar[4], ai[4];
; #pragma unroll
;         for (int nt = 0; nt < 4; ++nt) { const f32x4 z = {0.f, 0.f, 0.f, 0.f};
;             ar[nt] = mfma16(A0, Br[nt][0], z); ar[nt] = mfma16(A1, Br[nt][1], ar[nt]); ai[nt] = mfma16(A0, Bi[nt][0], z); ai[nt] = mfma16(A1, Bi[nt][1], ai[nt]); }
;         WAVE_SYNC();
; #pragma unroll
;         for (int nt = 0; nt < 4; ++nt)
; #pragma unroll
;             for (int j = 0; j < 4; ++j) { const int o = ((lane >> 4) * 4 + j) * 64 + nt * 16 + (lane & 15); stg[o] = ar[nt][j]; stg[1024 + o] = ai[nt][j]; }
;         WAVE_SYNC();
;         float av[16], iv[16];
; #pragma unroll
;         for (int ti = 0; ti < 16; ++ti) { const int tk = D ? 15 - ti : ti;
;             const float zr = stg[tk * 64 + lane] + ba, zi = stg[1024 + tk * 64 + lane] + bi;
;             const float r = sigmoid_f(zr), ig = sigmoid_f(zi);
	v_mfma_f32_16x16x32_bf16 v[0:3], v[32:35], v[80:83], 0
	v_mfma_f32_16x16x32_bf16 v[4:7], v[32:35], v[88:91], 0
	v_mfma_f32_16x16x32_bf16 v[8:11], v[32:35], v[96:99], 0
	v_mfma_f32_16x16x32_bf16 v[12:15], v[32:35], v[104:107], 0
	v_mfma_f32_16x16x32_bf16 v[16:19], v[32:35], v[112:115], 0
	v_mfma_f32_16x16x32_bf16 v[20:23], v[32:35], v[120:123], 0
	v_mfma_f32_16x16x32_bf16 v[24:27], v[32:35], v[128:131], 0
	v_mfma_f32_16x16x32_bf16 v[28:31], v[32:35], v[136:139], 0
	v_mfma_f32_16x16x32_bf16 v[0:3], v[36:39], v[84:87], v[0:3]
	v_mfma_f32_16x16x32_bf16 v[4:7], v[36:39], v[92:95], v[4:7]
	v_mfma_f32_16x16x32_bf16 v[8:11], v[36:39], v[100:103], v[8:11]
	v_mfma_f32_16x16x32_bf16 v[12:15], v[36:39], v[108:111], v[12:15]
	v_mfma_f32_16x16x32_bf16 v[16:19], v[36:39], v[116:119], v[16:19]
	v_mfma_f32_16x16x32_bf16 v[20:23], v[36:39], v[124:127], v[20:23]
	v_mfma_f32_16x16x32_bf16 v[24:27], v[36:39], v[132:135], v[24:27]
	v_mfma_f32_16x16x32_bf16 v[28:31], v[36:39], v[228:231], v[28:31]
	s_nop 3
	ds_write2_b32 v237, v0, v4 offset0:0 offset1:16
	ds_write2_b32 v237, v8, v12 offset0:32 offset1:48
	ds_write2_b32 v237, v1, v5 offset0:64 offset1:80
	ds_write2_b32 v237, v9, v13 offset0:96 offset1:112
	ds_write2_b32 v237, v2, v6 offset0:128 offset1:144
	ds_write2_b32 v237, v10, v14 offset0:160 offset1:176
	ds_write2_b32 v237, v3, v7 offset0:192 offset1:208
	ds_write2_b32 v237, v11, v15 offset0:224 offset1:240
	ds_write2_b32 v238, v16, v20 offset0:0 offset1:16
	ds_write2_b32 v238, v24, v28 offset0:32 offset1:48
	ds_write2_b32 v238, v17, v21 offset0:64 offset1:80
	ds_write2_b32 v238, v25, v29 offset0:96 offset1:112
	ds_write2_b32 v238, v18, v22 offset0:128 offset1:144
	ds_write2_b32 v238, v26, v30 offset0:160 offset1:176
	ds_write2_b32 v238, v19, v23 offset0:192 offset1:208
	ds_write2_b32 v238, v27, v31 offset0:224 offset1:240
	s_waitcnt lgkmcnt(0)
	ds_read2st64_b32 v[0:1], v239 offset0:36 offset1:37
	ds_read2st64_b32 v[2:3], v239 offset0:38 offset1:39
	ds_read2st64_b32 v[4:5], v239 offset0:40 offset1:41
	ds_read2st64_b32 v[6:7], v239 offset0:42 offset1:43
	ds_read2st64_b32 v[8:9], v239 offset0:44 offset1:45
	ds_read2st64_b32 v[10:11], v239 offset0:46 offset1:47
	ds_read2st64_b32 v[12:13], v239 offset0:48 offset1:49
	ds_read2st64_b32 v[14:15], v239 offset0:50 offset1:51
	ds_read2st64_b32 v[16:17], v239 offset0:52 offset1:53
	ds_read2st64_b32 v[18:19], v239 offset0:54 offset1:55
	ds_read2st64_b32 v[20:21], v239 offset0:56 offset1:57
	ds_read2st64_b32 v[22:23], v239 offset0:58 offset1:59
	ds_read2st64_b32 v[24:25], v239 offset0:60 offset1:61
	ds_read2st64_b32 v[26:27], v239 offset0:62 offset1:63
	ds_read2st64_b32 v[28:29], v239 offset0:64 offset1:65
	ds_read2st64_b32 v[30:31], v239 offset0:66 offset1:67
	ds_read_u16 v48, v240 offset:0
	ds_read_u16 v49, v240 offset:144
	ds_read_u16 v50, v240 offset:288
	ds_read_u16 v51, v240 offset:432
	ds_read_u16 v52, v240 offset:576
	ds_read_u16 v53, v240 offset:720
	ds_read_u16 v54, v240 offset:864
	ds_read_u16 v55, v240 offset:1008
	ds_read_u16 v56, v240 offset:1152
	ds_read_u16 v57, v240 offset:1296
	ds_read_u16 v58, v240 offset:1440
	ds_read_u16 v59, v240 offset:1584
	ds_read_u16 v60, v240 offset:1728
	ds_read_u16 v61, v240 offset:1872
	ds_read_u16 v62, v240 offset:2016
	ds_read_u16 v63, v240 offset:2160
	s_waitcnt lgkmcnt(0)
	v_pk_fma_f32 v[0:1], v[0:1], v[248:249], v[242:243]
	v_pk_fma_f32 v[2:3], v[2:3], v[248:249], v[242:243]
	v_pk_fma_f32 v[4:5], v[4:5], v[248:249], v[242:243]
	v_pk_fma_f32 v[6:7], v[6:7], v[248:249], v[242:243]
	v_pk_fma_f32 v[8:9], v[8:9], v[248:249], v[242:243]
	v_pk_fma_f32 v[10:11], v[10:11], v[248:249], v[242:243]
	v_pk_fma_f32 v[12:13], v[12:13], v[248:249], v[242:243]
	v_pk_fma_f32 v[14:15], v[14:15], v[248:249], v[242:243]
	v_pk_fma_f32 v[16:17], v[16:17], v[248:249], v[244:245]
	v_pk_fma_f32 v[18:19], v[18:19], v[248:249], v[244:245]
	v_pk_fma_f32 v[20:21], v[20:21], v[248:249], v[244:245]
	v_pk_fma_f32 v[22:23], v[22:23], v[248:249], v[244:245]
	v_pk_fma_f32 v[24:25], v[24:25], v[248:249], v[244:245]
	v_pk_fma_f32 v[26:27], v[26:27], v[248:249], v[244:245]
	v_pk_fma_f32 v[28:29], v[28:29], v[248:249], v[244:245]
	v_pk_fma_f32 v[30:31], v[30:31], v[248:249], v[244:245]
	v_exp_f32_e32 v0, v0
	v_exp_f32_e32 v1, v1
	v_exp_f32_e32 v2, v2
	v_exp_f32_e32 v3, v3
	v_exp_f32_e32 v4, v4
	v_exp_f32_e32 v5, v5
	v_exp_f32_e32 v6, v6
	v_exp_f32_e32 v7, v7
	v_exp_f32_e32 v8, v8
	v_exp_f32_e32 v9, v9
	v_exp_f32_e32 v10, v10
	v_exp_f32_e32 v11, v11
	v_exp_f32_e32 v12, v12
	v_exp_f32_e32 v13, v13
	v_exp_f32_e32 v14, v14
	v_exp_f32_e32 v15, v15
	v_exp_f32_e32 v16, v16
	v_exp_f32_e32 v17, v17
	v_exp_f32_e32 v18, v18
	v_exp_f32_e32 v19, v19
	v_exp_f32_e32 v20, v20
	v_exp_f32_e32 v21, v21
	v_exp_f32_e32 v22, v22
	v_exp_f32_e32 v23, v23
	v_exp_f32_e32 v24, v24
	v_exp_f32_e32 v25, v25
	v_exp_f32_e32 v26, v26
	v_exp_f32_e32 v27, v27
	v_exp_f32_e32 v28, v28
	v_exp_f32_e32 v29, v29
	v_exp_f32_e32 v30, v30
	v_exp_f32_e32 v31, v31
	v_pk_add_f32 v[0:1], v[0:1], 1.0 op_sel_hi:[1,0]
	v_pk_add_f32 v[2:3], v[2:3], 1.0 op_sel_hi:[1,0]
	v_pk_add_f32 v[4:5], v[4:5], 1.0 op_sel_hi:[1,0]
	v_pk_add_f32 v[6:7], v[6:7], 1.0 op_sel_hi:[1,0]
	v_pk_add_f32 v[8:9], v[8:9], 1.0 op_sel_hi:[1,0]
	v_pk_add_f32 v[10:11], v[10:11], 1.0 op_sel_hi:[1,0]
	v_pk_add_f32 v[12:13], v[12:13], 1.0 op_sel_hi:[1,0]
	v_pk_add_f32 v[14:15], v[14:15], 1.0 op_sel_hi:[1,0]
	v_pk_add_f32 v[16:17], v[16:17], 1.0 op_sel_hi:[1,0]
	v_pk_add_f32 v[18:19], v[18:19], 1.0 op_sel_hi:[1,0]
	v_pk_add_f32 v[20:21], v[20:21], 1.0 op_sel_hi:[1,0]
	v_pk_add_f32 v[22:23], v[22:23], 1.0 op_sel_hi:[1,0]
	v_pk_add_f32 v[24:25], v[24:25], 1.0 op_sel_hi:[1,0]
; #define LAS __attribute__((address_space(3)))
; #define WAVE_SYNC() asm volatile("s_waitcnt lgkmcnt(0)" ::: "memory")
; __device__ __forceinline__ unsigned f2bf(float f) { unsigned r; asm("v_cvt_pk_bf16_f32 %0, %1, %1" : "=v"(r) : "v"(f)); return r & 0xffffu; }
; __device__ __forceinline__ float sigmoid_f(float x) { return rcpf_(1.f + __expf(-x)); }
; __device__ __forceinline__ float gelu_tanh_f(float x) { const float y = 0.7978845608028654f * (x + 0.044715f * x * x * x); return x * sigmoid_f(2.f * y); }
; template <bool FINAL, int D>
; __device__ __forceinline__ void rg_dir(PREF p, int l, int h, int ch, int sidx, int rowbase  , LAS bf16_t* sXc, LAS float* stg, int lane) {
;     ...
;         const bf16x8 A0 = *(const LAS bf16x8*)(sXc + (mt * 16 + (lane & 15)) * 72 + (lane >> 4) * 8), A1 = *(const LAS bf16x8*)(sXc + (mt * 16 + (lane & 15)) * 72 + 32 + (lane >> 4) * 8);
;         f32x4 ar[4], ai[4];
; #pragma unroll
;         for (int nt = 0; nt < 4; ++nt) { const f32x4 z = {0.f, 0.f, 0.f, 0.f};
;             ar[nt] = mfma16(A0, Br[nt][0], z); ar[nt] = mfma16(A1, Br[nt][1], ar[nt]); ai[nt] = mfma16(A0, Bi[nt][0], z); ai[nt] = mfma16(A1, Bi[nt][1], ai[nt]); }
;         WAVE_SYNC();
; #pragma unroll
;         for (int nt = 0; nt < 4; ++nt)
; #pragma unroll
;             for (int j = 0; j < 4; ++j) { const int o = ((lane >> 4) * 4 + j) * 64 + nt * 16 + (lane & 15); stg[o] = ar[nt][j]; stg[1024 + o] = ai[nt][j]; }
;     ...
;         for (int ti = 0; ti < 16; ++ti) { const int tk = D ? 15 - ti : ti;
;             const float zr = stg[tk * 64 + lane] + ba, zi = stg[1024 + tk * 64 + lane] + bi;
;             const float r = sigmoid_f(zr), ig = sigmoid_f(zi);
;             const float a = __builtin_amdgcn_exp2f(r * sp8);
;             const float xc = bf2f(sXc[(mt * 16 + tk) * 72 + lane]);
;             av[ti] = a; iv[ti] = __builtin_amdgcn_sqrtf(fmaxf(1.f - a * a, 0.f)) * ig * xc;
;             if (FINAL && D == 1) grv[ti] = gelu_tanh_f(grv[ti]);
;         }
; #pragma unroll
;         for (int ti = 0; ti < 16; ++ti) { const int tk = D ? 15 - ti : ti;
;             hc = av[ti] * hc + iv[ti]; Ap *= av[ti];
;             if (FINAL) { const size_t row = (size_t)(rowbase + mt * 16 + tk);
;                 if (D == 0) TMP[row * 512 + ch] = (bf16_t)f2bf(hc);
	v_pk_add_f32 v[26:27], v[26:27], 1.0 op_sel_hi:[1,0]
	v_pk_add_f32 v[28:29], v[28:29], 1.0 op_sel_hi:[1,0]
	v_pk_add_f32 v[30:31], v[30:31], 1.0 op_sel_hi:[1,0]
	v_rcp_f32_e32 v0, v0
	v_rcp_f32_e32 v1, v1
	v_rcp_f32_e32 v2, v2
	v_rcp_f32_e32 v3, v3
	v_rcp_f32_e32 v4, v4
	v_rcp_f32_e32 v5, v5
	v_rcp_f32_e32 v6, v6
	v_rcp_f32_e32 v7, v7
	v_rcp_f32_e32 v8, v8
	v_rcp_f32_e32 v9, v9
	v_rcp_f32_e32 v10, v10
	v_rcp_f32_e32 v11, v11
	v_rcp_f32_e32 v12, v12
	v_rcp_f32_e32 v13, v13
	v_rcp_f32_e32 v14, v14
	v_rcp_f32_e32 v15, v15
	v_rcp_f32_e32 v16, v16
	v_rcp_f32_e32 v17, v17
	v_rcp_f32_e32 v18, v18
	v_rcp_f32_e32 v19, v19
	v_rcp_f32_e32 v20, v20
	v_rcp_f32_e32 v21, v21
	v_rcp_f32_e32 v22, v22
	v_rcp_f32_e32 v23, v23
	v_rcp_f32_e32 v24, v24
	v_rcp_f32_e32 v25, v25
	v_rcp_f32_e32 v26, v26
	v_rcp_f32_e32 v27, v27
	v_rcp_f32_e32 v28, v28
	v_rcp_f32_e32 v29, v29
	v_rcp_f32_e32 v30, v30
	v_rcp_f32_e32 v31, v31
	v_pk_mul_f32 v[0:1], v[246:247], v[0:1]
	v_pk_mul_f32 v[2:3], v[246:247], v[2:3]
	v_pk_mul_f32 v[4:5], v[246:247], v[4:5]
	v_pk_mul_f32 v[6:7], v[246:247], v[6:7]
	v_pk_mul_f32 v[8:9], v[246:247], v[8:9]
	v_pk_mul_f32 v[10:11], v[246:247], v[10:11]
	v_pk_mul_f32 v[12:13], v[246:247], v[12:13]
	v_pk_mul_f32 v[14:15], v[246:247], v[14:15]
	v_lshlrev_b32_e32 v48, 16, v48
	v_lshlrev_b32_e32 v49, 16, v49
	v_lshlrev_b32_e32 v50, 16, v50
	v_lshlrev_b32_e32 v51, 16, v51
	v_lshlrev_b32_e32 v52, 16, v52
	v_lshlrev_b32_e32 v53, 16, v53
	v_lshlrev_b32_e32 v54, 16, v54
	v_lshlrev_b32_e32 v55, 16, v55
	v_lshlrev_b32_e32 v56, 16, v56
	v_lshlrev_b32_e32 v57, 16, v57
	v_lshlrev_b32_e32 v58, 16, v58
	v_lshlrev_b32_e32 v59, 16, v59
	v_lshlrev_b32_e32 v60, 16, v60
	v_lshlrev_b32_e32 v61, 16, v61
	v_lshlrev_b32_e32 v62, 16, v62
	v_lshlrev_b32_e32 v63, 16, v63
	v_exp_f32_e32 v0, v0
	v_exp_f32_e32 v1, v1
	v_exp_f32_e32 v2, v2
	v_exp_f32_e32 v3, v3
	v_exp_f32_e32 v4, v4
	v_exp_f32_e32 v5, v5
	v_exp_f32_e32 v6, v6
	v_exp_f32_e32 v7, v7
	v_exp_f32_e32 v8, v8
	v_exp_f32_e32 v9, v9
	v_exp_f32_e32 v10, v10
	v_exp_f32_e32 v11, v11
	v_exp_f32_e32 v12, v12
	v_exp_f32_e32 v13, v13
	v_exp_f32_e32 v14, v14
	v_exp_f32_e32 v15, v15
	v_fma_f32 v32, -v0, v0, 1.0 clamp
	v_fma_f32 v33, -v1, v1, 1.0 clamp
	v_fma_f32 v34, -v2, v2, 1.0 clamp
	v_fma_f32 v35, -v3, v3, 1.0 clamp
	v_fma_f32 v36, -v4, v4, 1.0 clamp
	v_fma_f32 v37, -v5, v5, 1.0 clamp
	v_fma_f32 v38, -v6, v6, 1.0 clamp
	v_fma_f32 v39, -v7, v7, 1.0 clamp
	v_fma_f32 v40, -v8, v8, 1.0 clamp
	v_fma_f32 v41, -v9, v9, 1.0 clamp
	v_fma_f32 v42, -v10, v10, 1.0 clamp
	v_fma_f32 v43, -v11, v11, 1.0 clamp
	v_fma_f32 v44, -v12, v12, 1.0 clamp
	v_fma_f32 v45, -v13, v13, 1.0 clamp
	v_fma_f32 v46, -v14, v14, 1.0 clamp
	v_fma_f32 v47, -v15, v15, 1.0 clamp
	v_sqrt_f32_e32 v32, v32
	v_sqrt_f32_e32 v33, v33
	v_sqrt_f32_e32 v34, v34
	v_sqrt_f32_e32 v35, v35
	v_sqrt_f32_e32 v36, v36
	v_sqrt_f32_e32 v37, v37
	v_sqrt_f32_e32 v38, v38
	v_sqrt_f32_e32 v39, v39
	v_sqrt_f32_e32 v40, v40
	v_sqrt_f32_e32 v41, v41
	v_sqrt_f32_e32 v42, v42
	v_sqrt_f32_e32 v43, v43
	v_sqrt_f32_e32 v44, v44
	v_sqrt_f32_e32 v45, v45
	v_sqrt_f32_e32 v46, v46
	v_sqrt_f32_e32 v47, v47
	s_nop 0
	v_pk_mul_f32 v[16:17], v[16:17], v[32:33]
	v_pk_mul_f32 v[18:19], v[18:19], v[34:35]
	v_pk_mul_f32 v[20:21], v[20:21], v[36:37]
	v_pk_mul_f32 v[22:23], v[22:23], v[38:39]
	v_pk_mul_f32 v[24:25], v[24:25], v[40:41]
	v_pk_mul_f32 v[26:27], v[26:27], v[42:43]
	v_pk_mul_f32 v[28:29], v[28:29], v[44:45]
	v_pk_mul_f32 v[30:31], v[30:31], v[46:47]
	v_pk_mul_f32 v[16:17], v[16:17], v[48:49]
	v_pk_mul_f32 v[18:19], v[18:19], v[50:51]
	v_pk_mul_f32 v[20:21], v[20:21], v[52:53]
	v_pk_mul_f32 v[22:23], v[22:23], v[54:55]
	v_pk_mul_f32 v[24:25], v[24:25], v[56:57]
	v_pk_mul_f32 v[26:27], v[26:27], v[58:59]
	v_pk_mul_f32 v[28:29], v[28:29], v[60:61]
	v_pk_mul_f32 v[30:31], v[30:31], v[62:63]
	v_fma_f32 v32, v0, v250, v16
	v_fma_f32 v250, v1, v32, v17
	v_cvt_pk_bf16_f32 v158, v32, v250
	v_fma_f32 v32, v2, v250, v18
	v_fma_f32 v250, v3, v32, v19
	v_cvt_pk_bf16_f32 v159, v32, v250
	v_fma_f32 v32, v4, v250, v20
	v_fma_f32 v250, v5, v32, v21
	v_cvt_pk_bf16_f32 v160, v32, v250
	v_fma_f32 v32, v6, v250, v22
	v_fma_f32 v250, v7, v32, v23
	v_cvt_pk_bf16_f32 v161, v32, v250
	v_fma_f32 v32, v8, v250, v24
	v_fma_f32 v250, v9, v32, v25
	v_cvt_pk_bf16_f32 v162, v32, v250
	v_fma_f32 v32, v10, v250, v26
	v_fma_f32 v250, v11, v32, v27
	v_cvt_pk_bf16_f32 v163, v32, v250
	v_fma_f32 v32, v12, v250, v28
	v_fma_f32 v250, v13, v32, v29
	v_cvt_pk_bf16_f32 v164, v32, v250
	v_fma_f32 v32, v14, v250, v30
	v_fma_f32 v250, v15, v32, v31
	v_cvt_pk_bf16_f32 v165, v32, v250
	ds_read_b128 v[32:35], v236 offset:2304
	ds_read_b128 v[36:39], v236 offset:2368
	s_waitcnt lgkmcnt(0)
	v_mfma_f32_16x16x32_bf16 v[0:3], v[32:35], v[80:83], 0
	v_mfma_f32_16x16x32_bf16 v[4:7], v[32:35], v[88:91], 0
	v_mfma_f32_16x16x32_bf16 v[8:11], v[32:35], v[96:99], 0
	v_mfma_f32_16x16x32_bf16 v[12:15], v[32:35], v[104:107], 0
	v_mfma_f32_16x16x32_bf16 v[16:19], v[32:35], v[112:115], 0
	v_mfma_f32_16x16x32_bf16 v[20:23], v[32:35], v[120:123], 0
	v_mfma_f32_16x16x32_bf16 v[24:27], v[32:35], v[128:131], 0
	v_mfma_f32_16x16x32_bf16 v[28:31], v[32:35], v[136:139], 0
	v_mfma_f32_16x16x32_bf16 v[0:3], v[36:39], v[84:87], v[0:3]
	v_mfma_f32_16x16x32_bf16 v[4:7], v[36:39], v[92:95], v[4:7]
	v_mfma_f32_16x16x32_bf16 v[8:11], v[36:39], v[100:103], v[8:11]
	v_mfma_f32_16x16x32_bf16 v[12:15], v[36:39], v[108:111], v[12:15]
	v_mfma_f32_16x16x32_bf16 v[16:19], v[36:39], v[116:119], v[16:19]
	v_mfma_f32_16x16x32_bf16 v[20:23], v[36:39], v[124:127], v[20:23]
	v_mfma_f32_16x16x32_bf16 v[24:27], v[36:39], v[132:135], v[24:27]
	v_mfma_f32_16x16x32_bf16 v[28:31], v[36:39], v[228:231], v[28:31]
	s_nop 3
	ds_write2_b32 v237, v0, v4 offset0:0 offset1:16
	ds_write2_b32 v237, v8, v12 offset0:32 offset1:48
	ds_write2_b32 v237, v1, v5 offset0:64 offset1:80
	ds_write2_b32 v237, v9, v13 offset0:96 offset1:112
	ds_write2_b32 v237, v2, v6 offset0:128 offset1:144
	ds_write2_b32 v237, v10, v14 offset0:160 offset1:176
	ds_write2_b32 v237, v3, v7 offset0:192 offset1:208
	ds_write2_b32 v237, v11, v15 offset0:224 offset1:240
	ds_write2_b32 v238, v16, v20 offset0:0 offset1:16
	ds_write2_b32 v238, v24, v28 offset0:32 offset1:48
	ds_write2_b32 v238, v17, v21 offset0:64 offset1:80
	ds_write2_b32 v238, v25, v29 offset0:96 offset1:112
	ds_write2_b32 v238, v18, v22 offset0:128 offset1:144
	ds_write2_b32 v238, v26, v30 offset0:160 offset1:176
	ds_write2_b32 v238, v19, v23 offset0:192 offset1:208
	ds_write2_b32 v238, v27, v31 offset0:224 offset1:240
	s_waitcnt lgkmcnt(0)
; __device__ __forceinline__ float sigmoid_f(float x) { return rcpf_(1.f + __expf(-x)); }
; template <bool FINAL, int D>
; __device__ __forceinline__ void rg_dir(PREF p, int l, int h, int ch, int sidx, int rowbase  , LAS bf16_t* sXc, LAS float* stg, int lane) {
;     ...
;         float av[16], iv[16];
; #pragma unroll
;         for (int ti = 0; ti < 16; ++ti) { const int tk = D ? 15 - ti : ti;
;             const float zr = stg[tk * 64 + lane] + ba, zi = stg[1024 + tk * 64 + lane] + bi;
;             const float r = sigmoid_f(zr), ig = sigmoid_f(zi);
;             const float a = __builtin_amdgcn_exp2f(r * sp8);
;             const float xc = bf2f(sXc[(mt * 16 + tk) * 72 + lane]);
	ds_read2st64_b32 v[0:1], v239 offset0:36 offset1:37
	ds_read2st64_b32 v[2:3], v239 offset0:38 offset1:39
	ds_read2st64_b32 v[4:5], v239 offset0:40 offset1:41
	ds_read2st64_b32 v[6:7], v239 offset0:42 offset1:43
	ds_read2st64_b32 v[8:9], v239 offset0:44 offset1:45
	ds_read2st64_b32 v[10:11], v239 offset0:46 offset1:47
	ds_read2st64_b32 v[12:13], v239 offset0:48 offset1:49
	ds_read2st64_b32 v[14:15], v239 offset0:50 offset1:51
	ds_read2st64_b32 v[16:17], v239 offset0:52 offset1:53
	ds_read2st64_b32 v[18:19], v239 offset0:54 offset1:55
	ds_read2st64_b32 v[20:21], v239 offset0:56 offset1:57
	ds_read2st64_b32 v[22:23], v239 offset0:58 offset1:59
	ds_read2st64_b32 v[24:25], v239 offset0:60 offset1:61
	ds_read2st64_b32 v[26:27], v239 offset0:62 offset1:63
	ds_read2st64_b32 v[28:29], v239 offset0:64 offset1:65
	ds_read2st64_b32 v[30:31], v239 offset0:66 offset1:67
	ds_read_u16 v48, v240 offset:2304
	ds_read_u16 v49, v240 offset:2448
	ds_read_u16 v50, v240 offset:2592
	ds_read_u16 v51, v240 offset:2736
	ds_read_u16 v52, v240 offset:2880
	ds_read_u16 v53, v240 offset:3024
	ds_read_u16 v54, v240 offset:3168
	ds_read_u16 v55, v240 offset:3312
	ds_read_u16 v56, v240 offset:3456
	ds_read_u16 v57, v240 offset:3600
	ds_read_u16 v58, v240 offset:3744
	ds_read_u16 v59, v240 offset:3888
	ds_read_u16 v60, v240 offset:4032
	ds_read_u16 v61, v240 offset:4176
	ds_read_u16 v62, v240 offset:4320
	ds_read_u16 v63, v240 offset:4464
	s_waitcnt lgkmcnt(0)
	v_pk_fma_f32 v[0:1], v[0:1], v[248:249], v[242:243]
	v_pk_fma_f32 v[2:3], v[2:3], v[248:249], v[242:243]
	v_pk_fma_f32 v[4:5], v[4:5], v[248:249], v[242:243]
	v_pk_fma_f32 v[6:7], v[6:7], v[248:249], v[242:243]
	v_pk_fma_f32 v[8:9], v[8:9], v[248:249], v[242:243]
	v_pk_fma_f32 v[10:11], v[10:11], v[248:249], v[242:243]
	v_pk_fma_f32 v[12:13], v[12:13], v[248:249], v[242:243]
	v_pk_fma_f32 v[14:15], v[14:15], v[248:249], v[242:243]
	v_pk_fma_f32 v[16:17], v[16:17], v[248:249], v[244:245]
	v_pk_fma_f32 v[18:19], v[18:19], v[248:249], v[244:245]
	v_pk_fma_f32 v[20:21], v[20:21], v[248:249], v[244:245]
	v_pk_fma_f32 v[22:23], v[22:23], v[248:249], v[244:245]
	v_pk_fma_f32 v[24:25], v[24:25], v[248:249], v[244:245]
	v_pk_fma_f32 v[26:27], v[26:27], v[248:249], v[244:245]
	v_pk_fma_f32 v[28:29], v[28:29], v[248:249], v[244:245]
	v_pk_fma_f32 v[30:31], v[30:31], v[248:249], v[244:245]
	v_exp_f32_e32 v0, v0
	v_exp_f32_e32 v1, v1
	v_exp_f32_e32 v2, v2
	v_exp_f32_e32 v3, v3
	v_exp_f32_e32 v4, v4
	v_exp_f32_e32 v5, v5
	v_exp_f32_e32 v6, v6
	v_exp_f32_e32 v7, v7
	v_exp_f32_e32 v8, v8
	v_exp_f32_e32 v9, v9
	v_exp_f32_e32 v10, v10
	v_exp_f32_e32 v11, v11
	v_exp_f32_e32 v12, v12
	v_exp_f32_e32 v13, v13
	v_exp_f32_e32 v14, v14
	v_exp_f32_e32 v15, v15
	v_exp_f32_e32 v16, v16
	v_exp_f32_e32 v17, v17
	v_exp_f32_e32 v18, v18
	v_exp_f32_e32 v19, v19
	v_exp_f32_e32 v20, v20
	v_exp_f32_e32 v21, v21
	v_exp_f32_e32 v22, v22
	v_exp_f32_e32 v23, v23
	v_exp_f32_e32 v24, v24
	v_exp_f32_e32 v25, v25
	v_exp_f32_e32 v26, v26
	v_exp_f32_e32 v27, v27
	v_exp_f32_e32 v28, v28
	v_exp_f32_e32 v29, v29
	v_exp_f32_e32 v30, v30
	v_exp_f32_e32 v31, v31
	v_pk_add_f32 v[0:1], v[0:1], 1.0 op_sel_hi:[1,0]
	v_pk_add_f32 v[2:3], v[2:3], 1.0 op_sel_hi:[1,0]
	v_pk_add_f32 v[4:5], v[4:5], 1.0 op_sel_hi:[1,0]
	v_pk_add_f32 v[6:7], v[6:7], 1.0 op_sel_hi:[1,0]
	v_pk_add_f32 v[8:9], v[8:9], 1.0 op_sel_hi:[1,0]
	v_pk_add_f32 v[10:11], v[10:11], 1.0 op_sel_hi:[1,0]
	v_pk_add_f32 v[12:13], v[12:13], 1.0 op_sel_hi:[1,0]
	v_pk_add_f32 v[14:15], v[14:15], 1.0 op_sel_hi:[1,0]
	v_pk_add_f32 v[16:17], v[16:17], 1.0 op_sel_hi:[1,0]
	v_pk_add_f32 v[18:19], v[18:19], 1.0 op_sel_hi:[1,0]
	v_pk_add_f32 v[20:21], v[20:21], 1.0 op_sel_hi:[1,0]
	v_pk_add_f32 v[22:23], v[22:23], 1.0 op_sel_hi:[1,0]
	v_pk_add_f32 v[24:25], v[24:25], 1.0 op_sel_hi:[1,0]
	v_pk_add_f32 v[26:27], v[26:27], 1.0 op_sel_hi:[1,0]
	v_pk_add_f32 v[28:29], v[28:29], 1.0 op_sel_hi:[1,0]
	v_pk_add_f32 v[30:31], v[30:31], 1.0 op_sel_hi:[1,0]
	v_rcp_f32_e32 v0, v0
	v_rcp_f32_e32 v1, v1
	v_rcp_f32_e32 v2, v2
	v_rcp_f32_e32 v3, v3
	v_rcp_f32_e32 v4, v4
	v_rcp_f32_e32 v5, v5
	v_rcp_f32_e32 v6, v6
	v_rcp_f32_e32 v7, v7
	v_rcp_f32_e32 v8, v8
	v_rcp_f32_e32 v9, v9
	v_rcp_f32_e32 v10, v10
	v_rcp_f32_e32 v11, v11
	v_rcp_f32_e32 v12, v12
	v_rcp_f32_e32 v13, v13
	v_rcp_f32_e32 v14, v14
	v_rcp_f32_e32 v15, v15
	v_rcp_f32_e32 v16, v16
	v_rcp_f32_e32 v17, v17
	v_rcp_f32_e32 v18, v18
	v_rcp_f32_e32 v19, v19
	v_rcp_f32_e32 v20, v20
	v_rcp_f32_e32 v21, v21
	v_rcp_f32_e32 v22, v22
	v_rcp_f32_e32 v23, v23
	v_rcp_f32_e32 v24, v24
	v_rcp_f32_e32 v25, v25
	v_rcp_f32_e32 v26, v26
	v_rcp_f32_e32 v27, v27
	v_rcp_f32_e32 v28, v28
	v_rcp_f32_e32 v29, v29
	v_rcp_f32_e32 v30, v30
	v_rcp_f32_e32 v31, v31
	v_pk_mul_f32 v[0:1], v[246:247], v[0:1]
	v_pk_mul_f32 v[2:3], v[246:247], v[2:3]
	v_pk_mul_f32 v[4:5], v[246:247], v[4:5]
	v_pk_mul_f32 v[6:7], v[246:247], v[6:7]
	v_pk_mul_f32 v[8:9], v[246:247], v[8:9]
	v_pk_mul_f32 v[10:11], v[246:247], v[10:11]
	v_pk_mul_f32 v[12:13], v[246:247], v[12:13]
	v_pk_mul_f32 v[14:15], v[246:247], v[14:15]
	v_lshlrev_b32_e32 v48, 16, v48
	v_lshlrev_b32_e32 v49, 16, v49
	v_lshlrev_b32_e32 v50, 16, v50
	v_lshlrev_b32_e32 v51, 16, v51
	v_lshlrev_b32_e32 v52, 16, v52
	v_lshlrev_b32_e32 v53, 16, v53
	v_lshlrev_b32_e32 v54, 16, v54
	v_lshlrev_b32_e32 v55, 16, v55
	v_lshlrev_b32_e32 v56, 16, v56
	v_lshlrev_b32_e32 v57, 16, v57
	v_lshlrev_b32_e32 v58, 16, v58
	v_lshlrev_b32_e32 v59, 16, v59
	v_lshlrev_b32_e32 v60, 16, v60
	v_lshlrev_b32_e32 v61, 16, v61
	v_lshlrev_b32_e32 v62, 16, v62
	v_lshlrev_b32_e32 v63, 16, v63
	v_exp_f32_e32 v0, v0
	v_exp_f32_e32 v1, v1
	v_exp_f32_e32 v2, v2
	v_exp_f32_e32 v3, v3
	v_exp_f32_e32 v4, v4
; #define LAS __attribute__((address_space(3)))
; #define WAVE_SYNC() asm volatile("s_waitcnt lgkmcnt(0)" ::: "memory")
; __device__ __forceinline__ unsigned f2bf(float f) { unsigned r; asm("v_cvt_pk_bf16_f32 %0, %1, %1" : "=v"(r) : "v"(f)); return r & 0xffffu; }
; __device__ __forceinline__ float sigmoid_f(float x) { return rcpf_(1.f + __expf(-x)); }
; __device__ __forceinline__ float gelu_tanh_f(float x) { const float y = 0.7978845608028654f * (x + 0.044715f * x * x * x); return x * sigmoid_f(2.f * y); }
; __device__ __forceinline__ f32x4 mfma16(bf16x8 a, bf16x8 b, f32x4 c) { return __builtin_amdgcn_mfma_f32_16x16x32_bf16(a, b, c, 0, 0, 0); }
; template <bool FINAL, int D>
; __device__ __forceinline__ void rg_dir(PREF p, int l, int h, int ch, int sidx, int rowbase  , LAS bf16_t* sXc, LAS float* stg, int lane) {
;     ...
;         const bf16x8 A0 = *(const LAS bf16x8*)(sXc + (mt * 16 + (lane & 15)) * 72 + (lane >> 4) * 8), A1 = *(const LAS bf16x8*)(sXc + (mt * 16 + (lane & 15)) * 72 + 32 + (lane >> 4) * 8);
;         f32x4 ar[4], ai[4];
; #pragma unroll
;         for (int nt = 0; nt < 4; ++nt) { const f32x4 z = {0.f, 0.f, 0.f, 0.f};
;             ar[nt] = mfma16(A0, Br[nt][0], z); ar[nt] = mfma16(A1, Br[nt][1], ar[nt]); ai[nt] = mfma16(A0, Bi[nt][0], z); ai[nt] = mfma16(A1, Bi[nt][1], ai[nt]); }
;         WAVE_SYNC();
; #pragma unroll
;         for (int nt = 0; nt < 4; ++nt)
; #pragma unroll
;             for (int j = 0; j < 4; ++j) { const int o = ((lane >> 4) * 4 + j) * 64 + nt * 16 + (lane & 15); stg[o] = ar[nt][j]; stg[1024 + o] = ai[nt][j]; }
;     ...
;             const float r = sigmoid_f(zr), ig = sigmoid_f(zi);
;             const float a = __builtin_amdgcn_exp2f(r * sp8);
;             const float xc = bf2f(sXc[(mt * 16 + tk) * 72 + lane]);
;             av[ti] = a; iv[ti] = __builtin_amdgcn_sqrtf(fmaxf(1.f - a * a, 0.f)) * ig * xc;
;             if (FINAL && D == 1) grv[ti] = gelu_tanh_f(grv[ti]);
;         }
; #pragma unroll
;         for (int ti = 0; ti < 16; ++ti) { const int tk = D ? 15 - ti : ti;
;             hc = av[ti] * hc + iv[ti]; Ap *= av[ti];
;             if (FINAL) { const size_t row = (size_t)(rowbase + mt * 16 + tk);
;                 if (D == 0) TMP[row * 512 + ch] = (bf16_t)f2bf(hc);
	v_exp_f32_e32 v5, v5
	v_exp_f32_e32 v6, v6
	v_exp_f32_e32 v7, v7
	v_exp_f32_e32 v8, v8
	v_exp_f32_e32 v9, v9
	v_exp_f32_e32 v10, v10
	v_exp_f32_e32 v11, v11
	v_exp_f32_e32 v12, v12
	v_exp_f32_e32 v13, v13
	v_exp_f32_e32 v14, v14
	v_exp_f32_e32 v15, v15
	v_fma_f32 v32, -v0, v0, 1.0 clamp
	v_fma_f32 v33, -v1, v1, 1.0 clamp
	v_fma_f32 v34, -v2, v2, 1.0 clamp
	v_fma_f32 v35, -v3, v3, 1.0 clamp
	v_fma_f32 v36, -v4, v4, 1.0 clamp
	v_fma_f32 v37, -v5, v5, 1.0 clamp
	v_fma_f32 v38, -v6, v6, 1.0 clamp
	v_fma_f32 v39, -v7, v7, 1.0 clamp
	v_fma_f32 v40, -v8, v8, 1.0 clamp
	v_fma_f32 v41, -v9, v9, 1.0 clamp
	v_fma_f32 v42, -v10, v10, 1.0 clamp
	v_fma_f32 v43, -v11, v11, 1.0 clamp
	v_fma_f32 v44, -v12, v12, 1.0 clamp
	v_fma_f32 v45, -v13, v13, 1.0 clamp
	v_fma_f32 v46, -v14, v14, 1.0 clamp
	v_fma_f32 v47, -v15, v15, 1.0 clamp
	v_sqrt_f32_e32 v32, v32
	v_sqrt_f32_e32 v33, v33
	v_sqrt_f32_e32 v34, v34
	v_sqrt_f32_e32 v35, v35
	v_sqrt_f32_e32 v36, v36
	v_sqrt_f32_e32 v37, v37
	v_sqrt_f32_e32 v38, v38
	v_sqrt_f32_e32 v39, v39
	v_sqrt_f32_e32 v40, v40
	v_sqrt_f32_e32 v41, v41
	v_sqrt_f32_e32 v42, v42
	v_sqrt_f32_e32 v43, v43
	v_sqrt_f32_e32 v44, v44
	v_sqrt_f32_e32 v45, v45
	v_sqrt_f32_e32 v46, v46
	v_sqrt_f32_e32 v47, v47
	s_nop 0
	v_pk_mul_f32 v[16:17], v[16:17], v[32:33]
	v_pk_mul_f32 v[18:19], v[18:19], v[34:35]
	v_pk_mul_f32 v[20:21], v[20:21], v[36:37]
	v_pk_mul_f32 v[22:23], v[22:23], v[38:39]
	v_pk_mul_f32 v[24:25], v[24:25], v[40:41]
	v_pk_mul_f32 v[26:27], v[26:27], v[42:43]
	v_pk_mul_f32 v[28:29], v[28:29], v[44:45]
	v_pk_mul_f32 v[30:31], v[30:31], v[46:47]
	v_pk_mul_f32 v[16:17], v[16:17], v[48:49]
	v_pk_mul_f32 v[18:19], v[18:19], v[50:51]
	v_pk_mul_f32 v[20:21], v[20:21], v[52:53]
	v_pk_mul_f32 v[22:23], v[22:23], v[54:55]
	v_pk_mul_f32 v[24:25], v[24:25], v[56:57]
	v_pk_mul_f32 v[26:27], v[26:27], v[58:59]
	v_pk_mul_f32 v[28:29], v[28:29], v[60:61]
	v_pk_mul_f32 v[30:31], v[30:31], v[62:63]
	v_fma_f32 v32, v0, v250, v16
	v_fma_f32 v250, v1, v32, v17
	v_cvt_pk_bf16_f32 v166, v32, v250
	v_fma_f32 v32, v2, v250, v18
	v_fma_f32 v250, v3, v32, v19
	v_cvt_pk_bf16_f32 v167, v32, v250
	v_fma_f32 v32, v4, v250, v20
	v_fma_f32 v250, v5, v32, v21
	v_cvt_pk_bf16_f32 v168, v32, v250
	v_fma_f32 v32, v6, v250, v22
	v_fma_f32 v250, v7, v32, v23
	v_cvt_pk_bf16_f32 v169, v32, v250
	v_fma_f32 v32, v8, v250, v24
	v_fma_f32 v250, v9, v32, v25
	v_cvt_pk_bf16_f32 v170, v32, v250
	v_fma_f32 v32, v10, v250, v26
	v_fma_f32 v250, v11, v32, v27
	v_cvt_pk_bf16_f32 v171, v32, v250
	v_fma_f32 v32, v12, v250, v28
	v_fma_f32 v250, v13, v32, v29
	v_cvt_pk_bf16_f32 v172, v32, v250
	v_fma_f32 v32, v14, v250, v30
	v_fma_f32 v250, v15, v32, v31
	v_cvt_pk_bf16_f32 v173, v32, v250
	ds_read_b128 v[32:35], v236 offset:4608
	ds_read_b128 v[36:39], v236 offset:4672
	s_waitcnt lgkmcnt(0)
	v_mfma_f32_16x16x32_bf16 v[0:3], v[32:35], v[80:83], 0
	v_mfma_f32_16x16x32_bf16 v[4:7], v[32:35], v[88:91], 0
	v_mfma_f32_16x16x32_bf16 v[8:11], v[32:35], v[96:99], 0
	v_mfma_f32_16x16x32_bf16 v[12:15], v[32:35], v[104:107], 0
	v_mfma_f32_16x16x32_bf16 v[16:19], v[32:35], v[112:115], 0
	v_mfma_f32_16x16x32_bf16 v[20:23], v[32:35], v[120:123], 0
	v_mfma_f32_16x16x32_bf16 v[24:27], v[32:35], v[128:131], 0
	v_mfma_f32_16x16x32_bf16 v[28:31], v[32:35], v[136:139], 0
	v_mfma_f32_16x16x32_bf16 v[0:3], v[36:39], v[84:87], v[0:3]
	v_mfma_f32_16x16x32_bf16 v[4:7], v[36:39], v[92:95], v[4:7]
	v_mfma_f32_16x16x32_bf16 v[8:11], v[36:39], v[100:103], v[8:11]
	v_mfma_f32_16x16x32_bf16 v[12:15], v[36:39], v[108:111], v[12:15]
	v_mfma_f32_16x16x32_bf16 v[16:19], v[36:39], v[116:119], v[16:19]
	v_mfma_f32_16x16x32_bf16 v[20:23], v[36:39], v[124:127], v[20:23]
	v_mfma_f32_16x16x32_bf16 v[24:27], v[36:39], v[132:135], v[24:27]
	v_mfma_f32_16x16x32_bf16 v[28:31], v[36:39], v[228:231], v[28:31]
	s_nop 3
	ds_write2_b32 v237, v0, v4 offset0:0 offset1:16
	ds_write2_b32 v237, v8, v12 offset0:32 offset1:48
	ds_write2_b32 v237, v1, v5 offset0:64 offset1:80
	ds_write2_b32 v237, v9, v13 offset0:96 offset1:112
	ds_write2_b32 v237, v2, v6 offset0:128 offset1:144
	ds_write2_b32 v237, v10, v14 offset0:160 offset1:176
	ds_write2_b32 v237, v3, v7 offset0:192 offset1:208
	ds_write2_b32 v237, v11, v15 offset0:224 offset1:240
	ds_write2_b32 v238, v16, v20 offset0:0 offset1:16
	ds_write2_b32 v238, v24, v28 offset0:32 offset1:48
	ds_write2_b32 v238, v17, v21 offset0:64 offset1:80
	ds_write2_b32 v238, v25, v29 offset0:96 offset1:112
	ds_write2_b32 v238, v18, v22 offset0:128 offset1:144
	ds_write2_b32 v238, v26, v30 offset0:160 offset1:176
	ds_write2_b32 v238, v19, v23 offset0:192 offset1:208
	ds_write2_b32 v238, v27, v31 offset0:224 offset1:240
	s_waitcnt lgkmcnt(0)
	ds_read2st64_b32 v[0:1], v239 offset0:36 offset1:37
	ds_read2st64_b32 v[2:3], v239 offset0:38 offset1:39
	ds_read2st64_b32 v[4:5], v239 offset0:40 offset1:41
	ds_read2st64_b32 v[6:7], v239 offset0:42 offset1:43
	ds_read2st64_b32 v[8:9], v239 offset0:44 offset1:45
	ds_read2st64_b32 v[10:11], v239 offset0:46 offset1:47
	ds_read2st64_b32 v[12:13], v239 offset0:48 offset1:49
	ds_read2st64_b32 v[14:15], v239 offset0:50 offset1:51
	ds_read2st64_b32 v[16:17], v239 offset0:52 offset1:53
	ds_read2st64_b32 v[18:19], v239 offset0:54 offset1:55
	ds_read2st64_b32 v[20:21], v239 offset0:56 offset1:57
	ds_read2st64_b32 v[22:23], v239 offset0:58 offset1:59
	ds_read2st64_b32 v[24:25], v239 offset0:60 offset1:61
	ds_read2st64_b32 v[26:27], v239 offset0:62 offset1:63
	ds_read2st64_b32 v[28:29], v239 offset0:64 offset1:65
	ds_read2st64_b32 v[30:31], v239 offset0:66 offset1:67
	ds_read_u16 v48, v240 offset:4608
	ds_read_u16 v49, v240 offset:4752
	ds_read_u16 v50, v240 offset:4896
	ds_read_u16 v51, v240 offset:5040
	ds_read_u16 v52, v240 offset:5184
	ds_read_u16 v53, v240 offset:5328
	ds_read_u16 v54, v240 offset:5472
	ds_read_u16 v55, v240 offset:5616
	ds_read_u16 v56, v240 offset:5760
	ds_read_u16 v57, v240 offset:5904
	ds_read_u16 v58, v240 offset:6048
	ds_read_u16 v59, v240 offset:6192
	ds_read_u16 v60, v240 offset:6336
	ds_read_u16 v61, v240 offset:6480
	ds_read_u16 v62, v240 offset:6624
	ds_read_u16 v63, v240 offset:6768
	s_waitcnt lgkmcnt(0)
; __device__ __forceinline__ unsigned f2bf(float f) { unsigned r; asm("v_cvt_pk_bf16_f32 %0, %1, %1" : "=v"(r) : "v"(f)); return r & 0xffffu; }
; __device__ __forceinline__ float sigmoid_f(float x) { return rcpf_(1.f + __expf(-x)); }
; __device__ __forceinline__ float gelu_tanh_f(float x) { const float y = 0.7978845608028654f * (x + 0.044715f * x * x * x); return x * sigmoid_f(2.f * y); }
; template <bool FINAL, int D>
; __device__ __forceinline__ void rg_dir(PREF p, int l, int h, int ch, int sidx, int rowbase  , LAS bf16_t* sXc, LAS float* stg, int lane) {
;     ...
;         for (int ti = 0; ti < 16; ++ti) { const int tk = D ? 15 - ti : ti;
;             const float zr = stg[tk * 64 + lane] + ba, zi = stg[1024 + tk * 64 + lane] + bi;
;             const float r = sigmoid_f(zr), ig = sigmoid_f(zi);
;             const float a = __builtin_amdgcn_exp2f(r * sp8);
;             const float xc = bf2f(sXc[(mt * 16 + tk) * 72 + lane]);
;             av[ti] = a; iv[ti] = __builtin_amdgcn_sqrtf(fmaxf(1.f - a * a, 0.f)) * ig * xc;
;             if (FINAL && D == 1) grv[ti] = gelu_tanh_f(grv[ti]);
;         }
; #pragma unroll
;         for (int ti = 0; ti < 16; ++ti) { const int tk = D ? 15 - ti : ti;
;             hc = av[ti] * hc + iv[ti]; Ap *= av[ti];
;             if (FINAL) { const size_t row = (size_t)(rowbase + mt * 16 + tk);
;                 if (D == 0) TMP[row * 512 + ch] = (bf16_t)f2bf(hc);
;                 else MIX[row * DM + ch] = (bf16_t)f2bf(grv[ti] * (hfv[ti] + hc)); }
;         }
	v_pk_fma_f32 v[0:1], v[0:1], v[248:249], v[242:243]
	v_pk_fma_f32 v[2:3], v[2:3], v[248:249], v[242:243]
	v_pk_fma_f32 v[4:5], v[4:5], v[248:249], v[242:243]
	v_pk_fma_f32 v[6:7], v[6:7], v[248:249], v[242:243]
	v_pk_fma_f32 v[8:9], v[8:9], v[248:249], v[242:243]
	v_pk_fma_f32 v[10:11], v[10:11], v[248:249], v[242:243]
	v_pk_fma_f32 v[12:13], v[12:13], v[248:249], v[242:243]
	v_pk_fma_f32 v[14:15], v[14:15], v[248:249], v[242:243]
	v_pk_fma_f32 v[16:17], v[16:17], v[248:249], v[244:245]
	v_pk_fma_f32 v[18:19], v[18:19], v[248:249], v[244:245]
	v_pk_fma_f32 v[20:21], v[20:21], v[248:249], v[244:245]
	v_pk_fma_f32 v[22:23], v[22:23], v[248:249], v[244:245]
	v_pk_fma_f32 v[24:25], v[24:25], v[248:249], v[244:245]
	v_pk_fma_f32 v[26:27], v[26:27], v[248:249], v[244:245]
	v_pk_fma_f32 v[28:29], v[28:29], v[248:249], v[244:245]
	v_pk_fma_f32 v[30:31], v[30:31], v[248:249], v[244:245]
	v_exp_f32_e32 v0, v0
	v_exp_f32_e32 v1, v1
	v_exp_f32_e32 v2, v2
	v_exp_f32_e32 v3, v3
	v_exp_f32_e32 v4, v4
	v_exp_f32_e32 v5, v5
	v_exp_f32_e32 v6, v6
	v_exp_f32_e32 v7, v7
	v_exp_f32_e32 v8, v8
	v_exp_f32_e32 v9, v9
	v_exp_f32_e32 v10, v10
	v_exp_f32_e32 v11, v11
	v_exp_f32_e32 v12, v12
	v_exp_f32_e32 v13, v13
	v_exp_f32_e32 v14, v14
	v_exp_f32_e32 v15, v15
	v_exp_f32_e32 v16, v16
	v_exp_f32_e32 v17, v17
	v_exp_f32_e32 v18, v18
	v_exp_f32_e32 v19, v19
	v_exp_f32_e32 v20, v20
	v_exp_f32_e32 v21, v21
	v_exp_f32_e32 v22, v22
	v_exp_f32_e32 v23, v23
	v_exp_f32_e32 v24, v24
	v_exp_f32_e32 v25, v25
	v_exp_f32_e32 v26, v26
	v_exp_f32_e32 v27, v27
	v_exp_f32_e32 v28, v28
	v_exp_f32_e32 v29, v29
	v_exp_f32_e32 v30, v30
	v_exp_f32_e32 v31, v31
	v_pk_add_f32 v[0:1], v[0:1], 1.0 op_sel_hi:[1,0]
	v_pk_add_f32 v[2:3], v[2:3], 1.0 op_sel_hi:[1,0]
	v_pk_add_f32 v[4:5], v[4:5], 1.0 op_sel_hi:[1,0]
	v_pk_add_f32 v[6:7], v[6:7], 1.0 op_sel_hi:[1,0]
	v_pk_add_f32 v[8:9], v[8:9], 1.0 op_sel_hi:[1,0]
	v_pk_add_f32 v[10:11], v[10:11], 1.0 op_sel_hi:[1,0]
	v_pk_add_f32 v[12:13], v[12:13], 1.0 op_sel_hi:[1,0]
	v_pk_add_f32 v[14:15], v[14:15], 1.0 op_sel_hi:[1,0]
	v_pk_add_f32 v[16:17], v[16:17], 1.0 op_sel_hi:[1,0]
	v_pk_add_f32 v[18:19], v[18:19], 1.0 op_sel_hi:[1,0]
	v_pk_add_f32 v[20:21], v[20:21], 1.0 op_sel_hi:[1,0]
	v_pk_add_f32 v[22:23], v[22:23], 1.0 op_sel_hi:[1,0]
	v_pk_add_f32 v[24:25], v[24:25], 1.0 op_sel_hi:[1,0]
	v_pk_add_f32 v[26:27], v[26:27], 1.0 op_sel_hi:[1,0]
	v_pk_add_f32 v[28:29], v[28:29], 1.0 op_sel_hi:[1,0]
	v_pk_add_f32 v[30:31], v[30:31], 1.0 op_sel_hi:[1,0]
	v_rcp_f32_e32 v0, v0
	v_rcp_f32_e32 v1, v1
	v_rcp_f32_e32 v2, v2
	v_rcp_f32_e32 v3, v3
	v_rcp_f32_e32 v4, v4
	v_rcp_f32_e32 v5, v5
	v_rcp_f32_e32 v6, v6
	v_rcp_f32_e32 v7, v7
	v_rcp_f32_e32 v8, v8
	v_rcp_f32_e32 v9, v9
	v_rcp_f32_e32 v10, v10
	v_rcp_f32_e32 v11, v11
	v_rcp_f32_e32 v12, v12
	v_rcp_f32_e32 v13, v13
	v_rcp_f32_e32 v14, v14
	v_rcp_f32_e32 v15, v15
	v_rcp_f32_e32 v16, v16
	v_rcp_f32_e32 v17, v17
	v_rcp_f32_e32 v18, v18
	v_rcp_f32_e32 v19, v19
	v_rcp_f32_e32 v20, v20
	v_rcp_f32_e32 v21, v21
	v_rcp_f32_e32 v22, v22
	v_rcp_f32_e32 v23, v23
	v_rcp_f32_e32 v24, v24
	v_rcp_f32_e32 v25, v25
	v_rcp_f32_e32 v26, v26
	v_rcp_f32_e32 v27, v27
	v_rcp_f32_e32 v28, v28
	v_rcp_f32_e32 v29, v29
	v_rcp_f32_e32 v30, v30
	v_rcp_f32_e32 v31, v31
	v_pk_mul_f32 v[0:1], v[246:247], v[0:1]
	v_pk_mul_f32 v[2:3], v[246:247], v[2:3]
	v_pk_mul_f32 v[4:5], v[246:247], v[4:5]
	v_pk_mul_f32 v[6:7], v[246:247], v[6:7]
	v_pk_mul_f32 v[8:9], v[246:247], v[8:9]
	v_pk_mul_f32 v[10:11], v[246:247], v[10:11]
	v_pk_mul_f32 v[12:13], v[246:247], v[12:13]
	v_pk_mul_f32 v[14:15], v[246:247], v[14:15]
	v_lshlrev_b32_e32 v48, 16, v48
	v_lshlrev_b32_e32 v49, 16, v49
	v_lshlrev_b32_e32 v50, 16, v50
	v_lshlrev_b32_e32 v51, 16, v51
	v_lshlrev_b32_e32 v52, 16, v52
	v_lshlrev_b32_e32 v53, 16, v53
	v_lshlrev_b32_e32 v54, 16, v54
	v_lshlrev_b32_e32 v55, 16, v55
	v_lshlrev_b32_e32 v56, 16, v56
	v_lshlrev_b32_e32 v57, 16, v57
	v_lshlrev_b32_e32 v58, 16, v58
	v_lshlrev_b32_e32 v59, 16, v59
	v_lshlrev_b32_e32 v60, 16, v60
	v_lshlrev_b32_e32 v61, 16, v61
	v_lshlrev_b32_e32 v62, 16, v62
	v_lshlrev_b32_e32 v63, 16, v63
	v_exp_f32_e32 v0, v0
	v_exp_f32_e32 v1, v1
	v_exp_f32_e32 v2, v2
	v_exp_f32_e32 v3, v3
	v_exp_f32_e32 v4, v4
	v_exp_f32_e32 v5, v5
	v_exp_f32_e32 v6, v6
	v_exp_f32_e32 v7, v7
	v_exp_f32_e32 v8, v8
	v_exp_f32_e32 v9, v9
	v_exp_f32_e32 v10, v10
	v_exp_f32_e32 v11, v11
	v_exp_f32_e32 v12, v12
	v_exp_f32_e32 v13, v13
	v_exp_f32_e32 v14, v14
	v_exp_f32_e32 v15, v15
	v_fma_f32 v32, -v0, v0, 1.0 clamp
	v_fma_f32 v33, -v1, v1, 1.0 clamp
	v_fma_f32 v34, -v2, v2, 1.0 clamp
	v_fma_f32 v35, -v3, v3, 1.0 clamp
	v_fma_f32 v36, -v4, v4, 1.0 clamp
	v_fma_f32 v37, -v5, v5, 1.0 clamp
	v_fma_f32 v38, -v6, v6, 1.0 clamp
	v_fma_f32 v39, -v7, v7, 1.0 clamp
	v_fma_f32 v40, -v8, v8, 1.0 clamp
	v_fma_f32 v41, -v9, v9, 1.0 clamp
	v_fma_f32 v42, -v10, v10, 1.0 clamp
	v_fma_f32 v43, -v11, v11, 1.0 clamp
	v_fma_f32 v44, -v12, v12, 1.0 clamp
	v_fma_f32 v45, -v13, v13, 1.0 clamp
	v_fma_f32 v46, -v14, v14, 1.0 clamp
	v_fma_f32 v47, -v15, v15, 1.0 clamp
	v_sqrt_f32_e32 v32, v32
	v_sqrt_f32_e32 v33, v33
	v_sqrt_f32_e32 v34, v34
	v_sqrt_f32_e32 v35, v35
	v_sqrt_f32_e32 v36, v36
	v_sqrt_f32_e32 v37, v37
	v_sqrt_f32_e32 v38, v38
	v_sqrt_f32_e32 v39, v39
	v_sqrt_f32_e32 v40, v40
	v_sqrt_f32_e32 v41, v41
	v_sqrt_f32_e32 v42, v42
	v_sqrt_f32_e32 v43, v43
	v_sqrt_f32_e32 v44, v44
	v_sqrt_f32_e32 v45, v45
	v_sqrt_f32_e32 v46, v46
	v_sqrt_f32_e32 v47, v47
	s_nop 0
	v_pk_mul_f32 v[16:17], v[16:17], v[32:33]
	v_pk_mul_f32 v[18:19], v[18:19], v[34:35]
	v_pk_mul_f32 v[20:21], v[20:21], v[36:37]
	v_pk_mul_f32 v[22:23], v[22:23], v[38:39]
	v_pk_mul_f32 v[24:25], v[24:25], v[40:41]
	v_pk_mul_f32 v[26:27], v[26:27], v[42:43]
	v_pk_mul_f32 v[28:29], v[28:29], v[44:45]
	v_pk_mul_f32 v[30:31], v[30:31], v[46:47]
	v_pk_mul_f32 v[16:17], v[16:17], v[48:49]
	v_pk_mul_f32 v[18:19], v[18:19], v[50:51]
	v_pk_mul_f32 v[20:21], v[20:21], v[52:53]
	v_pk_mul_f32 v[22:23], v[22:23], v[54:55]
	v_pk_mul_f32 v[24:25], v[24:25], v[56:57]
	v_pk_mul_f32 v[26:27], v[26:27], v[58:59]
	v_pk_mul_f32 v[28:29], v[28:29], v[60:61]
	v_pk_mul_f32 v[30:31], v[30:31], v[62:63]
	v_fma_f32 v32, v0, v250, v16
	v_fma_f32 v250, v1, v32, v17
	v_cvt_pk_bf16_f32 v174, v32, v250
	v_fma_f32 v32, v2, v250, v18
	v_fma_f32 v250, v3, v32, v19
	v_cvt_pk_bf16_f32 v175, v32, v250
	v_fma_f32 v32, v4, v250, v20
	v_fma_f32 v250, v5, v32, v21
	v_cvt_pk_bf16_f32 v176, v32, v250
	v_fma_f32 v32, v6, v250, v22
	v_fma_f32 v250, v7, v32, v23
	v_cvt_pk_bf16_f32 v177, v32, v250
	v_fma_f32 v32, v8, v250, v24
	v_fma_f32 v250, v9, v32, v25
	v_cvt_pk_bf16_f32 v178, v32, v250
	v_fma_f32 v32, v10, v250, v26
	v_fma_f32 v250, v11, v32, v27
	v_cvt_pk_bf16_f32 v179, v32, v250
	v_fma_f32 v32, v12, v250, v28
	v_fma_f32 v250, v13, v32, v29
	v_cvt_pk_bf16_f32 v180, v32, v250
	v_fma_f32 v32, v14, v250, v30
	v_fma_f32 v250, v15, v32, v31
	v_cvt_pk_bf16_f32 v181, v32, v250
	ds_read_b128 v[32:35], v236 offset:6912
	ds_read_b128 v[36:39], v236 offset:6976
	s_waitcnt lgkmcnt(0)
; #define LAS __attribute__((address_space(3)))
; #define WAVE_SYNC() asm volatile("s_waitcnt lgkmcnt(0)" ::: "memory")
; __device__ __forceinline__ f32x4 mfma16(bf16x8 a, bf16x8 b, f32x4 c) { return __builtin_amdgcn_mfma_f32_16x16x32_bf16(a, b, c, 0, 0, 0); }
; template <bool FINAL, int D>
; __device__ __forceinline__ void rg_dir(PREF p, int l, int h, int ch, int sidx, int rowbase  , LAS bf16_t* sXc, LAS float* stg, int lane) {
;     ...
;     bf16x8 Br[4][2], Bi[4][2];
; #pragma unroll
;     for (int nt = 0; nt < 4; ++nt) { const int o0 = (nt * 16 + (lane & 15)) * 64 + (lane >> 4) * 8;
;         Br[nt][0] = *(const bf16x8*)(wr_ + o0); Br[nt][1] = *(const bf16x8*)(wr_ + o0 + 32); Bi[nt][0] = *(const bf16x8*)(wi_ + o0); Bi[nt][1] = *(const bf16x8*)(wi_ + o0 + 32); }
;     ...
;         const bf16x8 A0 = *(const LAS bf16x8*)(sXc + (mt * 16 + (lane & 15)) * 72 + (lane >> 4) * 8), A1 = *(const LAS bf16x8*)(sXc + (mt * 16 + (lane & 15)) * 72 + 32 + (lane >> 4) * 8);
;         f32x4 ar[4], ai[4];
; #pragma unroll
;         for (int nt = 0; nt < 4; ++nt) { const f32x4 z = {0.f, 0.f, 0.f, 0.f};
;             ar[nt] = mfma16(A0, Br[nt][0], z); ar[nt] = mfma16(A1, Br[nt][1], ar[nt]); ai[nt] = mfma16(A0, Bi[nt][0], z); ai[nt] = mfma16(A1, Bi[nt][1], ai[nt]); }
;         WAVE_SYNC();
; #pragma unroll
;         for (int nt = 0; nt < 4; ++nt)
; #pragma unroll
;             for (int j = 0; j < 4; ++j) { const int o = ((lane >> 4) * 4 + j) * 64 + nt * 16 + (lane & 15); stg[o] = ar[nt][j]; stg[1024 + o] = ai[nt][j]; }
;         WAVE_SYNC();
;         float av[16], iv[16];
; #pragma unroll
;         for (int ti = 0; ti < 16; ++ti) { const int tk = D ? 15 - ti : ti;
;             const float zr = stg[tk * 64 + lane] + ba, zi = stg[1024 + tk * 64 + lane] + bi;
	v_mfma_f32_16x16x32_bf16 v[0:3], v[32:35], v[80:83], 0
	v_mfma_f32_16x16x32_bf16 v[4:7], v[32:35], v[88:91], 0
	v_mfma_f32_16x16x32_bf16 v[8:11], v[32:35], v[96:99], 0
	v_mfma_f32_16x16x32_bf16 v[12:15], v[32:35], v[104:107], 0
	v_mfma_f32_16x16x32_bf16 v[16:19], v[32:35], v[112:115], 0
	v_mfma_f32_16x16x32_bf16 v[20:23], v[32:35], v[120:123], 0
	v_mfma_f32_16x16x32_bf16 v[24:27], v[32:35], v[128:131], 0
	v_mfma_f32_16x16x32_bf16 v[28:31], v[32:35], v[136:139], 0
	v_mfma_f32_16x16x32_bf16 v[0:3], v[36:39], v[84:87], v[0:3]
	v_mfma_f32_16x16x32_bf16 v[4:7], v[36:39], v[92:95], v[4:7]
	v_mfma_f32_16x16x32_bf16 v[8:11], v[36:39], v[100:103], v[8:11]
	v_mfma_f32_16x16x32_bf16 v[12:15], v[36:39], v[108:111], v[12:15]
	v_mfma_f32_16x16x32_bf16 v[16:19], v[36:39], v[116:119], v[16:19]
	v_mfma_f32_16x16x32_bf16 v[20:23], v[36:39], v[124:127], v[20:23]
	v_mfma_f32_16x16x32_bf16 v[24:27], v[36:39], v[132:135], v[24:27]
	v_mfma_f32_16x16x32_bf16 v[28:31], v[36:39], v[228:231], v[28:31]
	s_nop 3
	ds_write2_b32 v237, v0, v4 offset0:0 offset1:16
	ds_write2_b32 v237, v8, v12 offset0:32 offset1:48
	ds_write2_b32 v237, v1, v5 offset0:64 offset1:80
	ds_write2_b32 v237, v9, v13 offset0:96 offset1:112
	ds_write2_b32 v237, v2, v6 offset0:128 offset1:144
	ds_write2_b32 v237, v10, v14 offset0:160 offset1:176
	ds_write2_b32 v237, v3, v7 offset0:192 offset1:208
	ds_write2_b32 v237, v11, v15 offset0:224 offset1:240
	ds_write2_b32 v238, v16, v20 offset0:0 offset1:16
	ds_write2_b32 v238, v24, v28 offset0:32 offset1:48
	ds_write2_b32 v238, v17, v21 offset0:64 offset1:80
	ds_write2_b32 v238, v25, v29 offset0:96 offset1:112
	ds_write2_b32 v238, v18, v22 offset0:128 offset1:144
	ds_write2_b32 v238, v26, v30 offset0:160 offset1:176
	ds_write2_b32 v238, v19, v23 offset0:192 offset1:208
	ds_write2_b32 v238, v27, v31 offset0:224 offset1:240
	s_waitcnt lgkmcnt(0)
	ds_read2st64_b32 v[0:1], v239 offset0:36 offset1:37
	ds_read2st64_b32 v[2:3], v239 offset0:38 offset1:39
	ds_read2st64_b32 v[4:5], v239 offset0:40 offset1:41
	ds_read2st64_b32 v[6:7], v239 offset0:42 offset1:43
	ds_read2st64_b32 v[8:9], v239 offset0:44 offset1:45
	ds_read2st64_b32 v[10:11], v239 offset0:46 offset1:47
	ds_read2st64_b32 v[12:13], v239 offset0:48 offset1:49
	ds_read2st64_b32 v[14:15], v239 offset0:50 offset1:51
	ds_read2st64_b32 v[16:17], v239 offset0:52 offset1:53
	ds_read2st64_b32 v[18:19], v239 offset0:54 offset1:55
	ds_read2st64_b32 v[20:21], v239 offset0:56 offset1:57
	ds_read2st64_b32 v[22:23], v239 offset0:58 offset1:59
	ds_read2st64_b32 v[24:25], v239 offset0:60 offset1:61
	ds_read2st64_b32 v[26:27], v239 offset0:62 offset1:63
	ds_read2st64_b32 v[28:29], v239 offset0:64 offset1:65
	ds_read2st64_b32 v[30:31], v239 offset0:66 offset1:67
	ds_read_u16 v48, v240 offset:6912
	ds_read_u16 v49, v240 offset:7056
	ds_read_u16 v50, v240 offset:7200
	ds_read_u16 v51, v240 offset:7344
	ds_read_u16 v52, v240 offset:7488
	ds_read_u16 v53, v240 offset:7632
	ds_read_u16 v54, v240 offset:7776
	ds_read_u16 v55, v240 offset:7920
	ds_read_u16 v56, v240 offset:8064
	ds_read_u16 v57, v240 offset:8208
	ds_read_u16 v58, v240 offset:8352
	ds_read_u16 v59, v240 offset:8496
	ds_read_u16 v60, v240 offset:8640
	ds_read_u16 v61, v240 offset:8784
	ds_read_u16 v62, v240 offset:8928
	ds_read_u16 v63, v240 offset:9072
	s_add_u32 s90, s92, 0x20000
	s_addc_u32 s91, s93, 0
	global_load_dwordx4 v[80:83], v241, s[90:91]
	global_load_dwordx4 v[84:87], v241, s[90:91] offset:64
	global_load_dwordx4 v[88:91], v241, s[90:91] offset:2048
	global_load_dwordx4 v[92:95], v241, s[90:91] offset:2112
	s_add_u32 s90, s92, 0x21000
	s_addc_u32 s91, s93, 0
	global_load_dwordx4 v[96:99], v241, s[90:91]
	global_load_dwordx4 v[100:103], v241, s[90:91] offset:64
	global_load_dwordx4 v[104:107], v241, s[90:91] offset:2048
	global_load_dwordx4 v[108:111], v241, s[90:91] offset:2112
	s_add_u32 s90, s92, 0x30000
	s_addc_u32 s91, s93, 0
	global_load_dwordx4 v[112:115], v241, s[90:91]
	global_load_dwordx4 v[116:119], v241, s[90:91] offset:64
	global_load_dwordx4 v[120:123], v241, s[90:91] offset:2048
	global_load_dwordx4 v[124:127], v241, s[90:91] offset:2112
	s_add_u32 s90, s92, 0x31000
	s_addc_u32 s91, s93, 0
	global_load_dwordx4 v[128:131], v241, s[90:91]
	global_load_dwordx4 v[132:135], v241, s[90:91] offset:64
	global_load_dwordx4 v[136:139], v241, s[90:91] offset:2048
	global_load_dwordx4 v[228:231], v241, s[90:91] offset:2112
	s_waitcnt lgkmcnt(0)
; __device__ __forceinline__ float sigmoid_f(float x) { return rcpf_(1.f + __expf(-x)); }
; template <bool FINAL, int D>
; __device__ __forceinline__ void rg_dir(PREF p, int l, int h, int ch, int sidx, int rowbase  , LAS bf16_t* sXc, LAS float* stg, int lane) {
;     ...
;         for (int ti = 0; ti < 16; ++ti) { const int tk = D ? 15 - ti : ti;
;             const float zr = stg[tk * 64 + lane] + ba, zi = stg[1024 + tk * 64 + lane] + bi;
;             const float r = sigmoid_f(zr), ig = sigmoid_f(zi);
;             const float a = __builtin_amdgcn_exp2f(r * sp8);
;             const float xc = bf2f(sXc[(mt * 16 + tk) * 72 + lane]);
;             av[ti] = a; iv[ti] = __builtin_amdgcn_sqrtf(fmaxf(1.f - a * a, 0.f)) * ig * xc;
	v_pk_fma_f32 v[0:1], v[0:1], v[248:249], v[242:243]
	v_pk_fma_f32 v[2:3], v[2:3], v[248:249], v[242:243]
	v_pk_fma_f32 v[4:5], v[4:5], v[248:249], v[242:243]
	v_pk_fma_f32 v[6:7], v[6:7], v[248:249], v[242:243]
	v_pk_fma_f32 v[8:9], v[8:9], v[248:249], v[242:243]
	v_pk_fma_f32 v[10:11], v[10:11], v[248:249], v[242:243]
	v_pk_fma_f32 v[12:13], v[12:13], v[248:249], v[242:243]
	v_pk_fma_f32 v[14:15], v[14:15], v[248:249], v[242:243]
	v_pk_fma_f32 v[16:17], v[16:17], v[248:249], v[244:245]
	v_pk_fma_f32 v[18:19], v[18:19], v[248:249], v[244:245]
	v_pk_fma_f32 v[20:21], v[20:21], v[248:249], v[244:245]
	v_pk_fma_f32 v[22:23], v[22:23], v[248:249], v[244:245]
	v_pk_fma_f32 v[24:25], v[24:25], v[248:249], v[244:245]
	v_pk_fma_f32 v[26:27], v[26:27], v[248:249], v[244:245]
	v_pk_fma_f32 v[28:29], v[28:29], v[248:249], v[244:245]
	v_pk_fma_f32 v[30:31], v[30:31], v[248:249], v[244:245]
	v_exp_f32_e32 v0, v0
	v_exp_f32_e32 v1, v1
	v_exp_f32_e32 v2, v2
	v_exp_f32_e32 v3, v3
	v_exp_f32_e32 v4, v4
	v_exp_f32_e32 v5, v5
	v_exp_f32_e32 v6, v6
	v_exp_f32_e32 v7, v7
	v_exp_f32_e32 v8, v8
	v_exp_f32_e32 v9, v9
	v_exp_f32_e32 v10, v10
	v_exp_f32_e32 v11, v11
	v_exp_f32_e32 v12, v12
	v_exp_f32_e32 v13, v13
	v_exp_f32_e32 v14, v14
	v_exp_f32_e32 v15, v15
	v_exp_f32_e32 v16, v16
	v_exp_f32_e32 v17, v17
	v_exp_f32_e32 v18, v18
	v_exp_f32_e32 v19, v19
	v_exp_f32_e32 v20, v20
	v_exp_f32_e32 v21, v21
	v_exp_f32_e32 v22, v22
	v_exp_f32_e32 v23, v23
	v_exp_f32_e32 v24, v24
	v_exp_f32_e32 v25, v25
	v_exp_f32_e32 v26, v26
	v_exp_f32_e32 v27, v27
	v_exp_f32_e32 v28, v28
	v_exp_f32_e32 v29, v29
	v_exp_f32_e32 v30, v30
	v_exp_f32_e32 v31, v31
	v_pk_add_f32 v[0:1], v[0:1], 1.0 op_sel_hi:[1,0]
	v_pk_add_f32 v[2:3], v[2:3], 1.0 op_sel_hi:[1,0]
	v_pk_add_f32 v[4:5], v[4:5], 1.0 op_sel_hi:[1,0]
	v_pk_add_f32 v[6:7], v[6:7], 1.0 op_sel_hi:[1,0]
	v_pk_add_f32 v[8:9], v[8:9], 1.0 op_sel_hi:[1,0]
	v_pk_add_f32 v[10:11], v[10:11], 1.0 op_sel_hi:[1,0]
	v_pk_add_f32 v[12:13], v[12:13], 1.0 op_sel_hi:[1,0]
	v_pk_add_f32 v[14:15], v[14:15], 1.0 op_sel_hi:[1,0]
	v_pk_add_f32 v[16:17], v[16:17], 1.0 op_sel_hi:[1,0]
	v_pk_add_f32 v[18:19], v[18:19], 1.0 op_sel_hi:[1,0]
	v_pk_add_f32 v[20:21], v[20:21], 1.0 op_sel_hi:[1,0]
	v_pk_add_f32 v[22:23], v[22:23], 1.0 op_sel_hi:[1,0]
	v_pk_add_f32 v[24:25], v[24:25], 1.0 op_sel_hi:[1,0]
	v_pk_add_f32 v[26:27], v[26:27], 1.0 op_sel_hi:[1,0]
	v_pk_add_f32 v[28:29], v[28:29], 1.0 op_sel_hi:[1,0]
	v_pk_add_f32 v[30:31], v[30:31], 1.0 op_sel_hi:[1,0]
	v_rcp_f32_e32 v0, v0
	v_rcp_f32_e32 v1, v1
	v_rcp_f32_e32 v2, v2
	v_rcp_f32_e32 v3, v3
	v_rcp_f32_e32 v4, v4
	v_rcp_f32_e32 v5, v5
	v_rcp_f32_e32 v6, v6
	v_rcp_f32_e32 v7, v7
	v_rcp_f32_e32 v8, v8
	v_rcp_f32_e32 v9, v9
	v_rcp_f32_e32 v10, v10
	v_rcp_f32_e32 v11, v11
	v_rcp_f32_e32 v12, v12
	v_rcp_f32_e32 v13, v13
	v_rcp_f32_e32 v14, v14
	v_rcp_f32_e32 v15, v15
	v_rcp_f32_e32 v16, v16
	v_rcp_f32_e32 v17, v17
	v_rcp_f32_e32 v18, v18
	v_rcp_f32_e32 v19, v19
	v_rcp_f32_e32 v20, v20
	v_rcp_f32_e32 v21, v21
	v_rcp_f32_e32 v22, v22
	v_rcp_f32_e32 v23, v23
	v_rcp_f32_e32 v24, v24
	v_rcp_f32_e32 v25, v25
	v_rcp_f32_e32 v26, v26
	v_rcp_f32_e32 v27, v27
	v_rcp_f32_e32 v28, v28
	v_rcp_f32_e32 v29, v29
	v_rcp_f32_e32 v30, v30
	v_rcp_f32_e32 v31, v31
	v_pk_mul_f32 v[0:1], v[246:247], v[0:1]
	v_pk_mul_f32 v[2:3], v[246:247], v[2:3]
	v_pk_mul_f32 v[4:5], v[246:247], v[4:5]
	v_pk_mul_f32 v[6:7], v[246:247], v[6:7]
	v_pk_mul_f32 v[8:9], v[246:247], v[8:9]
	v_pk_mul_f32 v[10:11], v[246:247], v[10:11]
	v_pk_mul_f32 v[12:13], v[246:247], v[12:13]
	v_pk_mul_f32 v[14:15], v[246:247], v[14:15]
	v_lshlrev_b32_e32 v48, 16, v48
	v_lshlrev_b32_e32 v49, 16, v49
	v_lshlrev_b32_e32 v50, 16, v50
	v_lshlrev_b32_e32 v51, 16, v51
	v_lshlrev_b32_e32 v52, 16, v52
	v_lshlrev_b32_e32 v53, 16, v53
	v_lshlrev_b32_e32 v54, 16, v54
	v_lshlrev_b32_e32 v55, 16, v55
	v_lshlrev_b32_e32 v56, 16, v56
	v_lshlrev_b32_e32 v57, 16, v57
	v_lshlrev_b32_e32 v58, 16, v58
	v_lshlrev_b32_e32 v59, 16, v59
	v_lshlrev_b32_e32 v60, 16, v60
	v_lshlrev_b32_e32 v61, 16, v61
	v_lshlrev_b32_e32 v62, 16, v62
	v_lshlrev_b32_e32 v63, 16, v63
	v_exp_f32_e32 v0, v0
	v_exp_f32_e32 v1, v1
	v_exp_f32_e32 v2, v2
	v_exp_f32_e32 v3, v3
	v_exp_f32_e32 v4, v4
	v_exp_f32_e32 v5, v5
	v_exp_f32_e32 v6, v6
	v_exp_f32_e32 v7, v7
	v_exp_f32_e32 v8, v8
	v_exp_f32_e32 v9, v9
	v_exp_f32_e32 v10, v10
	v_exp_f32_e32 v11, v11
	v_exp_f32_e32 v12, v12
	v_exp_f32_e32 v13, v13
	v_exp_f32_e32 v14, v14
	v_exp_f32_e32 v15, v15
	v_fma_f32 v32, -v0, v0, 1.0 clamp
	v_fma_f32 v33, -v1, v1, 1.0 clamp
	v_fma_f32 v34, -v2, v2, 1.0 clamp
	v_fma_f32 v35, -v3, v3, 1.0 clamp
	v_fma_f32 v36, -v4, v4, 1.0 clamp
	v_fma_f32 v37, -v5, v5, 1.0 clamp
	v_fma_f32 v38, -v6, v6, 1.0 clamp
	v_fma_f32 v39, -v7, v7, 1.0 clamp
	v_fma_f32 v40, -v8, v8, 1.0 clamp
	v_fma_f32 v41, -v9, v9, 1.0 clamp
	v_fma_f32 v42, -v10, v10, 1.0 clamp
	v_fma_f32 v43, -v11, v11, 1.0 clamp
	v_fma_f32 v44, -v12, v12, 1.0 clamp
	v_fma_f32 v45, -v13, v13, 1.0 clamp
	v_fma_f32 v46, -v14, v14, 1.0 clamp
	v_fma_f32 v47, -v15, v15, 1.0 clamp
	v_sqrt_f32_e32 v32, v32
	v_sqrt_f32_e32 v33, v33
	v_sqrt_f32_e32 v34, v34
	v_sqrt_f32_e32 v35, v35
	v_sqrt_f32_e32 v36, v36
	v_sqrt_f32_e32 v37, v37
	v_sqrt_f32_e32 v38, v38
	v_sqrt_f32_e32 v39, v39
	v_sqrt_f32_e32 v40, v40
	v_sqrt_f32_e32 v41, v41
	v_sqrt_f32_e32 v42, v42
	v_sqrt_f32_e32 v43, v43
	v_sqrt_f32_e32 v44, v44
	v_sqrt_f32_e32 v45, v45
	v_sqrt_f32_e32 v46, v46
	v_sqrt_f32_e32 v47, v47
	s_nop 0
	v_pk_mul_f32 v[16:17], v[16:17], v[32:33]
	v_pk_mul_f32 v[18:19], v[18:19], v[34:35]
	v_pk_mul_f32 v[20:21], v[20:21], v[36:37]
	v_pk_mul_f32 v[22:23], v[22:23], v[38:39]
	v_pk_mul_f32 v[24:25], v[24:25], v[40:41]
; __device__ __forceinline__ unsigned f2bf(float f) { unsigned r; asm("v_cvt_pk_bf16_f32 %0, %1, %1" : "=v"(r) : "v"(f)); return r & 0xffffu; }
; __device__ __forceinline__ float rcpf_(float x) { return __builtin_amdgcn_rcpf(x); }
; template <bool FINAL, int D>
; __device__ __forceinline__ void rg_dir(PREF p, int l, int h, int ch, int sidx, int rowbase  , LAS bf16_t* sXc, LAS float* stg, int lane) {
;     ...
;     const float ba = p.rg_ba[(l * 2 + D) * 512 + ch], bi = p.rg_bi[(l * 2 + D) * 512 + ch], lam = p.rg_lam[(l * 2 + D) * 512 + ch];
;     const float e_ = __expf(-lam), u_ = 1.f + e_;
;     const float l1p = (u_ == 1.f) ? e_ : __logf(u_) * e_ * rcpf_(u_ - 1.f);
;     const float sp8 = -8.f * 1.4426950408889634f * l1p;
;     float hc = FINAL ? RGC[sidx] : 0.f, Ap = 1.f;
;     ...
;         for (int ti = 0; ti < 16; ++ti) { const int tk = D ? 15 - ti : ti;
;             hc = av[ti] * hc + iv[ti]; Ap *= av[ti];
;             if (FINAL) { const size_t row = (size_t)(rowbase + mt * 16 + tk);
;                 if (D == 0) TMP[row * 512 + ch] = (bf16_t)f2bf(hc);
;                 else MIX[row * DM + ch] = (bf16_t)f2bf(grv[ti] * (hfv[ti] + hc)); }
;         }
	v_pk_mul_f32 v[26:27], v[26:27], v[42:43]
	v_pk_mul_f32 v[28:29], v[28:29], v[44:45]
	v_pk_mul_f32 v[30:31], v[30:31], v[46:47]
	v_pk_mul_f32 v[16:17], v[16:17], v[48:49]
	v_pk_mul_f32 v[18:19], v[18:19], v[50:51]
	v_pk_mul_f32 v[20:21], v[20:21], v[52:53]
	v_pk_mul_f32 v[22:23], v[22:23], v[54:55]
	v_pk_mul_f32 v[24:25], v[24:25], v[56:57]
	v_pk_mul_f32 v[26:27], v[26:27], v[58:59]
	v_pk_mul_f32 v[28:29], v[28:29], v[60:61]
	v_pk_mul_f32 v[30:31], v[30:31], v[62:63]
	global_load_dword v45, v235, s[76:77] offset:2048
	global_load_dword v46, v235, s[78:79] offset:2048
	global_load_dword v47, v235, s[80:81] offset:2048
	global_load_dword v251, v235, s[96:97] offset:2048
	v_fma_f32 v32, v0, v250, v16
	v_fma_f32 v250, v1, v32, v17
	v_cvt_pk_bf16_f32 v182, v32, v250
	v_fma_f32 v32, v2, v250, v18
	v_fma_f32 v250, v3, v32, v19
	v_cvt_pk_bf16_f32 v183, v32, v250
	v_fma_f32 v32, v4, v250, v20
	v_fma_f32 v250, v5, v32, v21
	v_cvt_pk_bf16_f32 v184, v32, v250
	v_fma_f32 v32, v6, v250, v22
	v_fma_f32 v250, v7, v32, v23
	v_cvt_pk_bf16_f32 v185, v32, v250
	v_fma_f32 v32, v8, v250, v24
	v_fma_f32 v250, v9, v32, v25
	v_cvt_pk_bf16_f32 v186, v32, v250
	v_fma_f32 v32, v10, v250, v26
	v_fma_f32 v250, v11, v32, v27
	v_cvt_pk_bf16_f32 v187, v32, v250
	v_fma_f32 v32, v12, v250, v28
	v_fma_f32 v250, v13, v32, v29
	v_cvt_pk_bf16_f32 v188, v32, v250
	v_fma_f32 v32, v14, v250, v30
	v_fma_f32 v250, v15, v32, v31
	v_cvt_pk_bf16_f32 v189, v32, v250
	s_waitcnt vmcnt(0)
	s_mov_b32 s8, 0x800000
	s_mov_b32 s9, 0x3f317217
	s_mov_b32 s14, 0x7f800000
	v_mul_f32_e32 v32, 0xbfb8aa3b, v45
	v_exp_f32_e32 v32, v32
	s_nop 0
	v_add_f32_e32 v33, 1.0, v32
	v_cmp_gt_f32_e32 vcc, s8, v33
	s_nop 1
	v_cndmask_b32_e64 v34, 0, 32, vcc
	v_ldexp_f32 v34, v33, v34
	v_log_f32_e32 v34, v34
	v_cndmask_b32_e32 v36, 0, v226, vcc
	v_cmp_eq_f32_e32 vcc, 1.0, v33
	v_mul_f32_e32 v35, 0x3f317217, v34
	v_fma_f32 v35, v34, s9, -v35
	v_fmac_f32_e32 v35, 0x3377d1cf, v34
	v_fmac_f32_e32 v35, 0x3f317217, v34
	v_cmp_lt_f32_e64 s[10:11], |v34|, s14
	s_nop 1
	v_cndmask_b32_e64 v34, v34, v35, s[10:11]
	v_add_f32_e32 v35, -1.0, v33
	v_rcp_f32_e32 v35, v35
	v_sub_f32_e32 v34, v34, v36
	v_mul_f32_e32 v34, v32, v34
	v_mul_f32_e32 v34, v34, v35
	v_cndmask_b32_e32 v32, v34, v32, vcc
	v_mul_f32_e32 v246, 0xc138aa3b, v32
	v_mov_b32_e32 v247, v246
	v_mul_f32_e32 v242, 0xbfb8aa3b, v46
	v_mul_f32_e32 v244, 0xbfb8aa3b, v47
	v_mov_b32_e32 v243, v242
	v_mov_b32_e32 v245, v244
	v_mov_b32_e32 v250, v251
	ds_read_b128 v[32:35], v236 offset:6912
	ds_read_b128 v[36:39], v236 offset:6976
	s_waitcnt lgkmcnt(0)
	v_mfma_f32_16x16x32_bf16 v[0:3], v[32:35], v[80:83], 0
	v_mfma_f32_16x16x32_bf16 v[4:7], v[32:35], v[88:91], 0
	v_mfma_f32_16x16x32_bf16 v[8:11], v[32:35], v[96:99], 0
	v_mfma_f32_16x16x32_bf16 v[12:15], v[32:35], v[104:107], 0
	v_mfma_f32_16x16x32_bf16 v[16:19], v[32:35], v[112:115], 0
	v_mfma_f32_16x16x32_bf16 v[20:23], v[32:35], v[120:123], 0
	v_mfma_f32_16x16x32_bf16 v[24:27], v[32:35], v[128:131], 0
	v_mfma_f32_16x16x32_bf16 v[28:31], v[32:35], v[136:139], 0
	v_mfma_f32_16x16x32_bf16 v[0:3], v[36:39], v[84:87], v[0:3]
	v_mfma_f32_16x16x32_bf16 v[4:7], v[36:39], v[92:95], v[4:7]
	v_mfma_f32_16x16x32_bf16 v[8:11], v[36:39], v[100:103], v[8:11]
	v_mfma_f32_16x16x32_bf16 v[12:15], v[36:39], v[108:111], v[12:15]
	v_mfma_f32_16x16x32_bf16 v[16:19], v[36:39], v[116:119], v[16:19]
	v_mfma_f32_16x16x32_bf16 v[20:23], v[36:39], v[124:127], v[20:23]
	v_mfma_f32_16x16x32_bf16 v[24:27], v[36:39], v[132:135], v[24:27]
	v_mfma_f32_16x16x32_bf16 v[28:31], v[36:39], v[228:231], v[28:31]
	s_nop 3
	ds_write2_b32 v237, v0, v4 offset0:0 offset1:16
	ds_write2_b32 v237, v8, v12 offset0:32 offset1:48
	ds_write2_b32 v237, v1, v5 offset0:64 offset1:80
	ds_write2_b32 v237, v9, v13 offset0:96 offset1:112
	ds_write2_b32 v237, v2, v6 offset0:128 offset1:144
	ds_write2_b32 v237, v10, v14 offset0:160 offset1:176
	ds_write2_b32 v237, v3, v7 offset0:192 offset1:208
	ds_write2_b32 v237, v11, v15 offset0:224 offset1:240
	ds_write2_b32 v238, v16, v20 offset0:0 offset1:16
	ds_write2_b32 v238, v24, v28 offset0:32 offset1:48
	ds_write2_b32 v238, v17, v21 offset0:64 offset1:80
	ds_write2_b32 v238, v25, v29 offset0:96 offset1:112
	ds_write2_b32 v238, v18, v22 offset0:128 offset1:144
	ds_write2_b32 v238, v26, v30 offset0:160 offset1:176
	ds_write2_b32 v238, v19, v23 offset0:192 offset1:208
	ds_write2_b32 v238, v27, v31 offset0:224 offset1:240
	s_waitcnt lgkmcnt(0)
; #define LAS __attribute__((address_space(3)))
; #define WAVE_SYNC() asm volatile("s_waitcnt lgkmcnt(0)" ::: "memory")
; __device__ __forceinline__ float sigmoid_f(float x) { return rcpf_(1.f + __expf(-x)); }
; template <bool FINAL, int D>
; __device__ __forceinline__ void rg_dir(PREF p, int l, int h, int ch, int sidx, int rowbase  , LAS bf16_t* sXc, LAS float* stg, int lane) {
;     ...
;         if (FINAL && D == 1) {
; #pragma unroll
;             for (int ti = 0; ti < 16; ++ti) { const size_t row = (size_t)(rowbase + mt * 16 + 15 - ti); grv[ti] = __builtin_bit_cast(float, (unsigned)P[row * PW + 512 + ch]); hfv[ti] = __builtin_bit_cast(float, (unsigned)TMP[row * 512 + ch]); }
;             __builtin_amdgcn_sched_barrier(0);
; #pragma unroll
;             for (int ti = 0; ti < 16; ++ti) { grv[ti] = bf2f(__builtin_bit_cast(unsigned, grv[ti])); hfv[ti] = bf2f(__builtin_bit_cast(unsigned, hfv[ti])); }
;         }
;         const bf16x8 A0 = *(const LAS bf16x8*)(sXc + (mt * 16 + (lane & 15)) * 72 + (lane >> 4) * 8), A1 = *(const LAS bf16x8*)(sXc + (mt * 16 + (lane & 15)) * 72 + 32 + (lane >> 4) * 8);
;         f32x4 ar[4], ai[4];
; #pragma unroll
;         for (int nt = 0; nt < 4; ++nt) { const f32x4 z = {0.f, 0.f, 0.f, 0.f};
;             ar[nt] = mfma16(A0, Br[nt][0], z); ar[nt] = mfma16(A1, Br[nt][1], ar[nt]); ai[nt] = mfma16(A0, Bi[nt][0], z); ai[nt] = mfma16(A1, Bi[nt][1], ai[nt]); }
;         WAVE_SYNC();
; #pragma unroll
;         for (int nt = 0; nt < 4; ++nt)
; #pragma unroll
;             for (int j = 0; j < 4; ++j) { const int o = ((lane >> 4) * 4 + j) * 64 + nt * 16 + (lane & 15); stg[o] = ar[nt][j]; stg[1024 + o] = ai[nt][j]; }
;         WAVE_SYNC();
;         float av[16], iv[16];
; #pragma unroll
;         for (int ti = 0; ti < 16; ++ti) { const int tk = D ? 15 - ti : ti;
;             const float zr = stg[tk * 64 + lane] + ba, zi = stg[1024 + tk * 64 + lane] + bi;
;             const float r = sigmoid_f(zr), ig = sigmoid_f(zi);
;             const float a = __builtin_amdgcn_exp2f(r * sp8);
;             const float xc = bf2f(sXc[(mt * 16 + tk) * 72 + lane]);
;             av[ti] = a; iv[ti] = __builtin_amdgcn_sqrtf(fmaxf(1.f - a * a, 0.f)) * ig * xc;
;             if (FINAL && D == 1) grv[ti] = gelu_tanh_f(grv[ti]);
	ds_read2st64_b32 v[0:1], v239 offset0:36 offset1:37
	ds_read2st64_b32 v[2:3], v239 offset0:38 offset1:39
	ds_read2st64_b32 v[4:5], v239 offset0:40 offset1:41
	ds_read2st64_b32 v[6:7], v239 offset0:42 offset1:43
	ds_read2st64_b32 v[8:9], v239 offset0:44 offset1:45
	ds_read2st64_b32 v[10:11], v239 offset0:46 offset1:47
	ds_read2st64_b32 v[12:13], v239 offset0:48 offset1:49
	ds_read2st64_b32 v[14:15], v239 offset0:50 offset1:51
	ds_read2st64_b32 v[16:17], v239 offset0:52 offset1:53
	ds_read2st64_b32 v[18:19], v239 offset0:54 offset1:55
	ds_read2st64_b32 v[20:21], v239 offset0:56 offset1:57
	ds_read2st64_b32 v[22:23], v239 offset0:58 offset1:59
	ds_read2st64_b32 v[24:25], v239 offset0:60 offset1:61
	ds_read2st64_b32 v[26:27], v239 offset0:62 offset1:63
	ds_read2st64_b32 v[28:29], v239 offset0:64 offset1:65
	ds_read2st64_b32 v[30:31], v239 offset0:66 offset1:67
	ds_read_u16 v48, v240 offset:6912
	ds_read_u16 v49, v240 offset:7056
	ds_read_u16 v50, v240 offset:7200
	ds_read_u16 v51, v240 offset:7344
	ds_read_u16 v52, v240 offset:7488
	ds_read_u16 v53, v240 offset:7632
	ds_read_u16 v54, v240 offset:7776
	ds_read_u16 v55, v240 offset:7920
	ds_read_u16 v56, v240 offset:8064
	ds_read_u16 v57, v240 offset:8208
	ds_read_u16 v58, v240 offset:8352
	ds_read_u16 v59, v240 offset:8496
	ds_read_u16 v60, v240 offset:8640
	ds_read_u16 v61, v240 offset:8784
	ds_read_u16 v62, v240 offset:8928
	ds_read_u16 v63, v240 offset:9072
	v_lshlrev_b32_e32 v206, 16, v190
	v_lshlrev_b32_e32 v207, 16, v191
	v_lshlrev_b32_e32 v208, 16, v192
	v_lshlrev_b32_e32 v209, 16, v193
	v_lshlrev_b32_e32 v210, 16, v194
	v_lshlrev_b32_e32 v211, 16, v195
	v_lshlrev_b32_e32 v212, 16, v196
	v_lshlrev_b32_e32 v213, 16, v197
	v_lshlrev_b32_e32 v214, 16, v198
	v_lshlrev_b32_e32 v215, 16, v199
	v_lshlrev_b32_e32 v216, 16, v200
	v_lshlrev_b32_e32 v217, 16, v201
	v_lshlrev_b32_e32 v218, 16, v202
	v_lshlrev_b32_e32 v219, 16, v203
	v_lshlrev_b32_e32 v222, 16, v204
	v_lshlrev_b32_e32 v223, 16, v205
	v_pk_mul_f32 v[32:33], v[140:141], v[206:207]
	v_pk_mul_f32 v[34:35], v[140:141], v[208:209]
	v_pk_mul_f32 v[36:37], v[140:141], v[210:211]
	v_pk_mul_f32 v[38:39], v[140:141], v[212:213]
	v_pk_mul_f32 v[40:41], v[140:141], v[214:215]
	v_pk_mul_f32 v[42:43], v[140:141], v[216:217]
	v_pk_mul_f32 v[44:45], v[140:141], v[218:219]
	v_pk_mul_f32 v[46:47], v[140:141], v[222:223]
	v_pk_mul_f32 v[32:33], v[32:33], v[206:207]
	v_pk_mul_f32 v[34:35], v[34:35], v[208:209]
	v_pk_mul_f32 v[36:37], v[36:37], v[210:211]
	v_pk_mul_f32 v[38:39], v[38:39], v[212:213]
	v_pk_mul_f32 v[40:41], v[40:41], v[214:215]
	v_pk_mul_f32 v[42:43], v[42:43], v[216:217]
	v_pk_mul_f32 v[44:45], v[44:45], v[218:219]
	v_pk_mul_f32 v[46:47], v[46:47], v[222:223]
	v_fma_f32 v32, v32, v206, v206
	v_fma_f32 v33, v33, v207, v207
	v_fma_f32 v34, v34, v208, v208
	v_fma_f32 v35, v35, v209, v209
	v_fma_f32 v36, v36, v210, v210
	v_fma_f32 v37, v37, v211, v211
	v_fma_f32 v38, v38, v212, v212
	v_fma_f32 v39, v39, v213, v213
	v_fma_f32 v40, v40, v214, v214
	v_fma_f32 v41, v41, v215, v215
	v_fma_f32 v42, v42, v216, v216
	v_fma_f32 v43, v43, v217, v217
	v_fma_f32 v44, v44, v218, v218
	v_fma_f32 v45, v45, v219, v219
	v_fma_f32 v46, v46, v222, v222
	v_fma_f32 v47, v47, v223, v223
	s_mov_b32 s98, 0xc0135761
	v_pk_mul_f32 v[32:33], v[32:33], s[98:99] op_sel_hi:[1,0]
	v_pk_mul_f32 v[34:35], v[34:35], s[98:99] op_sel_hi:[1,0]
	v_pk_mul_f32 v[36:37], v[36:37], s[98:99] op_sel_hi:[1,0]
	v_pk_mul_f32 v[38:39], v[38:39], s[98:99] op_sel_hi:[1,0]
	v_pk_mul_f32 v[40:41], v[40:41], s[98:99] op_sel_hi:[1,0]
	v_pk_mul_f32 v[42:43], v[42:43], s[98:99] op_sel_hi:[1,0]
	v_pk_mul_f32 v[44:45], v[44:45], s[98:99] op_sel_hi:[1,0]
	v_pk_mul_f32 v[46:47], v[46:47], s[98:99] op_sel_hi:[1,0]
	v_exp_f32_e32 v32, v32
	v_exp_f32_e32 v33, v33
	v_exp_f32_e32 v34, v34
	v_exp_f32_e32 v35, v35
	v_exp_f32_e32 v36, v36
	v_exp_f32_e32 v37, v37
	v_exp_f32_e32 v38, v38
	v_exp_f32_e32 v39, v39
	v_exp_f32_e32 v40, v40
	v_exp_f32_e32 v41, v41
	v_exp_f32_e32 v42, v42
	v_exp_f32_e32 v43, v43
	v_exp_f32_e32 v44, v44
	v_exp_f32_e32 v45, v45
	v_exp_f32_e32 v46, v46
	v_exp_f32_e32 v47, v47
	v_pk_add_f32 v[32:33], v[32:33], 1.0 op_sel_hi:[1,0]
	v_pk_add_f32 v[34:35], v[34:35], 1.0 op_sel_hi:[1,0]
	v_pk_add_f32 v[36:37], v[36:37], 1.0 op_sel_hi:[1,0]
	v_pk_add_f32 v[38:39], v[38:39], 1.0 op_sel_hi:[1,0]
	v_pk_add_f32 v[40:41], v[40:41], 1.0 op_sel_hi:[1,0]
	v_pk_add_f32 v[42:43], v[42:43], 1.0 op_sel_hi:[1,0]
	v_pk_add_f32 v[44:45], v[44:45], 1.0 op_sel_hi:[1,0]
	v_pk_add_f32 v[46:47], v[46:47], 1.0 op_sel_hi:[1,0]
	v_rcp_f32_e32 v32, v32
	v_rcp_f32_e32 v33, v33
	v_rcp_f32_e32 v34, v34
	v_rcp_f32_e32 v35, v35
	v_rcp_f32_e32 v36, v36
	v_rcp_f32_e32 v37, v37
	v_rcp_f32_e32 v38, v38
	v_rcp_f32_e32 v39, v39
	v_rcp_f32_e32 v40, v40
	v_rcp_f32_e32 v41, v41
	v_rcp_f32_e32 v42, v42
	v_rcp_f32_e32 v43, v43
	v_rcp_f32_e32 v44, v44
	v_rcp_f32_e32 v45, v45
	v_rcp_f32_e32 v46, v46
	v_rcp_f32_e32 v47, v47
	s_nop 0
	v_pk_mul_f32 v[206:207], v[32:33], v[206:207]
	v_pk_mul_f32 v[208:209], v[34:35], v[208:209]
	v_pk_mul_f32 v[210:211], v[36:37], v[210:211]
	v_pk_mul_f32 v[212:213], v[38:39], v[212:213]
	v_pk_mul_f32 v[214:215], v[40:41], v[214:215]
	v_pk_mul_f32 v[216:217], v[42:43], v[216:217]
	v_pk_mul_f32 v[218:219], v[44:45], v[218:219]
	v_pk_mul_f32 v[222:223], v[46:47], v[222:223]
	s_add_i32 s39, s15, 32
	s_mul_hi_u32 s83, s39, 0x1600
	s_mul_i32 s82, s39, 0x1600
	s_add_u32 s82, s82, s0
	s_addc_u32 s83, s83, s1
	s_add_u32 s82, s82, 0xbc00400
	s_addc_u32 s83, s83, 0
	global_load_ushort v190, v234, s[82:83]
	s_add_u32 s82, s82, 0x1600
	s_addc_u32 s83, s83, 0
	global_load_ushort v191, v234, s[82:83]
	s_add_u32 s82, s82, 0x1600
	s_addc_u32 s83, s83, 0
	global_load_ushort v192, v234, s[82:83]
	s_add_u32 s82, s82, 0x1600
	s_addc_u32 s83, s83, 0
	global_load_ushort v193, v234, s[82:83]
	s_add_u32 s82, s82, 0x1600
	s_addc_u32 s83, s83, 0
	global_load_ushort v194, v234, s[82:83]
	s_add_u32 s82, s82, 0x1600
	s_addc_u32 s83, s83, 0
	global_load_ushort v195, v234, s[82:83]
	s_add_u32 s82, s82, 0x1600
	s_addc_u32 s83, s83, 0
	global_load_ushort v196, v234, s[82:83]
	s_add_u32 s82, s82, 0x1600
	s_addc_u32 s83, s83, 0
	global_load_ushort v197, v234, s[82:83]
	s_add_u32 s82, s82, 0x1600
	s_addc_u32 s83, s83, 0
	global_load_ushort v198, v234, s[82:83]
	s_add_u32 s82, s82, 0x1600
	s_addc_u32 s83, s83, 0
	global_load_ushort v199, v234, s[82:83]
	s_add_u32 s82, s82, 0x1600
	s_addc_u32 s83, s83, 0
	global_load_ushort v200, v234, s[82:83]
	s_add_u32 s82, s82, 0x1600
	s_addc_u32 s83, s83, 0
	global_load_ushort v201, v234, s[82:83]
	s_add_u32 s82, s82, 0x1600
	s_addc_u32 s83, s83, 0
	global_load_ushort v202, v234, s[82:83]
	s_add_u32 s82, s82, 0x1600
	s_addc_u32 s83, s83, 0
	global_load_ushort v203, v234, s[82:83]
	s_add_u32 s82, s82, 0x1600
	s_addc_u32 s83, s83, 0
	global_load_ushort v204, v234, s[82:83]
	s_add_u32 s82, s82, 0x1600
	s_addc_u32 s83, s83, 0
	global_load_ushort v205, v234, s[82:83]
	s_waitcnt lgkmcnt(0)
; __device__ __forceinline__ float sigmoid_f(float x) { return rcpf_(1.f + __expf(-x)); }
; template <bool FINAL, int D>
; __device__ __forceinline__ void rg_dir(PREF p, int l, int h, int ch, int sidx, int rowbase  , LAS bf16_t* sXc, LAS float* stg, int lane) {
;     ...
;         for (int ti = 0; ti < 16; ++ti) { const int tk = D ? 15 - ti : ti;
;             const float zr = stg[tk * 64 + lane] + ba, zi = stg[1024 + tk * 64 + lane] + bi;
;             const float r = sigmoid_f(zr), ig = sigmoid_f(zi);
;             const float a = __builtin_amdgcn_exp2f(r * sp8);
;             const float xc = bf2f(sXc[(mt * 16 + tk) * 72 + lane]);
;             av[ti] = a; iv[ti] = __builtin_amdgcn_sqrtf(fmaxf(1.f - a * a, 0.f)) * ig * xc;
	v_pk_fma_f32 v[0:1], v[0:1], v[248:249], v[242:243]
	v_pk_fma_f32 v[2:3], v[2:3], v[248:249], v[242:243]
	v_pk_fma_f32 v[4:5], v[4:5], v[248:249], v[242:243]
	v_pk_fma_f32 v[6:7], v[6:7], v[248:249], v[242:243]
	v_pk_fma_f32 v[8:9], v[8:9], v[248:249], v[242:243]
	v_pk_fma_f32 v[10:11], v[10:11], v[248:249], v[242:243]
	v_pk_fma_f32 v[12:13], v[12:13], v[248:249], v[242:243]
	v_pk_fma_f32 v[14:15], v[14:15], v[248:249], v[242:243]
	v_pk_fma_f32 v[16:17], v[16:17], v[248:249], v[244:245]
	v_pk_fma_f32 v[18:19], v[18:19], v[248:249], v[244:245]
	v_pk_fma_f32 v[20:21], v[20:21], v[248:249], v[244:245]
	v_pk_fma_f32 v[22:23], v[22:23], v[248:249], v[244:245]
	v_pk_fma_f32 v[24:25], v[24:25], v[248:249], v[244:245]
	v_pk_fma_f32 v[26:27], v[26:27], v[248:249], v[244:245]
	v_pk_fma_f32 v[28:29], v[28:29], v[248:249], v[244:245]
	v_pk_fma_f32 v[30:31], v[30:31], v[248:249], v[244:245]
	v_exp_f32_e32 v0, v0
	v_exp_f32_e32 v1, v1
	v_exp_f32_e32 v2, v2
	v_exp_f32_e32 v3, v3
	v_exp_f32_e32 v4, v4
	v_exp_f32_e32 v5, v5
	v_exp_f32_e32 v6, v6
	v_exp_f32_e32 v7, v7
	v_exp_f32_e32 v8, v8
	v_exp_f32_e32 v9, v9
	v_exp_f32_e32 v10, v10
	v_exp_f32_e32 v11, v11
	v_exp_f32_e32 v12, v12
	v_exp_f32_e32 v13, v13
	v_exp_f32_e32 v14, v14
	v_exp_f32_e32 v15, v15
	v_exp_f32_e32 v16, v16
	v_exp_f32_e32 v17, v17
	v_exp_f32_e32 v18, v18
	v_exp_f32_e32 v19, v19
	v_exp_f32_e32 v20, v20
	v_exp_f32_e32 v21, v21
	v_exp_f32_e32 v22, v22
	v_exp_f32_e32 v23, v23
	v_exp_f32_e32 v24, v24
	v_exp_f32_e32 v25, v25
	v_exp_f32_e32 v26, v26
	v_exp_f32_e32 v27, v27
	v_exp_f32_e32 v28, v28
	v_exp_f32_e32 v29, v29
	v_exp_f32_e32 v30, v30
	v_exp_f32_e32 v31, v31
	v_pk_add_f32 v[0:1], v[0:1], 1.0 op_sel_hi:[1,0]
	v_pk_add_f32 v[2:3], v[2:3], 1.0 op_sel_hi:[1,0]
	v_pk_add_f32 v[4:5], v[4:5], 1.0 op_sel_hi:[1,0]
	v_pk_add_f32 v[6:7], v[6:7], 1.0 op_sel_hi:[1,0]
	v_pk_add_f32 v[8:9], v[8:9], 1.0 op_sel_hi:[1,0]
	v_pk_add_f32 v[10:11], v[10:11], 1.0 op_sel_hi:[1,0]
	v_pk_add_f32 v[12:13], v[12:13], 1.0 op_sel_hi:[1,0]
	v_pk_add_f32 v[14:15], v[14:15], 1.0 op_sel_hi:[1,0]
	v_pk_add_f32 v[16:17], v[16:17], 1.0 op_sel_hi:[1,0]
	v_pk_add_f32 v[18:19], v[18:19], 1.0 op_sel_hi:[1,0]
	v_pk_add_f32 v[20:21], v[20:21], 1.0 op_sel_hi:[1,0]
	v_pk_add_f32 v[22:23], v[22:23], 1.0 op_sel_hi:[1,0]
	v_pk_add_f32 v[24:25], v[24:25], 1.0 op_sel_hi:[1,0]
	v_pk_add_f32 v[26:27], v[26:27], 1.0 op_sel_hi:[1,0]
	v_pk_add_f32 v[28:29], v[28:29], 1.0 op_sel_hi:[1,0]
	v_pk_add_f32 v[30:31], v[30:31], 1.0 op_sel_hi:[1,0]
	v_rcp_f32_e32 v0, v0
	v_rcp_f32_e32 v1, v1
	v_rcp_f32_e32 v2, v2
	v_rcp_f32_e32 v3, v3
	v_rcp_f32_e32 v4, v4
	v_rcp_f32_e32 v5, v5
	v_rcp_f32_e32 v6, v6
	v_rcp_f32_e32 v7, v7
	v_rcp_f32_e32 v8, v8
	v_rcp_f32_e32 v9, v9
	v_rcp_f32_e32 v10, v10
	v_rcp_f32_e32 v11, v11
	v_rcp_f32_e32 v12, v12
	v_rcp_f32_e32 v13, v13
	v_rcp_f32_e32 v14, v14
	v_rcp_f32_e32 v15, v15
	v_rcp_f32_e32 v16, v16
	v_rcp_f32_e32 v17, v17
	v_rcp_f32_e32 v18, v18
	v_rcp_f32_e32 v19, v19
	v_rcp_f32_e32 v20, v20
	v_rcp_f32_e32 v21, v21
	v_rcp_f32_e32 v22, v22
	v_rcp_f32_e32 v23, v23
	v_rcp_f32_e32 v24, v24
	v_rcp_f32_e32 v25, v25
	v_rcp_f32_e32 v26, v26
	v_rcp_f32_e32 v27, v27
	v_rcp_f32_e32 v28, v28
	v_rcp_f32_e32 v29, v29
	v_rcp_f32_e32 v30, v30
	v_rcp_f32_e32 v31, v31
	v_pk_mul_f32 v[0:1], v[246:247], v[0:1]
	v_pk_mul_f32 v[2:3], v[246:247], v[2:3]
	v_pk_mul_f32 v[4:5], v[246:247], v[4:5]
	v_pk_mul_f32 v[6:7], v[246:247], v[6:7]
	v_pk_mul_f32 v[8:9], v[246:247], v[8:9]
	v_pk_mul_f32 v[10:11], v[246:247], v[10:11]
	v_pk_mul_f32 v[12:13], v[246:247], v[12:13]
	v_pk_mul_f32 v[14:15], v[246:247], v[14:15]
	v_lshlrev_b32_e32 v48, 16, v48
	v_lshlrev_b32_e32 v49, 16, v49
	v_lshlrev_b32_e32 v50, 16, v50
	v_lshlrev_b32_e32 v51, 16, v51
	v_lshlrev_b32_e32 v52, 16, v52
	v_lshlrev_b32_e32 v53, 16, v53
	v_lshlrev_b32_e32 v54, 16, v54
	v_lshlrev_b32_e32 v55, 16, v55
	v_lshlrev_b32_e32 v56, 16, v56
	v_lshlrev_b32_e32 v57, 16, v57
	v_lshlrev_b32_e32 v58, 16, v58
	v_lshlrev_b32_e32 v59, 16, v59
	v_lshlrev_b32_e32 v60, 16, v60
	v_lshlrev_b32_e32 v61, 16, v61
	v_lshlrev_b32_e32 v62, 16, v62
	v_lshlrev_b32_e32 v63, 16, v63
	v_exp_f32_e32 v0, v0
	v_exp_f32_e32 v1, v1
	v_exp_f32_e32 v2, v2
	v_exp_f32_e32 v3, v3
	v_exp_f32_e32 v4, v4
	v_exp_f32_e32 v5, v5
	v_exp_f32_e32 v6, v6
	v_exp_f32_e32 v7, v7
	v_exp_f32_e32 v8, v8
	v_exp_f32_e32 v9, v9
	v_exp_f32_e32 v10, v10
	v_exp_f32_e32 v11, v11
	v_exp_f32_e32 v12, v12
	v_exp_f32_e32 v13, v13
	v_exp_f32_e32 v14, v14
	v_exp_f32_e32 v15, v15
	v_fma_f32 v32, -v0, v0, 1.0 clamp
	v_fma_f32 v33, -v1, v1, 1.0 clamp
	v_fma_f32 v34, -v2, v2, 1.0 clamp
	v_fma_f32 v35, -v3, v3, 1.0 clamp
	v_fma_f32 v36, -v4, v4, 1.0 clamp
	v_fma_f32 v37, -v5, v5, 1.0 clamp
	v_fma_f32 v38, -v6, v6, 1.0 clamp
	v_fma_f32 v39, -v7, v7, 1.0 clamp
	v_fma_f32 v40, -v8, v8, 1.0 clamp
	v_fma_f32 v41, -v9, v9, 1.0 clamp
	v_fma_f32 v42, -v10, v10, 1.0 clamp
	v_fma_f32 v43, -v11, v11, 1.0 clamp
	v_fma_f32 v44, -v12, v12, 1.0 clamp
	v_fma_f32 v45, -v13, v13, 1.0 clamp
	v_fma_f32 v46, -v14, v14, 1.0 clamp
	v_fma_f32 v47, -v15, v15, 1.0 clamp
	v_sqrt_f32_e32 v32, v32
	v_sqrt_f32_e32 v33, v33
	v_sqrt_f32_e32 v34, v34
	v_sqrt_f32_e32 v35, v35
	v_sqrt_f32_e32 v36, v36
	v_sqrt_f32_e32 v37, v37
	v_sqrt_f32_e32 v38, v38
	v_sqrt_f32_e32 v39, v39
	v_sqrt_f32_e32 v40, v40
	v_sqrt_f32_e32 v41, v41
	v_sqrt_f32_e32 v42, v42
	v_sqrt_f32_e32 v43, v43
	v_sqrt_f32_e32 v44, v44
	v_sqrt_f32_e32 v45, v45
	v_sqrt_f32_e32 v46, v46
	v_sqrt_f32_e32 v47, v47
	s_nop 0
	v_pk_mul_f32 v[16:17], v[16:17], v[32:33]
	v_pk_mul_f32 v[18:19], v[18:19], v[34:35]
	v_pk_mul_f32 v[20:21], v[20:21], v[36:37]
	v_pk_mul_f32 v[22:23], v[22:23], v[38:39]
	v_pk_mul_f32 v[24:25], v[24:25], v[40:41]
; __device__ __forceinline__ unsigned f2bf(float f) { unsigned r; asm("v_cvt_pk_bf16_f32 %0, %1, %1" : "=v"(r) : "v"(f)); return r & 0xffffu; }
; __device__ __forceinline__ float sigmoid_f(float x) { return rcpf_(1.f + __expf(-x)); }
; __device__ __forceinline__ float gelu_tanh_f(float x) { const float y = 0.7978845608028654f * (x + 0.044715f * x * x * x); return x * sigmoid_f(2.f * y); }
; template <bool FINAL, int D>
; __device__ __forceinline__ void rg_dir(PREF p, int l, int h, int ch, int sidx, int rowbase  , LAS bf16_t* sXc, LAS float* stg, int lane) {
;     ...
;         for (int ti = 0; ti < 16; ++ti) { const int tk = D ? 15 - ti : ti;
;             const float zr = stg[tk * 64 + lane] + ba, zi = stg[1024 + tk * 64 + lane] + bi;
;             const float r = sigmoid_f(zr), ig = sigmoid_f(zi);
;             const float a = __builtin_amdgcn_exp2f(r * sp8);
;             const float xc = bf2f(sXc[(mt * 16 + tk) * 72 + lane]);
;             av[ti] = a; iv[ti] = __builtin_amdgcn_sqrtf(fmaxf(1.f - a * a, 0.f)) * ig * xc;
;             if (FINAL && D == 1) grv[ti] = gelu_tanh_f(grv[ti]);
;         }
; #pragma unroll
;         for (int ti = 0; ti < 16; ++ti) { const int tk = D ? 15 - ti : ti;
;             hc = av[ti] * hc + iv[ti]; Ap *= av[ti];
;             if (FINAL) { const size_t row = (size_t)(rowbase + mt * 16 + tk);
;                 if (D == 0) TMP[row * 512 + ch] = (bf16_t)f2bf(hc);
;                 else MIX[row * DM + ch] = (bf16_t)f2bf(grv[ti] * (hfv[ti] + hc)); }
;         }
	v_pk_mul_f32 v[26:27], v[26:27], v[42:43]
	v_pk_mul_f32 v[28:29], v[28:29], v[44:45]
	v_pk_mul_f32 v[30:31], v[30:31], v[46:47]
	v_pk_mul_f32 v[16:17], v[16:17], v[48:49]
	v_pk_mul_f32 v[18:19], v[18:19], v[50:51]
	v_pk_mul_f32 v[20:21], v[20:21], v[52:53]
	v_pk_mul_f32 v[22:23], v[22:23], v[54:55]
	v_pk_mul_f32 v[24:25], v[24:25], v[56:57]
	v_pk_mul_f32 v[26:27], v[26:27], v[58:59]
	v_pk_mul_f32 v[28:29], v[28:29], v[60:61]
	v_pk_mul_f32 v[30:31], v[30:31], v[62:63]
	s_add_i32 s39, s15, 62
	s_lshl_b32 s39, s39, 11
	s_add_u32 s90, s0, 0x7b00000
	s_addc_u32 s91, s1, 0
	s_add_u32 s90, s90, s39
	s_addc_u32 s91, s91, 0
	v_lshlrev_b32_e32 v48, 16, v182
	v_and_b32_e32 v49, 0xffff0000, v182
	v_lshlrev_b32_e32 v50, 16, v183
	v_and_b32_e32 v51, 0xffff0000, v183
	v_lshlrev_b32_e32 v52, 16, v184
	v_and_b32_e32 v53, 0xffff0000, v184
	v_lshlrev_b32_e32 v54, 16, v185
	v_and_b32_e32 v55, 0xffff0000, v185
	v_lshlrev_b32_e32 v56, 16, v186
	v_and_b32_e32 v57, 0xffff0000, v186
	v_lshlrev_b32_e32 v58, 16, v187
	v_and_b32_e32 v59, 0xffff0000, v187
	v_lshlrev_b32_e32 v60, 16, v188
	v_and_b32_e32 v61, 0xffff0000, v188
	v_lshlrev_b32_e32 v62, 16, v189
	v_and_b32_e32 v63, 0xffff0000, v189
	v_fma_f32 v47, v15, v250, v31
	v_fma_f32 v46, v14, v47, v30
	v_fma_f32 v45, v13, v46, v29
	v_fma_f32 v44, v12, v45, v28
	v_fma_f32 v43, v11, v44, v27
	v_fma_f32 v42, v10, v43, v26
	v_fma_f32 v41, v9, v42, v25
	v_fma_f32 v40, v8, v41, v24
	v_fma_f32 v39, v7, v40, v23
	v_fma_f32 v38, v6, v39, v22
	v_fma_f32 v37, v5, v38, v21
	v_fma_f32 v36, v4, v37, v20
	v_fma_f32 v35, v3, v36, v19
	v_fma_f32 v34, v2, v35, v18
	v_fma_f32 v33, v1, v34, v17
	v_fma_f32 v32, v0, v33, v16
	v_mov_b32_e32 v250, v32
	v_pk_add_f32 v[48:49], v[48:49], v[32:33]
	v_pk_add_f32 v[50:51], v[50:51], v[34:35]
	v_pk_add_f32 v[52:53], v[52:53], v[36:37]
	v_pk_add_f32 v[54:55], v[54:55], v[38:39]
	v_pk_add_f32 v[56:57], v[56:57], v[40:41]
	v_pk_add_f32 v[58:59], v[58:59], v[42:43]
	v_pk_add_f32 v[60:61], v[60:61], v[44:45]
	v_pk_add_f32 v[62:63], v[62:63], v[46:47]
	v_pk_mul_f32 v[48:49], v[206:207], v[48:49]
	v_pk_mul_f32 v[50:51], v[208:209], v[50:51]
	v_pk_mul_f32 v[52:53], v[210:211], v[52:53]
	v_pk_mul_f32 v[54:55], v[212:213], v[54:55]
	v_pk_mul_f32 v[56:57], v[214:215], v[56:57]
	v_pk_mul_f32 v[58:59], v[216:217], v[58:59]
	v_pk_mul_f32 v[60:61], v[218:219], v[60:61]
	v_pk_mul_f32 v[62:63], v[222:223], v[62:63]
	v_cvt_pk_bf16_f32 v48, v48, v49
	v_cvt_pk_bf16_f32 v50, v50, v51
	v_cvt_pk_bf16_f32 v52, v52, v53
	v_cvt_pk_bf16_f32 v54, v54, v55
	v_cvt_pk_bf16_f32 v56, v56, v57
	v_cvt_pk_bf16_f32 v58, v58, v59
	v_cvt_pk_bf16_f32 v60, v60, v61
	v_cvt_pk_bf16_f32 v62, v62, v63
	global_store_short_d16_hi v234, v62, s[90:91] offset:2048
	global_store_short v234, v62, s[90:91]
	s_sub_u32 s90, s90, 0x1000
	s_subb_u32 s91, s91, 0
	global_store_short_d16_hi v234, v60, s[90:91] offset:2048
	global_store_short v234, v60, s[90:91]
	s_sub_u32 s90, s90, 0x1000
	s_subb_u32 s91, s91, 0
	global_store_short_d16_hi v234, v58, s[90:91] offset:2048
	global_store_short v234, v58, s[90:91]
	s_sub_u32 s90, s90, 0x1000
	s_subb_u32 s91, s91, 0
	global_store_short_d16_hi v234, v56, s[90:91] offset:2048
	global_store_short v234, v56, s[90:91]
	s_sub_u32 s90, s90, 0x1000
	s_subb_u32 s91, s91, 0
	global_store_short_d16_hi v234, v54, s[90:91] offset:2048
	global_store_short v234, v54, s[90:91]
	s_sub_u32 s90, s90, 0x1000
	s_subb_u32 s91, s91, 0
	global_store_short_d16_hi v234, v52, s[90:91] offset:2048
	global_store_short v234, v52, s[90:91]
	s_sub_u32 s90, s90, 0x1000
	s_subb_u32 s91, s91, 0
	global_store_short_d16_hi v234, v50, s[90:91] offset:2048
	global_store_short v234, v50, s[90:91]
	s_sub_u32 s90, s90, 0x1000
	s_subb_u32 s91, s91, 0
	global_store_short_d16_hi v234, v48, s[90:91] offset:2048
	global_store_short v234, v48, s[90:91]
	ds_read_b128 v[32:35], v236 offset:4608
	ds_read_b128 v[36:39], v236 offset:4672
	s_waitcnt lgkmcnt(0)
	v_mfma_f32_16x16x32_bf16 v[0:3], v[32:35], v[80:83], 0
	v_mfma_f32_16x16x32_bf16 v[4:7], v[32:35], v[88:91], 0
	v_mfma_f32_16x16x32_bf16 v[8:11], v[32:35], v[96:99], 0
	v_mfma_f32_16x16x32_bf16 v[12:15], v[32:35], v[104:107], 0
	v_mfma_f32_16x16x32_bf16 v[16:19], v[32:35], v[112:115], 0
	v_mfma_f32_16x16x32_bf16 v[20:23], v[32:35], v[120:123], 0
	v_mfma_f32_16x16x32_bf16 v[24:27], v[32:35], v[128:131], 0
	v_mfma_f32_16x16x32_bf16 v[28:31], v[32:35], v[136:139], 0
	v_mfma_f32_16x16x32_bf16 v[0:3], v[36:39], v[84:87], v[0:3]
	v_mfma_f32_16x16x32_bf16 v[4:7], v[36:39], v[92:95], v[4:7]
	v_mfma_f32_16x16x32_bf16 v[8:11], v[36:39], v[100:103], v[8:11]
	v_mfma_f32_16x16x32_bf16 v[12:15], v[36:39], v[108:111], v[12:15]
	v_mfma_f32_16x16x32_bf16 v[16:19], v[36:39], v[116:119], v[16:19]
	v_mfma_f32_16x16x32_bf16 v[20:23], v[36:39], v[124:127], v[20:23]
	v_mfma_f32_16x16x32_bf16 v[24:27], v[36:39], v[132:135], v[24:27]
	v_mfma_f32_16x16x32_bf16 v[28:31], v[36:39], v[228:231], v[28:31]
	s_nop 3
	ds_write2_b32 v237, v0, v4 offset0:0 offset1:16
	ds_write2_b32 v237, v8, v12 offset0:32 offset1:48
	ds_write2_b32 v237, v1, v5 offset0:64 offset1:80
	ds_write2_b32 v237, v9, v13 offset0:96 offset1:112
	ds_write2_b32 v237, v2, v6 offset0:128 offset1:144
	ds_write2_b32 v237, v10, v14 offset0:160 offset1:176
	ds_write2_b32 v237, v3, v7 offset0:192 offset1:208
	ds_write2_b32 v237, v11, v15 offset0:224 offset1:240
	ds_write2_b32 v238, v16, v20 offset0:0 offset1:16
	ds_write2_b32 v238, v24, v28 offset0:32 offset1:48
	ds_write2_b32 v238, v17, v21 offset0:64 offset1:80
	ds_write2_b32 v238, v25, v29 offset0:96 offset1:112
	ds_write2_b32 v238, v18, v22 offset0:128 offset1:144
	ds_write2_b32 v238, v26, v30 offset0:160 offset1:176
	ds_write2_b32 v238, v19, v23 offset0:192 offset1:208
	ds_write2_b32 v238, v27, v31 offset0:224 offset1:240
	s_waitcnt lgkmcnt(0)
; #define LAS __attribute__((address_space(3)))
; #define WAVE_SYNC() asm volatile("s_waitcnt lgkmcnt(0)" ::: "memory")
; __device__ __forceinline__ float sigmoid_f(float x) { return rcpf_(1.f + __expf(-x)); }
; template <bool FINAL, int D>
; __device__ __forceinline__ void rg_dir(PREF p, int l, int h, int ch, int sidx, int rowbase  , LAS bf16_t* sXc, LAS float* stg, int lane) {
;     ...
;         if (FINAL && D == 1) {
; #pragma unroll
;             for (int ti = 0; ti < 16; ++ti) { const size_t row = (size_t)(rowbase + mt * 16 + 15 - ti); grv[ti] = __builtin_bit_cast(float, (unsigned)P[row * PW + 512 + ch]); hfv[ti] = __builtin_bit_cast(float, (unsigned)TMP[row * 512 + ch]); }
;             __builtin_amdgcn_sched_barrier(0);
; #pragma unroll
;             for (int ti = 0; ti < 16; ++ti) { grv[ti] = bf2f(__builtin_bit_cast(unsigned, grv[ti])); hfv[ti] = bf2f(__builtin_bit_cast(unsigned, hfv[ti])); }
;         }
;         const bf16x8 A0 = *(const LAS bf16x8*)(sXc + (mt * 16 + (lane & 15)) * 72 + (lane >> 4) * 8), A1 = *(const LAS bf16x8*)(sXc + (mt * 16 + (lane & 15)) * 72 + 32 + (lane >> 4) * 8);
;         f32x4 ar[4], ai[4];
; #pragma unroll
;         for (int nt = 0; nt < 4; ++nt) { const f32x4 z = {0.f, 0.f, 0.f, 0.f};
;             ar[nt] = mfma16(A0, Br[nt][0], z); ar[nt] = mfma16(A1, Br[nt][1], ar[nt]); ai[nt] = mfma16(A0, Bi[nt][0], z); ai[nt] = mfma16(A1, Bi[nt][1], ai[nt]); }
;         WAVE_SYNC();
; #pragma unroll
;         for (int nt = 0; nt < 4; ++nt)
; #pragma unroll
;             for (int j = 0; j < 4; ++j) { const int o = ((lane >> 4) * 4 + j) * 64 + nt * 16 + (lane & 15); stg[o] = ar[nt][j]; stg[1024 + o] = ai[nt][j]; }
;         WAVE_SYNC();
;         float av[16], iv[16];
; #pragma unroll
;         for (int ti = 0; ti < 16; ++ti) { const int tk = D ? 15 - ti : ti;
;             const float zr = stg[tk * 64 + lane] + ba, zi = stg[1024 + tk * 64 + lane] + bi;
;             const float r = sigmoid_f(zr), ig = sigmoid_f(zi);
;             const float a = __builtin_amdgcn_exp2f(r * sp8);
;             const float xc = bf2f(sXc[(mt * 16 + tk) * 72 + lane]);
;             av[ti] = a; iv[ti] = __builtin_amdgcn_sqrtf(fmaxf(1.f - a * a, 0.f)) * ig * xc;
;             if (FINAL && D == 1) grv[ti] = gelu_tanh_f(grv[ti]);
	ds_read2st64_b32 v[0:1], v239 offset0:36 offset1:37
	ds_read2st64_b32 v[2:3], v239 offset0:38 offset1:39
	ds_read2st64_b32 v[4:5], v239 offset0:40 offset1:41
	ds_read2st64_b32 v[6:7], v239 offset0:42 offset1:43
	ds_read2st64_b32 v[8:9], v239 offset0:44 offset1:45
	ds_read2st64_b32 v[10:11], v239 offset0:46 offset1:47
	ds_read2st64_b32 v[12:13], v239 offset0:48 offset1:49
	ds_read2st64_b32 v[14:15], v239 offset0:50 offset1:51
	ds_read2st64_b32 v[16:17], v239 offset0:52 offset1:53
	ds_read2st64_b32 v[18:19], v239 offset0:54 offset1:55
	ds_read2st64_b32 v[20:21], v239 offset0:56 offset1:57
	ds_read2st64_b32 v[22:23], v239 offset0:58 offset1:59
	ds_read2st64_b32 v[24:25], v239 offset0:60 offset1:61
	ds_read2st64_b32 v[26:27], v239 offset0:62 offset1:63
	ds_read2st64_b32 v[28:29], v239 offset0:64 offset1:65
	ds_read2st64_b32 v[30:31], v239 offset0:66 offset1:67
	ds_read_u16 v48, v240 offset:4608
	ds_read_u16 v49, v240 offset:4752
	ds_read_u16 v50, v240 offset:4896
	ds_read_u16 v51, v240 offset:5040
	ds_read_u16 v52, v240 offset:5184
	ds_read_u16 v53, v240 offset:5328
	ds_read_u16 v54, v240 offset:5472
	ds_read_u16 v55, v240 offset:5616
	ds_read_u16 v56, v240 offset:5760
	ds_read_u16 v57, v240 offset:5904
	ds_read_u16 v58, v240 offset:6048
	ds_read_u16 v59, v240 offset:6192
	ds_read_u16 v60, v240 offset:6336
	ds_read_u16 v61, v240 offset:6480
	ds_read_u16 v62, v240 offset:6624
	ds_read_u16 v63, v240 offset:6768
	s_waitcnt vmcnt(16)
	v_lshlrev_b32_e32 v206, 16, v190
	v_lshlrev_b32_e32 v207, 16, v191
	v_lshlrev_b32_e32 v208, 16, v192
	v_lshlrev_b32_e32 v209, 16, v193
	v_lshlrev_b32_e32 v210, 16, v194
	v_lshlrev_b32_e32 v211, 16, v195
	v_lshlrev_b32_e32 v212, 16, v196
	v_lshlrev_b32_e32 v213, 16, v197
	v_lshlrev_b32_e32 v214, 16, v198
	v_lshlrev_b32_e32 v215, 16, v199
	v_lshlrev_b32_e32 v216, 16, v200
	v_lshlrev_b32_e32 v217, 16, v201
	v_lshlrev_b32_e32 v218, 16, v202
	v_lshlrev_b32_e32 v219, 16, v203
	v_lshlrev_b32_e32 v222, 16, v204
	v_lshlrev_b32_e32 v223, 16, v205
	v_pk_mul_f32 v[32:33], v[140:141], v[206:207]
	v_pk_mul_f32 v[34:35], v[140:141], v[208:209]
	v_pk_mul_f32 v[36:37], v[140:141], v[210:211]
	v_pk_mul_f32 v[38:39], v[140:141], v[212:213]
	v_pk_mul_f32 v[40:41], v[140:141], v[214:215]
	v_pk_mul_f32 v[42:43], v[140:141], v[216:217]
	v_pk_mul_f32 v[44:45], v[140:141], v[218:219]
	v_pk_mul_f32 v[46:47], v[140:141], v[222:223]
	v_pk_mul_f32 v[32:33], v[32:33], v[206:207]
	v_pk_mul_f32 v[34:35], v[34:35], v[208:209]
	v_pk_mul_f32 v[36:37], v[36:37], v[210:211]
	v_pk_mul_f32 v[38:39], v[38:39], v[212:213]
	v_pk_mul_f32 v[40:41], v[40:41], v[214:215]
	v_pk_mul_f32 v[42:43], v[42:43], v[216:217]
	v_pk_mul_f32 v[44:45], v[44:45], v[218:219]
	v_pk_mul_f32 v[46:47], v[46:47], v[222:223]
	v_fma_f32 v32, v32, v206, v206
	v_fma_f32 v33, v33, v207, v207
	v_fma_f32 v34, v34, v208, v208
	v_fma_f32 v35, v35, v209, v209
	v_fma_f32 v36, v36, v210, v210
	v_fma_f32 v37, v37, v211, v211
	v_fma_f32 v38, v38, v212, v212
	v_fma_f32 v39, v39, v213, v213
	v_fma_f32 v40, v40, v214, v214
	v_fma_f32 v41, v41, v215, v215
	v_fma_f32 v42, v42, v216, v216
	v_fma_f32 v43, v43, v217, v217
	v_fma_f32 v44, v44, v218, v218
	v_fma_f32 v45, v45, v219, v219
	v_fma_f32 v46, v46, v222, v222
	v_fma_f32 v47, v47, v223, v223
	s_mov_b32 s98, 0xc0135761
	v_pk_mul_f32 v[32:33], v[32:33], s[98:99] op_sel_hi:[1,0]
	v_pk_mul_f32 v[34:35], v[34:35], s[98:99] op_sel_hi:[1,0]
	v_pk_mul_f32 v[36:37], v[36:37], s[98:99] op_sel_hi:[1,0]
	v_pk_mul_f32 v[38:39], v[38:39], s[98:99] op_sel_hi:[1,0]
	v_pk_mul_f32 v[40:41], v[40:41], s[98:99] op_sel_hi:[1,0]
	v_pk_mul_f32 v[42:43], v[42:43], s[98:99] op_sel_hi:[1,0]
	v_pk_mul_f32 v[44:45], v[44:45], s[98:99] op_sel_hi:[1,0]
	v_pk_mul_f32 v[46:47], v[46:47], s[98:99] op_sel_hi:[1,0]
	v_exp_f32_e32 v32, v32
	v_exp_f32_e32 v33, v33
	v_exp_f32_e32 v34, v34
	v_exp_f32_e32 v35, v35
	v_exp_f32_e32 v36, v36
	v_exp_f32_e32 v37, v37
	v_exp_f32_e32 v38, v38
	v_exp_f32_e32 v39, v39
	v_exp_f32_e32 v40, v40
	v_exp_f32_e32 v41, v41
	v_exp_f32_e32 v42, v42
	v_exp_f32_e32 v43, v43
	v_exp_f32_e32 v44, v44
	v_exp_f32_e32 v45, v45
	v_exp_f32_e32 v46, v46
	v_exp_f32_e32 v47, v47
	v_pk_add_f32 v[32:33], v[32:33], 1.0 op_sel_hi:[1,0]
	v_pk_add_f32 v[34:35], v[34:35], 1.0 op_sel_hi:[1,0]
	v_pk_add_f32 v[36:37], v[36:37], 1.0 op_sel_hi:[1,0]
	v_pk_add_f32 v[38:39], v[38:39], 1.0 op_sel_hi:[1,0]
	v_pk_add_f32 v[40:41], v[40:41], 1.0 op_sel_hi:[1,0]
	v_pk_add_f32 v[42:43], v[42:43], 1.0 op_sel_hi:[1,0]
	v_pk_add_f32 v[44:45], v[44:45], 1.0 op_sel_hi:[1,0]
	v_pk_add_f32 v[46:47], v[46:47], 1.0 op_sel_hi:[1,0]
	v_rcp_f32_e32 v32, v32
	v_rcp_f32_e32 v33, v33
	v_rcp_f32_e32 v34, v34
	v_rcp_f32_e32 v35, v35
	v_rcp_f32_e32 v36, v36
	v_rcp_f32_e32 v37, v37
	v_rcp_f32_e32 v38, v38
	v_rcp_f32_e32 v39, v39
	v_rcp_f32_e32 v40, v40
	v_rcp_f32_e32 v41, v41
	v_rcp_f32_e32 v42, v42
	v_rcp_f32_e32 v43, v43
	v_rcp_f32_e32 v44, v44
	v_rcp_f32_e32 v45, v45
	v_rcp_f32_e32 v46, v46
	v_rcp_f32_e32 v47, v47
	s_nop 0
	v_pk_mul_f32 v[206:207], v[32:33], v[206:207]
	v_pk_mul_f32 v[208:209], v[34:35], v[208:209]
	v_pk_mul_f32 v[210:211], v[36:37], v[210:211]
	v_pk_mul_f32 v[212:213], v[38:39], v[212:213]
	v_pk_mul_f32 v[214:215], v[40:41], v[214:215]
	v_pk_mul_f32 v[216:217], v[42:43], v[216:217]
	v_pk_mul_f32 v[218:219], v[44:45], v[218:219]
	v_pk_mul_f32 v[222:223], v[46:47], v[222:223]
	s_add_i32 s39, s15, 16
	s_mul_hi_u32 s83, s39, 0x1600
	s_mul_i32 s82, s39, 0x1600
	s_add_u32 s82, s82, s0
	s_addc_u32 s83, s83, s1
	s_add_u32 s82, s82, 0xbc00400
	s_addc_u32 s83, s83, 0
	global_load_ushort v190, v234, s[82:83]
	s_add_u32 s82, s82, 0x1600
	s_addc_u32 s83, s83, 0
	global_load_ushort v191, v234, s[82:83]
	s_add_u32 s82, s82, 0x1600
	s_addc_u32 s83, s83, 0
	global_load_ushort v192, v234, s[82:83]
	s_add_u32 s82, s82, 0x1600
	s_addc_u32 s83, s83, 0
	global_load_ushort v193, v234, s[82:83]
	s_add_u32 s82, s82, 0x1600
	s_addc_u32 s83, s83, 0
	global_load_ushort v194, v234, s[82:83]
	s_add_u32 s82, s82, 0x1600
	s_addc_u32 s83, s83, 0
	global_load_ushort v195, v234, s[82:83]
	s_add_u32 s82, s82, 0x1600
	s_addc_u32 s83, s83, 0
	global_load_ushort v196, v234, s[82:83]
	s_add_u32 s82, s82, 0x1600
	s_addc_u32 s83, s83, 0
	global_load_ushort v197, v234, s[82:83]
	s_add_u32 s82, s82, 0x1600
	s_addc_u32 s83, s83, 0
	global_load_ushort v198, v234, s[82:83]
	s_add_u32 s82, s82, 0x1600
	s_addc_u32 s83, s83, 0
	global_load_ushort v199, v234, s[82:83]
	s_add_u32 s82, s82, 0x1600
	s_addc_u32 s83, s83, 0
	global_load_ushort v200, v234, s[82:83]
	s_add_u32 s82, s82, 0x1600
	s_addc_u32 s83, s83, 0
	global_load_ushort v201, v234, s[82:83]
	s_add_u32 s82, s82, 0x1600
	s_addc_u32 s83, s83, 0
	global_load_ushort v202, v234, s[82:83]
	s_add_u32 s82, s82, 0x1600
	s_addc_u32 s83, s83, 0
	global_load_ushort v203, v234, s[82:83]
	s_add_u32 s82, s82, 0x1600
	s_addc_u32 s83, s83, 0
	global_load_ushort v204, v234, s[82:83]
	s_add_u32 s82, s82, 0x1600
	s_addc_u32 s83, s83, 0
	global_load_ushort v205, v234, s[82:83]
	s_waitcnt lgkmcnt(0)
; __device__ __forceinline__ float sigmoid_f(float x) { return rcpf_(1.f + __expf(-x)); }
; template <bool FINAL, int D>
; __device__ __forceinline__ void rg_dir(PREF p, int l, int h, int ch, int sidx, int rowbase  , LAS bf16_t* sXc, LAS float* stg, int lane) {
;     ...
;         for (int ti = 0; ti < 16; ++ti) { const int tk = D ? 15 - ti : ti;
;             const float zr = stg[tk * 64 + lane] + ba, zi = stg[1024 + tk * 64 + lane] + bi;
;             const float r = sigmoid_f(zr), ig = sigmoid_f(zi);
;             const float a = __builtin_amdgcn_exp2f(r * sp8);
;             const float xc = bf2f(sXc[(mt * 16 + tk) * 72 + lane]);
;             av[ti] = a; iv[ti] = __builtin_amdgcn_sqrtf(fmaxf(1.f - a * a, 0.f)) * ig * xc;
	v_pk_fma_f32 v[0:1], v[0:1], v[248:249], v[242:243]
	v_pk_fma_f32 v[2:3], v[2:3], v[248:249], v[242:243]
	v_pk_fma_f32 v[4:5], v[4:5], v[248:249], v[242:243]
	v_pk_fma_f32 v[6:7], v[6:7], v[248:249], v[242:243]
	v_pk_fma_f32 v[8:9], v[8:9], v[248:249], v[242:243]
	v_pk_fma_f32 v[10:11], v[10:11], v[248:249], v[242:243]
	v_pk_fma_f32 v[12:13], v[12:13], v[248:249], v[242:243]
	v_pk_fma_f32 v[14:15], v[14:15], v[248:249], v[242:243]
	v_pk_fma_f32 v[16:17], v[16:17], v[248:249], v[244:245]
	v_pk_fma_f32 v[18:19], v[18:19], v[248:249], v[244:245]
	v_pk_fma_f32 v[20:21], v[20:21], v[248:249], v[244:245]
	v_pk_fma_f32 v[22:23], v[22:23], v[248:249], v[244:245]
	v_pk_fma_f32 v[24:25], v[24:25], v[248:249], v[244:245]
	v_pk_fma_f32 v[26:27], v[26:27], v[248:249], v[244:245]
	v_pk_fma_f32 v[28:29], v[28:29], v[248:249], v[244:245]
	v_pk_fma_f32 v[30:31], v[30:31], v[248:249], v[244:245]
	v_exp_f32_e32 v0, v0
	v_exp_f32_e32 v1, v1
	v_exp_f32_e32 v2, v2
	v_exp_f32_e32 v3, v3
	v_exp_f32_e32 v4, v4
	v_exp_f32_e32 v5, v5
	v_exp_f32_e32 v6, v6
	v_exp_f32_e32 v7, v7
	v_exp_f32_e32 v8, v8
	v_exp_f32_e32 v9, v9
	v_exp_f32_e32 v10, v10
	v_exp_f32_e32 v11, v11
	v_exp_f32_e32 v12, v12
	v_exp_f32_e32 v13, v13
	v_exp_f32_e32 v14, v14
	v_exp_f32_e32 v15, v15
	v_exp_f32_e32 v16, v16
	v_exp_f32_e32 v17, v17
	v_exp_f32_e32 v18, v18
	v_exp_f32_e32 v19, v19
	v_exp_f32_e32 v20, v20
	v_exp_f32_e32 v21, v21
	v_exp_f32_e32 v22, v22
	v_exp_f32_e32 v23, v23
	v_exp_f32_e32 v24, v24
	v_exp_f32_e32 v25, v25
	v_exp_f32_e32 v26, v26
	v_exp_f32_e32 v27, v27
	v_exp_f32_e32 v28, v28
	v_exp_f32_e32 v29, v29
	v_exp_f32_e32 v30, v30
	v_exp_f32_e32 v31, v31
	v_pk_add_f32 v[0:1], v[0:1], 1.0 op_sel_hi:[1,0]
	v_pk_add_f32 v[2:3], v[2:3], 1.0 op_sel_hi:[1,0]
	v_pk_add_f32 v[4:5], v[4:5], 1.0 op_sel_hi:[1,0]
	v_pk_add_f32 v[6:7], v[6:7], 1.0 op_sel_hi:[1,0]
	v_pk_add_f32 v[8:9], v[8:9], 1.0 op_sel_hi:[1,0]
	v_pk_add_f32 v[10:11], v[10:11], 1.0 op_sel_hi:[1,0]
	v_pk_add_f32 v[12:13], v[12:13], 1.0 op_sel_hi:[1,0]
	v_pk_add_f32 v[14:15], v[14:15], 1.0 op_sel_hi:[1,0]
	v_pk_add_f32 v[16:17], v[16:17], 1.0 op_sel_hi:[1,0]
	v_pk_add_f32 v[18:19], v[18:19], 1.0 op_sel_hi:[1,0]
	v_pk_add_f32 v[20:21], v[20:21], 1.0 op_sel_hi:[1,0]
	v_pk_add_f32 v[22:23], v[22:23], 1.0 op_sel_hi:[1,0]
	v_pk_add_f32 v[24:25], v[24:25], 1.0 op_sel_hi:[1,0]
	v_pk_add_f32 v[26:27], v[26:27], 1.0 op_sel_hi:[1,0]
	v_pk_add_f32 v[28:29], v[28:29], 1.0 op_sel_hi:[1,0]
	v_pk_add_f32 v[30:31], v[30:31], 1.0 op_sel_hi:[1,0]
	v_rcp_f32_e32 v0, v0
	v_rcp_f32_e32 v1, v1
	v_rcp_f32_e32 v2, v2
	v_rcp_f32_e32 v3, v3
	v_rcp_f32_e32 v4, v4
	v_rcp_f32_e32 v5, v5
	v_rcp_f32_e32 v6, v6
	v_rcp_f32_e32 v7, v7
	v_rcp_f32_e32 v8, v8
	v_rcp_f32_e32 v9, v9
	v_rcp_f32_e32 v10, v10
	v_rcp_f32_e32 v11, v11
	v_rcp_f32_e32 v12, v12
	v_rcp_f32_e32 v13, v13
	v_rcp_f32_e32 v14, v14
	v_rcp_f32_e32 v15, v15
	v_rcp_f32_e32 v16, v16
	v_rcp_f32_e32 v17, v17
	v_rcp_f32_e32 v18, v18
	v_rcp_f32_e32 v19, v19
	v_rcp_f32_e32 v20, v20
	v_rcp_f32_e32 v21, v21
	v_rcp_f32_e32 v22, v22
	v_rcp_f32_e32 v23, v23
	v_rcp_f32_e32 v24, v24
	v_rcp_f32_e32 v25, v25
	v_rcp_f32_e32 v26, v26
	v_rcp_f32_e32 v27, v27
	v_rcp_f32_e32 v28, v28
	v_rcp_f32_e32 v29, v29
	v_rcp_f32_e32 v30, v30
	v_rcp_f32_e32 v31, v31
	v_pk_mul_f32 v[0:1], v[246:247], v[0:1]
	v_pk_mul_f32 v[2:3], v[246:247], v[2:3]
	v_pk_mul_f32 v[4:5], v[246:247], v[4:5]
	v_pk_mul_f32 v[6:7], v[246:247], v[6:7]
	v_pk_mul_f32 v[8:9], v[246:247], v[8:9]
	v_pk_mul_f32 v[10:11], v[246:247], v[10:11]
	v_pk_mul_f32 v[12:13], v[246:247], v[12:13]
	v_pk_mul_f32 v[14:15], v[246:247], v[14:15]
	v_lshlrev_b32_e32 v48, 16, v48
	v_lshlrev_b32_e32 v49, 16, v49
	v_lshlrev_b32_e32 v50, 16, v50
	v_lshlrev_b32_e32 v51, 16, v51
	v_lshlrev_b32_e32 v52, 16, v52
	v_lshlrev_b32_e32 v53, 16, v53
	v_lshlrev_b32_e32 v54, 16, v54
	v_lshlrev_b32_e32 v55, 16, v55
	v_lshlrev_b32_e32 v56, 16, v56
	v_lshlrev_b32_e32 v57, 16, v57
	v_lshlrev_b32_e32 v58, 16, v58
	v_lshlrev_b32_e32 v59, 16, v59
	v_lshlrev_b32_e32 v60, 16, v60
	v_lshlrev_b32_e32 v61, 16, v61
	v_lshlrev_b32_e32 v62, 16, v62
	v_lshlrev_b32_e32 v63, 16, v63
	v_exp_f32_e32 v0, v0
	v_exp_f32_e32 v1, v1
	v_exp_f32_e32 v2, v2
	v_exp_f32_e32 v3, v3
	v_exp_f32_e32 v4, v4
	v_exp_f32_e32 v5, v5
	v_exp_f32_e32 v6, v6
	v_exp_f32_e32 v7, v7
	v_exp_f32_e32 v8, v8
	v_exp_f32_e32 v9, v9
	v_exp_f32_e32 v10, v10
	v_exp_f32_e32 v11, v11
	v_exp_f32_e32 v12, v12
	v_exp_f32_e32 v13, v13
	v_exp_f32_e32 v14, v14
	v_exp_f32_e32 v15, v15
	v_fma_f32 v32, -v0, v0, 1.0 clamp
	v_fma_f32 v33, -v1, v1, 1.0 clamp
	v_fma_f32 v34, -v2, v2, 1.0 clamp
	v_fma_f32 v35, -v3, v3, 1.0 clamp
	v_fma_f32 v36, -v4, v4, 1.0 clamp
	v_fma_f32 v37, -v5, v5, 1.0 clamp
	v_fma_f32 v38, -v6, v6, 1.0 clamp
	v_fma_f32 v39, -v7, v7, 1.0 clamp
	v_fma_f32 v40, -v8, v8, 1.0 clamp
	v_fma_f32 v41, -v9, v9, 1.0 clamp
	v_fma_f32 v42, -v10, v10, 1.0 clamp
	v_fma_f32 v43, -v11, v11, 1.0 clamp
	v_fma_f32 v44, -v12, v12, 1.0 clamp
	v_fma_f32 v45, -v13, v13, 1.0 clamp
	v_fma_f32 v46, -v14, v14, 1.0 clamp
	v_fma_f32 v47, -v15, v15, 1.0 clamp
	v_sqrt_f32_e32 v32, v32
	v_sqrt_f32_e32 v33, v33
	v_sqrt_f32_e32 v34, v34
	v_sqrt_f32_e32 v35, v35
	v_sqrt_f32_e32 v36, v36
	v_sqrt_f32_e32 v37, v37
	v_sqrt_f32_e32 v38, v38
	v_sqrt_f32_e32 v39, v39
	v_sqrt_f32_e32 v40, v40
	v_sqrt_f32_e32 v41, v41
	v_sqrt_f32_e32 v42, v42
	v_sqrt_f32_e32 v43, v43
	v_sqrt_f32_e32 v44, v44
	v_sqrt_f32_e32 v45, v45
	v_sqrt_f32_e32 v46, v46
	v_sqrt_f32_e32 v47, v47
	s_nop 0
	v_pk_mul_f32 v[16:17], v[16:17], v[32:33]
	v_pk_mul_f32 v[18:19], v[18:19], v[34:35]
	v_pk_mul_f32 v[20:21], v[20:21], v[36:37]
	v_pk_mul_f32 v[22:23], v[22:23], v[38:39]
	v_pk_mul_f32 v[24:25], v[24:25], v[40:41]
; __device__ __forceinline__ unsigned f2bf(float f) { unsigned r; asm("v_cvt_pk_bf16_f32 %0, %1, %1" : "=v"(r) : "v"(f)); return r & 0xffffu; }
; __device__ __forceinline__ float sigmoid_f(float x) { return rcpf_(1.f + __expf(-x)); }
; __device__ __forceinline__ float gelu_tanh_f(float x) { const float y = 0.7978845608028654f * (x + 0.044715f * x * x * x); return x * sigmoid_f(2.f * y); }
; template <bool FINAL, int D>
; __device__ __forceinline__ void rg_dir(PREF p, int l, int h, int ch, int sidx, int rowbase  , LAS bf16_t* sXc, LAS float* stg, int lane) {
;     ...
;         for (int ti = 0; ti < 16; ++ti) { const int tk = D ? 15 - ti : ti;
;             const float zr = stg[tk * 64 + lane] + ba, zi = stg[1024 + tk * 64 + lane] + bi;
;             const float r = sigmoid_f(zr), ig = sigmoid_f(zi);
;             const float a = __builtin_amdgcn_exp2f(r * sp8);
;             const float xc = bf2f(sXc[(mt * 16 + tk) * 72 + lane]);
;             av[ti] = a; iv[ti] = __builtin_amdgcn_sqrtf(fmaxf(1.f - a * a, 0.f)) * ig * xc;
;             if (FINAL && D == 1) grv[ti] = gelu_tanh_f(grv[ti]);
;         }
; #pragma unroll
;         for (int ti = 0; ti < 16; ++ti) { const int tk = D ? 15 - ti : ti;
;             hc = av[ti] * hc + iv[ti]; Ap *= av[ti];
;             if (FINAL) { const size_t row = (size_t)(rowbase + mt * 16 + tk);
;                 if (D == 0) TMP[row * 512 + ch] = (bf16_t)f2bf(hc);
;                 else MIX[row * DM + ch] = (bf16_t)f2bf(grv[ti] * (hfv[ti] + hc)); }
;         }
	v_pk_mul_f32 v[26:27], v[26:27], v[42:43]
	v_pk_mul_f32 v[28:29], v[28:29], v[44:45]
	v_pk_mul_f32 v[30:31], v[30:31], v[46:47]
	v_pk_mul_f32 v[16:17], v[16:17], v[48:49]
	v_pk_mul_f32 v[18:19], v[18:19], v[50:51]
	v_pk_mul_f32 v[20:21], v[20:21], v[52:53]
	v_pk_mul_f32 v[22:23], v[22:23], v[54:55]
	v_pk_mul_f32 v[24:25], v[24:25], v[56:57]
	v_pk_mul_f32 v[26:27], v[26:27], v[58:59]
	v_pk_mul_f32 v[28:29], v[28:29], v[60:61]
	v_pk_mul_f32 v[30:31], v[30:31], v[62:63]
	s_add_i32 s39, s15, 46
	s_lshl_b32 s39, s39, 11
	s_add_u32 s90, s0, 0x7b00000
	s_addc_u32 s91, s1, 0
	s_add_u32 s90, s90, s39
	s_addc_u32 s91, s91, 0
	v_lshlrev_b32_e32 v48, 16, v174
	v_and_b32_e32 v49, 0xffff0000, v174
	v_lshlrev_b32_e32 v50, 16, v175
	v_and_b32_e32 v51, 0xffff0000, v175
	v_lshlrev_b32_e32 v52, 16, v176
	v_and_b32_e32 v53, 0xffff0000, v176
	v_lshlrev_b32_e32 v54, 16, v177
	v_and_b32_e32 v55, 0xffff0000, v177
	v_lshlrev_b32_e32 v56, 16, v178
	v_and_b32_e32 v57, 0xffff0000, v178
	v_lshlrev_b32_e32 v58, 16, v179
	v_and_b32_e32 v59, 0xffff0000, v179
	v_lshlrev_b32_e32 v60, 16, v180
	v_and_b32_e32 v61, 0xffff0000, v180
	v_lshlrev_b32_e32 v62, 16, v181
	v_and_b32_e32 v63, 0xffff0000, v181
	v_fma_f32 v47, v15, v250, v31
	v_fma_f32 v46, v14, v47, v30
	v_fma_f32 v45, v13, v46, v29
	v_fma_f32 v44, v12, v45, v28
	v_fma_f32 v43, v11, v44, v27
	v_fma_f32 v42, v10, v43, v26
	v_fma_f32 v41, v9, v42, v25
	v_fma_f32 v40, v8, v41, v24
	v_fma_f32 v39, v7, v40, v23
	v_fma_f32 v38, v6, v39, v22
	v_fma_f32 v37, v5, v38, v21
	v_fma_f32 v36, v4, v37, v20
	v_fma_f32 v35, v3, v36, v19
	v_fma_f32 v34, v2, v35, v18
	v_fma_f32 v33, v1, v34, v17
	v_fma_f32 v32, v0, v33, v16
	v_mov_b32_e32 v250, v32
	v_pk_add_f32 v[48:49], v[48:49], v[32:33]
	v_pk_add_f32 v[50:51], v[50:51], v[34:35]
	v_pk_add_f32 v[52:53], v[52:53], v[36:37]
	v_pk_add_f32 v[54:55], v[54:55], v[38:39]
	v_pk_add_f32 v[56:57], v[56:57], v[40:41]
	v_pk_add_f32 v[58:59], v[58:59], v[42:43]
	v_pk_add_f32 v[60:61], v[60:61], v[44:45]
	v_pk_add_f32 v[62:63], v[62:63], v[46:47]
	v_pk_mul_f32 v[48:49], v[206:207], v[48:49]
	v_pk_mul_f32 v[50:51], v[208:209], v[50:51]
	v_pk_mul_f32 v[52:53], v[210:211], v[52:53]
	v_pk_mul_f32 v[54:55], v[212:213], v[54:55]
	v_pk_mul_f32 v[56:57], v[214:215], v[56:57]
	v_pk_mul_f32 v[58:59], v[216:217], v[58:59]
	v_pk_mul_f32 v[60:61], v[218:219], v[60:61]
	v_pk_mul_f32 v[62:63], v[222:223], v[62:63]
	v_cvt_pk_bf16_f32 v48, v48, v49
	v_cvt_pk_bf16_f32 v50, v50, v51
	v_cvt_pk_bf16_f32 v52, v52, v53
	v_cvt_pk_bf16_f32 v54, v54, v55
	v_cvt_pk_bf16_f32 v56, v56, v57
	v_cvt_pk_bf16_f32 v58, v58, v59
	v_cvt_pk_bf16_f32 v60, v60, v61
	v_cvt_pk_bf16_f32 v62, v62, v63
	global_store_short_d16_hi v234, v62, s[90:91] offset:2048
	global_store_short v234, v62, s[90:91]
	s_sub_u32 s90, s90, 0x1000
	s_subb_u32 s91, s91, 0
	global_store_short_d16_hi v234, v60, s[90:91] offset:2048
	global_store_short v234, v60, s[90:91]
	s_sub_u32 s90, s90, 0x1000
	s_subb_u32 s91, s91, 0
	global_store_short_d16_hi v234, v58, s[90:91] offset:2048
	global_store_short v234, v58, s[90:91]
	s_sub_u32 s90, s90, 0x1000
	s_subb_u32 s91, s91, 0
	global_store_short_d16_hi v234, v56, s[90:91] offset:2048
	global_store_short v234, v56, s[90:91]
	s_sub_u32 s90, s90, 0x1000
	s_subb_u32 s91, s91, 0
	global_store_short_d16_hi v234, v54, s[90:91] offset:2048
	global_store_short v234, v54, s[90:91]
	s_sub_u32 s90, s90, 0x1000
	s_subb_u32 s91, s91, 0
	global_store_short_d16_hi v234, v52, s[90:91] offset:2048
	global_store_short v234, v52, s[90:91]
	s_sub_u32 s90, s90, 0x1000
	s_subb_u32 s91, s91, 0
	global_store_short_d16_hi v234, v50, s[90:91] offset:2048
	global_store_short v234, v50, s[90:91]
	s_sub_u32 s90, s90, 0x1000
	s_subb_u32 s91, s91, 0
	global_store_short_d16_hi v234, v48, s[90:91] offset:2048
	global_store_short v234, v48, s[90:91]
	ds_read_b128 v[32:35], v236 offset:2304
	ds_read_b128 v[36:39], v236 offset:2368
	s_waitcnt lgkmcnt(0)
	v_mfma_f32_16x16x32_bf16 v[0:3], v[32:35], v[80:83], 0
	v_mfma_f32_16x16x32_bf16 v[4:7], v[32:35], v[88:91], 0
	v_mfma_f32_16x16x32_bf16 v[8:11], v[32:35], v[96:99], 0
	v_mfma_f32_16x16x32_bf16 v[12:15], v[32:35], v[104:107], 0
	v_mfma_f32_16x16x32_bf16 v[16:19], v[32:35], v[112:115], 0
	v_mfma_f32_16x16x32_bf16 v[20:23], v[32:35], v[120:123], 0
	v_mfma_f32_16x16x32_bf16 v[24:27], v[32:35], v[128:131], 0
	v_mfma_f32_16x16x32_bf16 v[28:31], v[32:35], v[136:139], 0
	v_mfma_f32_16x16x32_bf16 v[0:3], v[36:39], v[84:87], v[0:3]
	v_mfma_f32_16x16x32_bf16 v[4:7], v[36:39], v[92:95], v[4:7]
	v_mfma_f32_16x16x32_bf16 v[8:11], v[36:39], v[100:103], v[8:11]
	v_mfma_f32_16x16x32_bf16 v[12:15], v[36:39], v[108:111], v[12:15]
	v_mfma_f32_16x16x32_bf16 v[16:19], v[36:39], v[116:119], v[16:19]
	v_mfma_f32_16x16x32_bf16 v[20:23], v[36:39], v[124:127], v[20:23]
	v_mfma_f32_16x16x32_bf16 v[24:27], v[36:39], v[132:135], v[24:27]
	v_mfma_f32_16x16x32_bf16 v[28:31], v[36:39], v[228:231], v[28:31]
	s_nop 3
	ds_write2_b32 v237, v0, v4 offset0:0 offset1:16
	ds_write2_b32 v237, v8, v12 offset0:32 offset1:48
	ds_write2_b32 v237, v1, v5 offset0:64 offset1:80
	ds_write2_b32 v237, v9, v13 offset0:96 offset1:112
	ds_write2_b32 v237, v2, v6 offset0:128 offset1:144
	ds_write2_b32 v237, v10, v14 offset0:160 offset1:176
	ds_write2_b32 v237, v3, v7 offset0:192 offset1:208
	ds_write2_b32 v237, v11, v15 offset0:224 offset1:240
	ds_write2_b32 v238, v16, v20 offset0:0 offset1:16
	ds_write2_b32 v238, v24, v28 offset0:32 offset1:48
	ds_write2_b32 v238, v17, v21 offset0:64 offset1:80
	ds_write2_b32 v238, v25, v29 offset0:96 offset1:112
	ds_write2_b32 v238, v18, v22 offset0:128 offset1:144
	ds_write2_b32 v238, v26, v30 offset0:160 offset1:176
	ds_write2_b32 v238, v19, v23 offset0:192 offset1:208
	ds_write2_b32 v238, v27, v31 offset0:224 offset1:240
	s_waitcnt lgkmcnt(0)
; #define LAS __attribute__((address_space(3)))
; #define WAVE_SYNC() asm volatile("s_waitcnt lgkmcnt(0)" ::: "memory")
; __device__ __forceinline__ float sigmoid_f(float x) { return rcpf_(1.f + __expf(-x)); }
; template <bool FINAL, int D>
; __device__ __forceinline__ void rg_dir(PREF p, int l, int h, int ch, int sidx, int rowbase  , LAS bf16_t* sXc, LAS float* stg, int lane) {
;     ...
;         if (FINAL && D == 1) {
; #pragma unroll
;             for (int ti = 0; ti < 16; ++ti) { const size_t row = (size_t)(rowbase + mt * 16 + 15 - ti); grv[ti] = __builtin_bit_cast(float, (unsigned)P[row * PW + 512 + ch]); hfv[ti] = __builtin_bit_cast(float, (unsigned)TMP[row * 512 + ch]); }
;             __builtin_amdgcn_sched_barrier(0);
; #pragma unroll
;             for (int ti = 0; ti < 16; ++ti) { grv[ti] = bf2f(__builtin_bit_cast(unsigned, grv[ti])); hfv[ti] = bf2f(__builtin_bit_cast(unsigned, hfv[ti])); }
;         }
;         const bf16x8 A0 = *(const LAS bf16x8*)(sXc + (mt * 16 + (lane & 15)) * 72 + (lane >> 4) * 8), A1 = *(const LAS bf16x8*)(sXc + (mt * 16 + (lane & 15)) * 72 + 32 + (lane >> 4) * 8);
;         f32x4 ar[4], ai[4];
; #pragma unroll
;         for (int nt = 0; nt < 4; ++nt) { const f32x4 z = {0.f, 0.f, 0.f, 0.f};
;             ar[nt] = mfma16(A0, Br[nt][0], z); ar[nt] = mfma16(A1, Br[nt][1], ar[nt]); ai[nt] = mfma16(A0, Bi[nt][0], z); ai[nt] = mfma16(A1, Bi[nt][1], ai[nt]); }
;         WAVE_SYNC();
; #pragma unroll
;         for (int nt = 0; nt < 4; ++nt)
; #pragma unroll
;             for (int j = 0; j < 4; ++j) { const int o = ((lane >> 4) * 4 + j) * 64 + nt * 16 + (lane & 15); stg[o] = ar[nt][j]; stg[1024 + o] = ai[nt][j]; }
;         WAVE_SYNC();
;         float av[16], iv[16];
; #pragma unroll
;         for (int ti = 0; ti < 16; ++ti) { const int tk = D ? 15 - ti : ti;
;             const float zr = stg[tk * 64 + lane] + ba, zi = stg[1024 + tk * 64 + lane] + bi;
;             const float r = sigmoid_f(zr), ig = sigmoid_f(zi);
;             const float a = __builtin_amdgcn_exp2f(r * sp8);
;             const float xc = bf2f(sXc[(mt * 16 + tk) * 72 + lane]);
;             av[ti] = a; iv[ti] = __builtin_amdgcn_sqrtf(fmaxf(1.f - a * a, 0.f)) * ig * xc;
;             if (FINAL && D == 1) grv[ti] = gelu_tanh_f(grv[ti]);
	ds_read2st64_b32 v[0:1], v239 offset0:36 offset1:37
	ds_read2st64_b32 v[2:3], v239 offset0:38 offset1:39
	ds_read2st64_b32 v[4:5], v239 offset0:40 offset1:41
	ds_read2st64_b32 v[6:7], v239 offset0:42 offset1:43
	ds_read2st64_b32 v[8:9], v239 offset0:44 offset1:45
	ds_read2st64_b32 v[10:11], v239 offset0:46 offset1:47
	ds_read2st64_b32 v[12:13], v239 offset0:48 offset1:49
	ds_read2st64_b32 v[14:15], v239 offset0:50 offset1:51
	ds_read2st64_b32 v[16:17], v239 offset0:52 offset1:53
	ds_read2st64_b32 v[18:19], v239 offset0:54 offset1:55
	ds_read2st64_b32 v[20:21], v239 offset0:56 offset1:57
	ds_read2st64_b32 v[22:23], v239 offset0:58 offset1:59
	ds_read2st64_b32 v[24:25], v239 offset0:60 offset1:61
	ds_read2st64_b32 v[26:27], v239 offset0:62 offset1:63
	ds_read2st64_b32 v[28:29], v239 offset0:64 offset1:65
	ds_read2st64_b32 v[30:31], v239 offset0:66 offset1:67
	ds_read_u16 v48, v240 offset:2304
	ds_read_u16 v49, v240 offset:2448
	ds_read_u16 v50, v240 offset:2592
	ds_read_u16 v51, v240 offset:2736
	ds_read_u16 v52, v240 offset:2880
	ds_read_u16 v53, v240 offset:3024
	ds_read_u16 v54, v240 offset:3168
	ds_read_u16 v55, v240 offset:3312
	ds_read_u16 v56, v240 offset:3456
	ds_read_u16 v57, v240 offset:3600
	ds_read_u16 v58, v240 offset:3744
	ds_read_u16 v59, v240 offset:3888
	ds_read_u16 v60, v240 offset:4032
	ds_read_u16 v61, v240 offset:4176
	ds_read_u16 v62, v240 offset:4320
	ds_read_u16 v63, v240 offset:4464
	s_waitcnt vmcnt(16)
	v_lshlrev_b32_e32 v206, 16, v190
	v_lshlrev_b32_e32 v207, 16, v191
	v_lshlrev_b32_e32 v208, 16, v192
	v_lshlrev_b32_e32 v209, 16, v193
	v_lshlrev_b32_e32 v210, 16, v194
	v_lshlrev_b32_e32 v211, 16, v195
	v_lshlrev_b32_e32 v212, 16, v196
	v_lshlrev_b32_e32 v213, 16, v197
	v_lshlrev_b32_e32 v214, 16, v198
	v_lshlrev_b32_e32 v215, 16, v199
	v_lshlrev_b32_e32 v216, 16, v200
	v_lshlrev_b32_e32 v217, 16, v201
	v_lshlrev_b32_e32 v218, 16, v202
	v_lshlrev_b32_e32 v219, 16, v203
	v_lshlrev_b32_e32 v222, 16, v204
	v_lshlrev_b32_e32 v223, 16, v205
	v_pk_mul_f32 v[32:33], v[140:141], v[206:207]
	v_pk_mul_f32 v[34:35], v[140:141], v[208:209]
	v_pk_mul_f32 v[36:37], v[140:141], v[210:211]
	v_pk_mul_f32 v[38:39], v[140:141], v[212:213]
	v_pk_mul_f32 v[40:41], v[140:141], v[214:215]
	v_pk_mul_f32 v[42:43], v[140:141], v[216:217]
	v_pk_mul_f32 v[44:45], v[140:141], v[218:219]
	v_pk_mul_f32 v[46:47], v[140:141], v[222:223]
	v_pk_mul_f32 v[32:33], v[32:33], v[206:207]
	v_pk_mul_f32 v[34:35], v[34:35], v[208:209]
	v_pk_mul_f32 v[36:37], v[36:37], v[210:211]
	v_pk_mul_f32 v[38:39], v[38:39], v[212:213]
	v_pk_mul_f32 v[40:41], v[40:41], v[214:215]
	v_pk_mul_f32 v[42:43], v[42:43], v[216:217]
	v_pk_mul_f32 v[44:45], v[44:45], v[218:219]
	v_pk_mul_f32 v[46:47], v[46:47], v[222:223]
	v_fma_f32 v32, v32, v206, v206
	v_fma_f32 v33, v33, v207, v207
	v_fma_f32 v34, v34, v208, v208
	v_fma_f32 v35, v35, v209, v209
	v_fma_f32 v36, v36, v210, v210
	v_fma_f32 v37, v37, v211, v211
	v_fma_f32 v38, v38, v212, v212
	v_fma_f32 v39, v39, v213, v213
	v_fma_f32 v40, v40, v214, v214
	v_fma_f32 v41, v41, v215, v215
	v_fma_f32 v42, v42, v216, v216
	v_fma_f32 v43, v43, v217, v217
	v_fma_f32 v44, v44, v218, v218
	v_fma_f32 v45, v45, v219, v219
	v_fma_f32 v46, v46, v222, v222
	v_fma_f32 v47, v47, v223, v223
	s_mov_b32 s98, 0xc0135761
	v_pk_mul_f32 v[32:33], v[32:33], s[98:99] op_sel_hi:[1,0]
	v_pk_mul_f32 v[34:35], v[34:35], s[98:99] op_sel_hi:[1,0]
	v_pk_mul_f32 v[36:37], v[36:37], s[98:99] op_sel_hi:[1,0]
	v_pk_mul_f32 v[38:39], v[38:39], s[98:99] op_sel_hi:[1,0]
	v_pk_mul_f32 v[40:41], v[40:41], s[98:99] op_sel_hi:[1,0]
	v_pk_mul_f32 v[42:43], v[42:43], s[98:99] op_sel_hi:[1,0]
	v_pk_mul_f32 v[44:45], v[44:45], s[98:99] op_sel_hi:[1,0]
	v_pk_mul_f32 v[46:47], v[46:47], s[98:99] op_sel_hi:[1,0]
	v_exp_f32_e32 v32, v32
	v_exp_f32_e32 v33, v33
	v_exp_f32_e32 v34, v34
	v_exp_f32_e32 v35, v35
	v_exp_f32_e32 v36, v36
	v_exp_f32_e32 v37, v37
	v_exp_f32_e32 v38, v38
	v_exp_f32_e32 v39, v39
	v_exp_f32_e32 v40, v40
	v_exp_f32_e32 v41, v41
	v_exp_f32_e32 v42, v42
	v_exp_f32_e32 v43, v43
	v_exp_f32_e32 v44, v44
	v_exp_f32_e32 v45, v45
	v_exp_f32_e32 v46, v46
	v_exp_f32_e32 v47, v47
	v_pk_add_f32 v[32:33], v[32:33], 1.0 op_sel_hi:[1,0]
	v_pk_add_f32 v[34:35], v[34:35], 1.0 op_sel_hi:[1,0]
	v_pk_add_f32 v[36:37], v[36:37], 1.0 op_sel_hi:[1,0]
	v_pk_add_f32 v[38:39], v[38:39], 1.0 op_sel_hi:[1,0]
	v_pk_add_f32 v[40:41], v[40:41], 1.0 op_sel_hi:[1,0]
	v_pk_add_f32 v[42:43], v[42:43], 1.0 op_sel_hi:[1,0]
	v_pk_add_f32 v[44:45], v[44:45], 1.0 op_sel_hi:[1,0]
	v_pk_add_f32 v[46:47], v[46:47], 1.0 op_sel_hi:[1,0]
	v_rcp_f32_e32 v32, v32
	v_rcp_f32_e32 v33, v33
	v_rcp_f32_e32 v34, v34
	v_rcp_f32_e32 v35, v35
	v_rcp_f32_e32 v36, v36
	v_rcp_f32_e32 v37, v37
	v_rcp_f32_e32 v38, v38
	v_rcp_f32_e32 v39, v39
	v_rcp_f32_e32 v40, v40
	v_rcp_f32_e32 v41, v41
	v_rcp_f32_e32 v42, v42
	v_rcp_f32_e32 v43, v43
	v_rcp_f32_e32 v44, v44
	v_rcp_f32_e32 v45, v45
	v_rcp_f32_e32 v46, v46
	v_rcp_f32_e32 v47, v47
	s_nop 0
	v_pk_mul_f32 v[206:207], v[32:33], v[206:207]
	v_pk_mul_f32 v[208:209], v[34:35], v[208:209]
	v_pk_mul_f32 v[210:211], v[36:37], v[210:211]
	v_pk_mul_f32 v[212:213], v[38:39], v[212:213]
	v_pk_mul_f32 v[214:215], v[40:41], v[214:215]
	v_pk_mul_f32 v[216:217], v[42:43], v[216:217]
	v_pk_mul_f32 v[218:219], v[44:45], v[218:219]
	v_pk_mul_f32 v[222:223], v[46:47], v[222:223]
	s_add_i32 s39, s15, 0
	s_mul_hi_u32 s83, s39, 0x1600
	s_mul_i32 s82, s39, 0x1600
	s_add_u32 s82, s82, s0
	s_addc_u32 s83, s83, s1
	s_add_u32 s82, s82, 0xbc00400
	s_addc_u32 s83, s83, 0
	global_load_ushort v190, v234, s[82:83]
	s_add_u32 s82, s82, 0x1600
	s_addc_u32 s83, s83, 0
	global_load_ushort v191, v234, s[82:83]
	s_add_u32 s82, s82, 0x1600
	s_addc_u32 s83, s83, 0
	global_load_ushort v192, v234, s[82:83]
	s_add_u32 s82, s82, 0x1600
	s_addc_u32 s83, s83, 0
	global_load_ushort v193, v234, s[82:83]
	s_add_u32 s82, s82, 0x1600
	s_addc_u32 s83, s83, 0
	global_load_ushort v194, v234, s[82:83]
	s_add_u32 s82, s82, 0x1600
	s_addc_u32 s83, s83, 0
	global_load_ushort v195, v234, s[82:83]
	s_add_u32 s82, s82, 0x1600
	s_addc_u32 s83, s83, 0
	global_load_ushort v196, v234, s[82:83]
	s_add_u32 s82, s82, 0x1600
	s_addc_u32 s83, s83, 0
	global_load_ushort v197, v234, s[82:83]
	s_add_u32 s82, s82, 0x1600
	s_addc_u32 s83, s83, 0
	global_load_ushort v198, v234, s[82:83]
	s_add_u32 s82, s82, 0x1600
	s_addc_u32 s83, s83, 0
	global_load_ushort v199, v234, s[82:83]
	s_add_u32 s82, s82, 0x1600
	s_addc_u32 s83, s83, 0
	global_load_ushort v200, v234, s[82:83]
	s_add_u32 s82, s82, 0x1600
	s_addc_u32 s83, s83, 0
	global_load_ushort v201, v234, s[82:83]
	s_add_u32 s82, s82, 0x1600
	s_addc_u32 s83, s83, 0
	global_load_ushort v202, v234, s[82:83]
	s_add_u32 s82, s82, 0x1600
	s_addc_u32 s83, s83, 0
	global_load_ushort v203, v234, s[82:83]
	s_add_u32 s82, s82, 0x1600
	s_addc_u32 s83, s83, 0
	global_load_ushort v204, v234, s[82:83]
	s_add_u32 s82, s82, 0x1600
	s_addc_u32 s83, s83, 0
	global_load_ushort v205, v234, s[82:83]
	s_waitcnt lgkmcnt(0)
; __device__ __forceinline__ float sigmoid_f(float x) { return rcpf_(1.f + __expf(-x)); }
; template <bool FINAL, int D>
; __device__ __forceinline__ void rg_dir(PREF p, int l, int h, int ch, int sidx, int rowbase  , LAS bf16_t* sXc, LAS float* stg, int lane) {
;     ...
;         for (int ti = 0; ti < 16; ++ti) { const int tk = D ? 15 - ti : ti;
;             const float zr = stg[tk * 64 + lane] + ba, zi = stg[1024 + tk * 64 + lane] + bi;
;             const float r = sigmoid_f(zr), ig = sigmoid_f(zi);
;             const float a = __builtin_amdgcn_exp2f(r * sp8);
;             const float xc = bf2f(sXc[(mt * 16 + tk) * 72 + lane]);
;             av[ti] = a; iv[ti] = __builtin_amdgcn_sqrtf(fmaxf(1.f - a * a, 0.f)) * ig * xc;
	v_pk_fma_f32 v[0:1], v[0:1], v[248:249], v[242:243]
	v_pk_fma_f32 v[2:3], v[2:3], v[248:249], v[242:243]
	v_pk_fma_f32 v[4:5], v[4:5], v[248:249], v[242:243]
	v_pk_fma_f32 v[6:7], v[6:7], v[248:249], v[242:243]
	v_pk_fma_f32 v[8:9], v[8:9], v[248:249], v[242:243]
	v_pk_fma_f32 v[10:11], v[10:11], v[248:249], v[242:243]
	v_pk_fma_f32 v[12:13], v[12:13], v[248:249], v[242:243]
	v_pk_fma_f32 v[14:15], v[14:15], v[248:249], v[242:243]
	v_pk_fma_f32 v[16:17], v[16:17], v[248:249], v[244:245]
	v_pk_fma_f32 v[18:19], v[18:19], v[248:249], v[244:245]
	v_pk_fma_f32 v[20:21], v[20:21], v[248:249], v[244:245]
	v_pk_fma_f32 v[22:23], v[22:23], v[248:249], v[244:245]
	v_pk_fma_f32 v[24:25], v[24:25], v[248:249], v[244:245]
	v_pk_fma_f32 v[26:27], v[26:27], v[248:249], v[244:245]
	v_pk_fma_f32 v[28:29], v[28:29], v[248:249], v[244:245]
	v_pk_fma_f32 v[30:31], v[30:31], v[248:249], v[244:245]
	v_exp_f32_e32 v0, v0
	v_exp_f32_e32 v1, v1
	v_exp_f32_e32 v2, v2
	v_exp_f32_e32 v3, v3
	v_exp_f32_e32 v4, v4
	v_exp_f32_e32 v5, v5
	v_exp_f32_e32 v6, v6
	v_exp_f32_e32 v7, v7
	v_exp_f32_e32 v8, v8
	v_exp_f32_e32 v9, v9
	v_exp_f32_e32 v10, v10
	v_exp_f32_e32 v11, v11
	v_exp_f32_e32 v12, v12
	v_exp_f32_e32 v13, v13
	v_exp_f32_e32 v14, v14
	v_exp_f32_e32 v15, v15
	v_exp_f32_e32 v16, v16
	v_exp_f32_e32 v17, v17
	v_exp_f32_e32 v18, v18
	v_exp_f32_e32 v19, v19
	v_exp_f32_e32 v20, v20
	v_exp_f32_e32 v21, v21
	v_exp_f32_e32 v22, v22
	v_exp_f32_e32 v23, v23
	v_exp_f32_e32 v24, v24
	v_exp_f32_e32 v25, v25
	v_exp_f32_e32 v26, v26
	v_exp_f32_e32 v27, v27
	v_exp_f32_e32 v28, v28
	v_exp_f32_e32 v29, v29
	v_exp_f32_e32 v30, v30
	v_exp_f32_e32 v31, v31
	v_pk_add_f32 v[0:1], v[0:1], 1.0 op_sel_hi:[1,0]
	v_pk_add_f32 v[2:3], v[2:3], 1.0 op_sel_hi:[1,0]
	v_pk_add_f32 v[4:5], v[4:5], 1.0 op_sel_hi:[1,0]
	v_pk_add_f32 v[6:7], v[6:7], 1.0 op_sel_hi:[1,0]
	v_pk_add_f32 v[8:9], v[8:9], 1.0 op_sel_hi:[1,0]
	v_pk_add_f32 v[10:11], v[10:11], 1.0 op_sel_hi:[1,0]
	v_pk_add_f32 v[12:13], v[12:13], 1.0 op_sel_hi:[1,0]
	v_pk_add_f32 v[14:15], v[14:15], 1.0 op_sel_hi:[1,0]
	v_pk_add_f32 v[16:17], v[16:17], 1.0 op_sel_hi:[1,0]
	v_pk_add_f32 v[18:19], v[18:19], 1.0 op_sel_hi:[1,0]
	v_pk_add_f32 v[20:21], v[20:21], 1.0 op_sel_hi:[1,0]
	v_pk_add_f32 v[22:23], v[22:23], 1.0 op_sel_hi:[1,0]
	v_pk_add_f32 v[24:25], v[24:25], 1.0 op_sel_hi:[1,0]
	v_pk_add_f32 v[26:27], v[26:27], 1.0 op_sel_hi:[1,0]
	v_pk_add_f32 v[28:29], v[28:29], 1.0 op_sel_hi:[1,0]
	v_pk_add_f32 v[30:31], v[30:31], 1.0 op_sel_hi:[1,0]
	v_rcp_f32_e32 v0, v0
	v_rcp_f32_e32 v1, v1
	v_rcp_f32_e32 v2, v2
	v_rcp_f32_e32 v3, v3
	v_rcp_f32_e32 v4, v4
	v_rcp_f32_e32 v5, v5
	v_rcp_f32_e32 v6, v6
	v_rcp_f32_e32 v7, v7
	v_rcp_f32_e32 v8, v8
	v_rcp_f32_e32 v9, v9
	v_rcp_f32_e32 v10, v10
	v_rcp_f32_e32 v11, v11
	v_rcp_f32_e32 v12, v12
	v_rcp_f32_e32 v13, v13
	v_rcp_f32_e32 v14, v14
	v_rcp_f32_e32 v15, v15
	v_rcp_f32_e32 v16, v16
	v_rcp_f32_e32 v17, v17
	v_rcp_f32_e32 v18, v18
	v_rcp_f32_e32 v19, v19
	v_rcp_f32_e32 v20, v20
	v_rcp_f32_e32 v21, v21
	v_rcp_f32_e32 v22, v22
	v_rcp_f32_e32 v23, v23
	v_rcp_f32_e32 v24, v24
	v_rcp_f32_e32 v25, v25
	v_rcp_f32_e32 v26, v26
	v_rcp_f32_e32 v27, v27
	v_rcp_f32_e32 v28, v28
	v_rcp_f32_e32 v29, v29
	v_rcp_f32_e32 v30, v30
	v_rcp_f32_e32 v31, v31
	v_pk_mul_f32 v[0:1], v[246:247], v[0:1]
	v_pk_mul_f32 v[2:3], v[246:247], v[2:3]
	v_pk_mul_f32 v[4:5], v[246:247], v[4:5]
	v_pk_mul_f32 v[6:7], v[246:247], v[6:7]
	v_pk_mul_f32 v[8:9], v[246:247], v[8:9]
	v_pk_mul_f32 v[10:11], v[246:247], v[10:11]
	v_pk_mul_f32 v[12:13], v[246:247], v[12:13]
	v_pk_mul_f32 v[14:15], v[246:247], v[14:15]
	v_lshlrev_b32_e32 v48, 16, v48
	v_lshlrev_b32_e32 v49, 16, v49
	v_lshlrev_b32_e32 v50, 16, v50
	v_lshlrev_b32_e32 v51, 16, v51
	v_lshlrev_b32_e32 v52, 16, v52
	v_lshlrev_b32_e32 v53, 16, v53
	v_lshlrev_b32_e32 v54, 16, v54
	v_lshlrev_b32_e32 v55, 16, v55
	v_lshlrev_b32_e32 v56, 16, v56
	v_lshlrev_b32_e32 v57, 16, v57
	v_lshlrev_b32_e32 v58, 16, v58
	v_lshlrev_b32_e32 v59, 16, v59
	v_lshlrev_b32_e32 v60, 16, v60
	v_lshlrev_b32_e32 v61, 16, v61
	v_lshlrev_b32_e32 v62, 16, v62
	v_lshlrev_b32_e32 v63, 16, v63
	v_exp_f32_e32 v0, v0
	v_exp_f32_e32 v1, v1
	v_exp_f32_e32 v2, v2
	v_exp_f32_e32 v3, v3
	v_exp_f32_e32 v4, v4
	v_exp_f32_e32 v5, v5
	v_exp_f32_e32 v6, v6
	v_exp_f32_e32 v7, v7
	v_exp_f32_e32 v8, v8
	v_exp_f32_e32 v9, v9
	v_exp_f32_e32 v10, v10
	v_exp_f32_e32 v11, v11
	v_exp_f32_e32 v12, v12
	v_exp_f32_e32 v13, v13
	v_exp_f32_e32 v14, v14
	v_exp_f32_e32 v15, v15
	v_fma_f32 v32, -v0, v0, 1.0 clamp
	v_fma_f32 v33, -v1, v1, 1.0 clamp
	v_fma_f32 v34, -v2, v2, 1.0 clamp
	v_fma_f32 v35, -v3, v3, 1.0 clamp
	v_fma_f32 v36, -v4, v4, 1.0 clamp
	v_fma_f32 v37, -v5, v5, 1.0 clamp
	v_fma_f32 v38, -v6, v6, 1.0 clamp
	v_fma_f32 v39, -v7, v7, 1.0 clamp
	v_fma_f32 v40, -v8, v8, 1.0 clamp
	v_fma_f32 v41, -v9, v9, 1.0 clamp
	v_fma_f32 v42, -v10, v10, 1.0 clamp
	v_fma_f32 v43, -v11, v11, 1.0 clamp
	v_fma_f32 v44, -v12, v12, 1.0 clamp
	v_fma_f32 v45, -v13, v13, 1.0 clamp
	v_fma_f32 v46, -v14, v14, 1.0 clamp
	v_fma_f32 v47, -v15, v15, 1.0 clamp
	v_sqrt_f32_e32 v32, v32
	v_sqrt_f32_e32 v33, v33
	v_sqrt_f32_e32 v34, v34
	v_sqrt_f32_e32 v35, v35
	v_sqrt_f32_e32 v36, v36
	v_sqrt_f32_e32 v37, v37
	v_sqrt_f32_e32 v38, v38
	v_sqrt_f32_e32 v39, v39
	v_sqrt_f32_e32 v40, v40
	v_sqrt_f32_e32 v41, v41
	v_sqrt_f32_e32 v42, v42
	v_sqrt_f32_e32 v43, v43
	v_sqrt_f32_e32 v44, v44
	v_sqrt_f32_e32 v45, v45
	v_sqrt_f32_e32 v46, v46
	v_sqrt_f32_e32 v47, v47
	s_nop 0
	v_pk_mul_f32 v[16:17], v[16:17], v[32:33]
	v_pk_mul_f32 v[18:19], v[18:19], v[34:35]
	v_pk_mul_f32 v[20:21], v[20:21], v[36:37]
	v_pk_mul_f32 v[22:23], v[22:23], v[38:39]
	v_pk_mul_f32 v[24:25], v[24:25], v[40:41]
; __device__ __forceinline__ unsigned f2bf(float f) { unsigned r; asm("v_cvt_pk_bf16_f32 %0, %1, %1" : "=v"(r) : "v"(f)); return r & 0xffffu; }
; __device__ __forceinline__ float sigmoid_f(float x) { return rcpf_(1.f + __expf(-x)); }
; __device__ __forceinline__ float gelu_tanh_f(float x) { const float y = 0.7978845608028654f * (x + 0.044715f * x * x * x); return x * sigmoid_f(2.f * y); }
; template <bool FINAL, int D>
; __device__ __forceinline__ void rg_dir(PREF p, int l, int h, int ch, int sidx, int rowbase  , LAS bf16_t* sXc, LAS float* stg, int lane) {
;     ...
;         for (int ti = 0; ti < 16; ++ti) { const int tk = D ? 15 - ti : ti;
;             const float zr = stg[tk * 64 + lane] + ba, zi = stg[1024 + tk * 64 + lane] + bi;
;             const float r = sigmoid_f(zr), ig = sigmoid_f(zi);
;             const float a = __builtin_amdgcn_exp2f(r * sp8);
;             const float xc = bf2f(sXc[(mt * 16 + tk) * 72 + lane]);
;             av[ti] = a; iv[ti] = __builtin_amdgcn_sqrtf(fmaxf(1.f - a * a, 0.f)) * ig * xc;
;             if (FINAL && D == 1) grv[ti] = gelu_tanh_f(grv[ti]);
;         }
; #pragma unroll
;         for (int ti = 0; ti < 16; ++ti) { const int tk = D ? 15 - ti : ti;
;             hc = av[ti] * hc + iv[ti]; Ap *= av[ti];
;             if (FINAL) { const size_t row = (size_t)(rowbase + mt * 16 + tk);
;                 if (D == 0) TMP[row * 512 + ch] = (bf16_t)f2bf(hc);
;                 else MIX[row * DM + ch] = (bf16_t)f2bf(grv[ti] * (hfv[ti] + hc)); }
;         }
	v_pk_mul_f32 v[26:27], v[26:27], v[42:43]
	v_pk_mul_f32 v[28:29], v[28:29], v[44:45]
	v_pk_mul_f32 v[30:31], v[30:31], v[46:47]
	v_pk_mul_f32 v[16:17], v[16:17], v[48:49]
	v_pk_mul_f32 v[18:19], v[18:19], v[50:51]
	v_pk_mul_f32 v[20:21], v[20:21], v[52:53]
	v_pk_mul_f32 v[22:23], v[22:23], v[54:55]
	v_pk_mul_f32 v[24:25], v[24:25], v[56:57]
	v_pk_mul_f32 v[26:27], v[26:27], v[58:59]
	v_pk_mul_f32 v[28:29], v[28:29], v[60:61]
	v_pk_mul_f32 v[30:31], v[30:31], v[62:63]
	s_add_i32 s39, s15, 30
	s_lshl_b32 s39, s39, 11
	s_add_u32 s90, s0, 0x7b00000
	s_addc_u32 s91, s1, 0
	s_add_u32 s90, s90, s39
	s_addc_u32 s91, s91, 0
	v_lshlrev_b32_e32 v48, 16, v166
	v_and_b32_e32 v49, 0xffff0000, v166
	v_lshlrev_b32_e32 v50, 16, v167
	v_and_b32_e32 v51, 0xffff0000, v167
	v_lshlrev_b32_e32 v52, 16, v168
	v_and_b32_e32 v53, 0xffff0000, v168
	v_lshlrev_b32_e32 v54, 16, v169
	v_and_b32_e32 v55, 0xffff0000, v169
	v_lshlrev_b32_e32 v56, 16, v170
	v_and_b32_e32 v57, 0xffff0000, v170
	v_lshlrev_b32_e32 v58, 16, v171
	v_and_b32_e32 v59, 0xffff0000, v171
	v_lshlrev_b32_e32 v60, 16, v172
	v_and_b32_e32 v61, 0xffff0000, v172
	v_lshlrev_b32_e32 v62, 16, v173
	v_and_b32_e32 v63, 0xffff0000, v173
	v_fma_f32 v47, v15, v250, v31
	v_fma_f32 v46, v14, v47, v30
	v_fma_f32 v45, v13, v46, v29
	v_fma_f32 v44, v12, v45, v28
	v_fma_f32 v43, v11, v44, v27
	v_fma_f32 v42, v10, v43, v26
	v_fma_f32 v41, v9, v42, v25
	v_fma_f32 v40, v8, v41, v24
	v_fma_f32 v39, v7, v40, v23
	v_fma_f32 v38, v6, v39, v22
	v_fma_f32 v37, v5, v38, v21
	v_fma_f32 v36, v4, v37, v20
	v_fma_f32 v35, v3, v36, v19
	v_fma_f32 v34, v2, v35, v18
	v_fma_f32 v33, v1, v34, v17
	v_fma_f32 v32, v0, v33, v16
	v_mov_b32_e32 v250, v32
	v_pk_add_f32 v[48:49], v[48:49], v[32:33]
	v_pk_add_f32 v[50:51], v[50:51], v[34:35]
	v_pk_add_f32 v[52:53], v[52:53], v[36:37]
	v_pk_add_f32 v[54:55], v[54:55], v[38:39]
	v_pk_add_f32 v[56:57], v[56:57], v[40:41]
	v_pk_add_f32 v[58:59], v[58:59], v[42:43]
	v_pk_add_f32 v[60:61], v[60:61], v[44:45]
	v_pk_add_f32 v[62:63], v[62:63], v[46:47]
	v_pk_mul_f32 v[48:49], v[206:207], v[48:49]
	v_pk_mul_f32 v[50:51], v[208:209], v[50:51]
	v_pk_mul_f32 v[52:53], v[210:211], v[52:53]
	v_pk_mul_f32 v[54:55], v[212:213], v[54:55]
	v_pk_mul_f32 v[56:57], v[214:215], v[56:57]
	v_pk_mul_f32 v[58:59], v[216:217], v[58:59]
	v_pk_mul_f32 v[60:61], v[218:219], v[60:61]
	v_pk_mul_f32 v[62:63], v[222:223], v[62:63]
	v_cvt_pk_bf16_f32 v48, v48, v49
	v_cvt_pk_bf16_f32 v50, v50, v51
	v_cvt_pk_bf16_f32 v52, v52, v53
	v_cvt_pk_bf16_f32 v54, v54, v55
	v_cvt_pk_bf16_f32 v56, v56, v57
	v_cvt_pk_bf16_f32 v58, v58, v59
	v_cvt_pk_bf16_f32 v60, v60, v61
	v_cvt_pk_bf16_f32 v62, v62, v63
	global_store_short_d16_hi v234, v62, s[90:91] offset:2048
	global_store_short v234, v62, s[90:91]
	s_sub_u32 s90, s90, 0x1000
	s_subb_u32 s91, s91, 0
	global_store_short_d16_hi v234, v60, s[90:91] offset:2048
	global_store_short v234, v60, s[90:91]
	s_sub_u32 s90, s90, 0x1000
	s_subb_u32 s91, s91, 0
	global_store_short_d16_hi v234, v58, s[90:91] offset:2048
	global_store_short v234, v58, s[90:91]
	s_sub_u32 s90, s90, 0x1000
	s_subb_u32 s91, s91, 0
	global_store_short_d16_hi v234, v56, s[90:91] offset:2048
	global_store_short v234, v56, s[90:91]
	s_sub_u32 s90, s90, 0x1000
	s_subb_u32 s91, s91, 0
	global_store_short_d16_hi v234, v54, s[90:91] offset:2048
	global_store_short v234, v54, s[90:91]
	s_sub_u32 s90, s90, 0x1000
	s_subb_u32 s91, s91, 0
	global_store_short_d16_hi v234, v52, s[90:91] offset:2048
	global_store_short v234, v52, s[90:91]
	s_sub_u32 s90, s90, 0x1000
	s_subb_u32 s91, s91, 0
	global_store_short_d16_hi v234, v50, s[90:91] offset:2048
	global_store_short v234, v50, s[90:91]
	s_sub_u32 s90, s90, 0x1000
	s_subb_u32 s91, s91, 0
	global_store_short_d16_hi v234, v48, s[90:91] offset:2048
	global_store_short v234, v48, s[90:91]
	ds_read_b128 v[32:35], v236 offset:0
	ds_read_b128 v[36:39], v236 offset:64
	s_waitcnt lgkmcnt(0)
	v_mfma_f32_16x16x32_bf16 v[0:3], v[32:35], v[80:83], 0
	v_mfma_f32_16x16x32_bf16 v[4:7], v[32:35], v[88:91], 0
	v_mfma_f32_16x16x32_bf16 v[8:11], v[32:35], v[96:99], 0
	v_mfma_f32_16x16x32_bf16 v[12:15], v[32:35], v[104:107], 0
	v_mfma_f32_16x16x32_bf16 v[16:19], v[32:35], v[112:115], 0
	v_mfma_f32_16x16x32_bf16 v[20:23], v[32:35], v[120:123], 0
	v_mfma_f32_16x16x32_bf16 v[24:27], v[32:35], v[128:131], 0
	v_mfma_f32_16x16x32_bf16 v[28:31], v[32:35], v[136:139], 0
	v_mfma_f32_16x16x32_bf16 v[0:3], v[36:39], v[84:87], v[0:3]
	v_mfma_f32_16x16x32_bf16 v[4:7], v[36:39], v[92:95], v[4:7]
	v_mfma_f32_16x16x32_bf16 v[8:11], v[36:39], v[100:103], v[8:11]
	v_mfma_f32_16x16x32_bf16 v[12:15], v[36:39], v[108:111], v[12:15]
	v_mfma_f32_16x16x32_bf16 v[16:19], v[36:39], v[116:119], v[16:19]
	v_mfma_f32_16x16x32_bf16 v[20:23], v[36:39], v[124:127], v[20:23]
	v_mfma_f32_16x16x32_bf16 v[24:27], v[36:39], v[132:135], v[24:27]
	v_mfma_f32_16x16x32_bf16 v[28:31], v[36:39], v[228:231], v[28:31]
	s_nop 3
	ds_write2_b32 v237, v0, v4 offset0:0 offset1:16
	ds_write2_b32 v237, v8, v12 offset0:32 offset1:48
	ds_write2_b32 v237, v1, v5 offset0:64 offset1:80
	ds_write2_b32 v237, v9, v13 offset0:96 offset1:112
	ds_write2_b32 v237, v2, v6 offset0:128 offset1:144
	ds_write2_b32 v237, v10, v14 offset0:160 offset1:176
	ds_write2_b32 v237, v3, v7 offset0:192 offset1:208
	ds_write2_b32 v237, v11, v15 offset0:224 offset1:240
	ds_write2_b32 v238, v16, v20 offset0:0 offset1:16
	ds_write2_b32 v238, v24, v28 offset0:32 offset1:48
	ds_write2_b32 v238, v17, v21 offset0:64 offset1:80
	ds_write2_b32 v238, v25, v29 offset0:96 offset1:112
	ds_write2_b32 v238, v18, v22 offset0:128 offset1:144
	ds_write2_b32 v238, v26, v30 offset0:160 offset1:176
	ds_write2_b32 v238, v19, v23 offset0:192 offset1:208
	ds_write2_b32 v238, v27, v31 offset0:224 offset1:240
	s_waitcnt lgkmcnt(0)
; #define LAS __attribute__((address_space(3)))
; #define WAVE_SYNC() asm volatile("s_waitcnt lgkmcnt(0)" ::: "memory")
; __device__ __forceinline__ float sigmoid_f(float x) { return rcpf_(1.f + __expf(-x)); }
; template <bool FINAL, int D>
; __device__ __forceinline__ void rg_dir(PREF p, int l, int h, int ch, int sidx, int rowbase  , LAS bf16_t* sXc, LAS float* stg, int lane) {
;     ...
;         if (FINAL && D == 1) {
; #pragma unroll
;             for (int ti = 0; ti < 16; ++ti) { const size_t row = (size_t)(rowbase + mt * 16 + 15 - ti); grv[ti] = __builtin_bit_cast(float, (unsigned)P[row * PW + 512 + ch]); hfv[ti] = __builtin_bit_cast(float, (unsigned)TMP[row * 512 + ch]); }
;             __builtin_amdgcn_sched_barrier(0);
; #pragma unroll
;             for (int ti = 0; ti < 16; ++ti) { grv[ti] = bf2f(__builtin_bit_cast(unsigned, grv[ti])); hfv[ti] = bf2f(__builtin_bit_cast(unsigned, hfv[ti])); }
;         }
;         const bf16x8 A0 = *(const LAS bf16x8*)(sXc + (mt * 16 + (lane & 15)) * 72 + (lane >> 4) * 8), A1 = *(const LAS bf16x8*)(sXc + (mt * 16 + (lane & 15)) * 72 + 32 + (lane >> 4) * 8);
;         f32x4 ar[4], ai[4];
; #pragma unroll
;         for (int nt = 0; nt < 4; ++nt) { const f32x4 z = {0.f, 0.f, 0.f, 0.f};
;             ar[nt] = mfma16(A0, Br[nt][0], z); ar[nt] = mfma16(A1, Br[nt][1], ar[nt]); ai[nt] = mfma16(A0, Bi[nt][0], z); ai[nt] = mfma16(A1, Bi[nt][1], ai[nt]); }
;         WAVE_SYNC();
; #pragma unroll
;         for (int nt = 0; nt < 4; ++nt)
; #pragma unroll
;             for (int j = 0; j < 4; ++j) { const int o = ((lane >> 4) * 4 + j) * 64 + nt * 16 + (lane & 15); stg[o] = ar[nt][j]; stg[1024 + o] = ai[nt][j]; }
;         WAVE_SYNC();
;         float av[16], iv[16];
; #pragma unroll
;         for (int ti = 0; ti < 16; ++ti) { const int tk = D ? 15 - ti : ti;
;             const float zr = stg[tk * 64 + lane] + ba, zi = stg[1024 + tk * 64 + lane] + bi;
;             const float r = sigmoid_f(zr), ig = sigmoid_f(zi);
;             const float a = __builtin_amdgcn_exp2f(r * sp8);
;             const float xc = bf2f(sXc[(mt * 16 + tk) * 72 + lane]);
;             av[ti] = a; iv[ti] = __builtin_amdgcn_sqrtf(fmaxf(1.f - a * a, 0.f)) * ig * xc;
;             if (FINAL && D == 1) grv[ti] = gelu_tanh_f(grv[ti]);
	ds_read2st64_b32 v[0:1], v239 offset0:36 offset1:37
	ds_read2st64_b32 v[2:3], v239 offset0:38 offset1:39
	ds_read2st64_b32 v[4:5], v239 offset0:40 offset1:41
	ds_read2st64_b32 v[6:7], v239 offset0:42 offset1:43
	ds_read2st64_b32 v[8:9], v239 offset0:44 offset1:45
	ds_read2st64_b32 v[10:11], v239 offset0:46 offset1:47
	ds_read2st64_b32 v[12:13], v239 offset0:48 offset1:49
	ds_read2st64_b32 v[14:15], v239 offset0:50 offset1:51
	ds_read2st64_b32 v[16:17], v239 offset0:52 offset1:53
	ds_read2st64_b32 v[18:19], v239 offset0:54 offset1:55
	ds_read2st64_b32 v[20:21], v239 offset0:56 offset1:57
	ds_read2st64_b32 v[22:23], v239 offset0:58 offset1:59
	ds_read2st64_b32 v[24:25], v239 offset0:60 offset1:61
	ds_read2st64_b32 v[26:27], v239 offset0:62 offset1:63
	ds_read2st64_b32 v[28:29], v239 offset0:64 offset1:65
	ds_read2st64_b32 v[30:31], v239 offset0:66 offset1:67
	ds_read_u16 v48, v240 offset:0
	ds_read_u16 v49, v240 offset:144
	ds_read_u16 v50, v240 offset:288
	ds_read_u16 v51, v240 offset:432
	ds_read_u16 v52, v240 offset:576
	ds_read_u16 v53, v240 offset:720
	ds_read_u16 v54, v240 offset:864
	ds_read_u16 v55, v240 offset:1008
	ds_read_u16 v56, v240 offset:1152
	ds_read_u16 v57, v240 offset:1296
	ds_read_u16 v58, v240 offset:1440
	ds_read_u16 v59, v240 offset:1584
	ds_read_u16 v60, v240 offset:1728
	ds_read_u16 v61, v240 offset:1872
	ds_read_u16 v62, v240 offset:2016
	ds_read_u16 v63, v240 offset:2160
	s_waitcnt vmcnt(16)
	v_lshlrev_b32_e32 v206, 16, v190
	v_lshlrev_b32_e32 v207, 16, v191
	v_lshlrev_b32_e32 v208, 16, v192
	v_lshlrev_b32_e32 v209, 16, v193
	v_lshlrev_b32_e32 v210, 16, v194
	v_lshlrev_b32_e32 v211, 16, v195
	v_lshlrev_b32_e32 v212, 16, v196
	v_lshlrev_b32_e32 v213, 16, v197
	v_lshlrev_b32_e32 v214, 16, v198
	v_lshlrev_b32_e32 v215, 16, v199
	v_lshlrev_b32_e32 v216, 16, v200
	v_lshlrev_b32_e32 v217, 16, v201
	v_lshlrev_b32_e32 v218, 16, v202
	v_lshlrev_b32_e32 v219, 16, v203
	v_lshlrev_b32_e32 v222, 16, v204
	v_lshlrev_b32_e32 v223, 16, v205
	v_pk_mul_f32 v[32:33], v[140:141], v[206:207]
	v_pk_mul_f32 v[34:35], v[140:141], v[208:209]
	v_pk_mul_f32 v[36:37], v[140:141], v[210:211]
	v_pk_mul_f32 v[38:39], v[140:141], v[212:213]
	v_pk_mul_f32 v[40:41], v[140:141], v[214:215]
	v_pk_mul_f32 v[42:43], v[140:141], v[216:217]
	v_pk_mul_f32 v[44:45], v[140:141], v[218:219]
	v_pk_mul_f32 v[46:47], v[140:141], v[222:223]
	v_pk_mul_f32 v[32:33], v[32:33], v[206:207]
	v_pk_mul_f32 v[34:35], v[34:35], v[208:209]
	v_pk_mul_f32 v[36:37], v[36:37], v[210:211]
	v_pk_mul_f32 v[38:39], v[38:39], v[212:213]
	v_pk_mul_f32 v[40:41], v[40:41], v[214:215]
	v_pk_mul_f32 v[42:43], v[42:43], v[216:217]
	v_pk_mul_f32 v[44:45], v[44:45], v[218:219]
	v_pk_mul_f32 v[46:47], v[46:47], v[222:223]
	v_fma_f32 v32, v32, v206, v206
	v_fma_f32 v33, v33, v207, v207
	v_fma_f32 v34, v34, v208, v208
	v_fma_f32 v35, v35, v209, v209
	v_fma_f32 v36, v36, v210, v210
	v_fma_f32 v37, v37, v211, v211
	v_fma_f32 v38, v38, v212, v212
	v_fma_f32 v39, v39, v213, v213
	v_fma_f32 v40, v40, v214, v214
	v_fma_f32 v41, v41, v215, v215
	v_fma_f32 v42, v42, v216, v216
	v_fma_f32 v43, v43, v217, v217
	v_fma_f32 v44, v44, v218, v218
	v_fma_f32 v45, v45, v219, v219
	v_fma_f32 v46, v46, v222, v222
	v_fma_f32 v47, v47, v223, v223
	s_mov_b32 s98, 0xc0135761
	v_pk_mul_f32 v[32:33], v[32:33], s[98:99] op_sel_hi:[1,0]
	v_pk_mul_f32 v[34:35], v[34:35], s[98:99] op_sel_hi:[1,0]
	v_pk_mul_f32 v[36:37], v[36:37], s[98:99] op_sel_hi:[1,0]
	v_pk_mul_f32 v[38:39], v[38:39], s[98:99] op_sel_hi:[1,0]
	v_pk_mul_f32 v[40:41], v[40:41], s[98:99] op_sel_hi:[1,0]
	v_pk_mul_f32 v[42:43], v[42:43], s[98:99] op_sel_hi:[1,0]
	v_pk_mul_f32 v[44:45], v[44:45], s[98:99] op_sel_hi:[1,0]
	v_pk_mul_f32 v[46:47], v[46:47], s[98:99] op_sel_hi:[1,0]
	v_exp_f32_e32 v32, v32
	v_exp_f32_e32 v33, v33
	v_exp_f32_e32 v34, v34
	v_exp_f32_e32 v35, v35
	v_exp_f32_e32 v36, v36
	v_exp_f32_e32 v37, v37
	v_exp_f32_e32 v38, v38
	v_exp_f32_e32 v39, v39
	v_exp_f32_e32 v40, v40
	v_exp_f32_e32 v41, v41
	v_exp_f32_e32 v42, v42
	v_exp_f32_e32 v43, v43
	v_exp_f32_e32 v44, v44
	v_exp_f32_e32 v45, v45
	v_exp_f32_e32 v46, v46
	v_exp_f32_e32 v47, v47
	v_pk_add_f32 v[32:33], v[32:33], 1.0 op_sel_hi:[1,0]
	v_pk_add_f32 v[34:35], v[34:35], 1.0 op_sel_hi:[1,0]
	v_pk_add_f32 v[36:37], v[36:37], 1.0 op_sel_hi:[1,0]
	v_pk_add_f32 v[38:39], v[38:39], 1.0 op_sel_hi:[1,0]
	v_pk_add_f32 v[40:41], v[40:41], 1.0 op_sel_hi:[1,0]
	v_pk_add_f32 v[42:43], v[42:43], 1.0 op_sel_hi:[1,0]
	v_pk_add_f32 v[44:45], v[44:45], 1.0 op_sel_hi:[1,0]
	v_pk_add_f32 v[46:47], v[46:47], 1.0 op_sel_hi:[1,0]
	v_rcp_f32_e32 v32, v32
	v_rcp_f32_e32 v33, v33
	v_rcp_f32_e32 v34, v34
	v_rcp_f32_e32 v35, v35
	v_rcp_f32_e32 v36, v36
	v_rcp_f32_e32 v37, v37
	v_rcp_f32_e32 v38, v38
	v_rcp_f32_e32 v39, v39
	v_rcp_f32_e32 v40, v40
	v_rcp_f32_e32 v41, v41
	v_rcp_f32_e32 v42, v42
	v_rcp_f32_e32 v43, v43
	v_rcp_f32_e32 v44, v44
	v_rcp_f32_e32 v45, v45
	v_rcp_f32_e32 v46, v46
	v_rcp_f32_e32 v47, v47
	s_nop 0
	v_pk_mul_f32 v[206:207], v[32:33], v[206:207]
	v_pk_mul_f32 v[208:209], v[34:35], v[208:209]
	v_pk_mul_f32 v[210:211], v[36:37], v[210:211]
	v_pk_mul_f32 v[212:213], v[38:39], v[212:213]
	v_pk_mul_f32 v[214:215], v[40:41], v[214:215]
	v_pk_mul_f32 v[216:217], v[42:43], v[216:217]
	v_pk_mul_f32 v[218:219], v[44:45], v[218:219]
	v_pk_mul_f32 v[222:223], v[46:47], v[222:223]
	s_waitcnt lgkmcnt(0)
; __device__ __forceinline__ float sigmoid_f(float x) { return rcpf_(1.f + __expf(-x)); }
; template <bool FINAL, int D>
; __device__ __forceinline__ void rg_dir(PREF p, int l, int h, int ch, int sidx, int rowbase  , LAS bf16_t* sXc, LAS float* stg, int lane) {
;     ...
;         for (int ti = 0; ti < 16; ++ti) { const int tk = D ? 15 - ti : ti;
;             const float zr = stg[tk * 64 + lane] + ba, zi = stg[1024 + tk * 64 + lane] + bi;
;             const float r = sigmoid_f(zr), ig = sigmoid_f(zi);
;             const float a = __builtin_amdgcn_exp2f(r * sp8);
;             const float xc = bf2f(sXc[(mt * 16 + tk) * 72 + lane]);
;             av[ti] = a; iv[ti] = __builtin_amdgcn_sqrtf(fmaxf(1.f - a * a, 0.f)) * ig * xc;
	v_pk_fma_f32 v[0:1], v[0:1], v[248:249], v[242:243]
	v_pk_fma_f32 v[2:3], v[2:3], v[248:249], v[242:243]
	v_pk_fma_f32 v[4:5], v[4:5], v[248:249], v[242:243]
	v_pk_fma_f32 v[6:7], v[6:7], v[248:249], v[242:243]
	v_pk_fma_f32 v[8:9], v[8:9], v[248:249], v[242:243]
	v_pk_fma_f32 v[10:11], v[10:11], v[248:249], v[242:243]
	v_pk_fma_f32 v[12:13], v[12:13], v[248:249], v[242:243]
	v_pk_fma_f32 v[14:15], v[14:15], v[248:249], v[242:243]
	v_pk_fma_f32 v[16:17], v[16:17], v[248:249], v[244:245]
	v_pk_fma_f32 v[18:19], v[18:19], v[248:249], v[244:245]
	v_pk_fma_f32 v[20:21], v[20:21], v[248:249], v[244:245]
	v_pk_fma_f32 v[22:23], v[22:23], v[248:249], v[244:245]
	v_pk_fma_f32 v[24:25], v[24:25], v[248:249], v[244:245]
	v_pk_fma_f32 v[26:27], v[26:27], v[248:249], v[244:245]
	v_pk_fma_f32 v[28:29], v[28:29], v[248:249], v[244:245]
	v_pk_fma_f32 v[30:31], v[30:31], v[248:249], v[244:245]
	v_exp_f32_e32 v0, v0
	v_exp_f32_e32 v1, v1
	v_exp_f32_e32 v2, v2
	v_exp_f32_e32 v3, v3
	v_exp_f32_e32 v4, v4
	v_exp_f32_e32 v5, v5
	v_exp_f32_e32 v6, v6
	v_exp_f32_e32 v7, v7
	v_exp_f32_e32 v8, v8
	v_exp_f32_e32 v9, v9
	v_exp_f32_e32 v10, v10
	v_exp_f32_e32 v11, v11
	v_exp_f32_e32 v12, v12
	v_exp_f32_e32 v13, v13
	v_exp_f32_e32 v14, v14
	v_exp_f32_e32 v15, v15
	v_exp_f32_e32 v16, v16
	v_exp_f32_e32 v17, v17
	v_exp_f32_e32 v18, v18
	v_exp_f32_e32 v19, v19
	v_exp_f32_e32 v20, v20
	v_exp_f32_e32 v21, v21
	v_exp_f32_e32 v22, v22
	v_exp_f32_e32 v23, v23
	v_exp_f32_e32 v24, v24
	v_exp_f32_e32 v25, v25
	v_exp_f32_e32 v26, v26
	v_exp_f32_e32 v27, v27
	v_exp_f32_e32 v28, v28
	v_exp_f32_e32 v29, v29
	v_exp_f32_e32 v30, v30
	v_exp_f32_e32 v31, v31
	v_pk_add_f32 v[0:1], v[0:1], 1.0 op_sel_hi:[1,0]
	v_pk_add_f32 v[2:3], v[2:3], 1.0 op_sel_hi:[1,0]
	v_pk_add_f32 v[4:5], v[4:5], 1.0 op_sel_hi:[1,0]
	v_pk_add_f32 v[6:7], v[6:7], 1.0 op_sel_hi:[1,0]
	v_pk_add_f32 v[8:9], v[8:9], 1.0 op_sel_hi:[1,0]
	v_pk_add_f32 v[10:11], v[10:11], 1.0 op_sel_hi:[1,0]
	v_pk_add_f32 v[12:13], v[12:13], 1.0 op_sel_hi:[1,0]
	v_pk_add_f32 v[14:15], v[14:15], 1.0 op_sel_hi:[1,0]
	v_pk_add_f32 v[16:17], v[16:17], 1.0 op_sel_hi:[1,0]
	v_pk_add_f32 v[18:19], v[18:19], 1.0 op_sel_hi:[1,0]
	v_pk_add_f32 v[20:21], v[20:21], 1.0 op_sel_hi:[1,0]
	v_pk_add_f32 v[22:23], v[22:23], 1.0 op_sel_hi:[1,0]
	v_pk_add_f32 v[24:25], v[24:25], 1.0 op_sel_hi:[1,0]
	v_pk_add_f32 v[26:27], v[26:27], 1.0 op_sel_hi:[1,0]
	v_pk_add_f32 v[28:29], v[28:29], 1.0 op_sel_hi:[1,0]
	v_pk_add_f32 v[30:31], v[30:31], 1.0 op_sel_hi:[1,0]
	v_rcp_f32_e32 v0, v0
	v_rcp_f32_e32 v1, v1
	v_rcp_f32_e32 v2, v2
	v_rcp_f32_e32 v3, v3
	v_rcp_f32_e32 v4, v4
	v_rcp_f32_e32 v5, v5
	v_rcp_f32_e32 v6, v6
	v_rcp_f32_e32 v7, v7
	v_rcp_f32_e32 v8, v8
	v_rcp_f32_e32 v9, v9
	v_rcp_f32_e32 v10, v10
	v_rcp_f32_e32 v11, v11
	v_rcp_f32_e32 v12, v12
	v_rcp_f32_e32 v13, v13
	v_rcp_f32_e32 v14, v14
	v_rcp_f32_e32 v15, v15
	v_rcp_f32_e32 v16, v16
	v_rcp_f32_e32 v17, v17
	v_rcp_f32_e32 v18, v18
	v_rcp_f32_e32 v19, v19
	v_rcp_f32_e32 v20, v20
	v_rcp_f32_e32 v21, v21
	v_rcp_f32_e32 v22, v22
	v_rcp_f32_e32 v23, v23
	v_rcp_f32_e32 v24, v24
	v_rcp_f32_e32 v25, v25
	v_rcp_f32_e32 v26, v26
	v_rcp_f32_e32 v27, v27
	v_rcp_f32_e32 v28, v28
	v_rcp_f32_e32 v29, v29
	v_rcp_f32_e32 v30, v30
	v_rcp_f32_e32 v31, v31
	v_pk_mul_f32 v[0:1], v[246:247], v[0:1]
	v_pk_mul_f32 v[2:3], v[246:247], v[2:3]
	v_pk_mul_f32 v[4:5], v[246:247], v[4:5]
	v_pk_mul_f32 v[6:7], v[246:247], v[6:7]
	v_pk_mul_f32 v[8:9], v[246:247], v[8:9]
	v_pk_mul_f32 v[10:11], v[246:247], v[10:11]
	v_pk_mul_f32 v[12:13], v[246:247], v[12:13]
	v_pk_mul_f32 v[14:15], v[246:247], v[14:15]
	v_lshlrev_b32_e32 v48, 16, v48
	v_lshlrev_b32_e32 v49, 16, v49
	v_lshlrev_b32_e32 v50, 16, v50
	v_lshlrev_b32_e32 v51, 16, v51
	v_lshlrev_b32_e32 v52, 16, v52
	v_lshlrev_b32_e32 v53, 16, v53
	v_lshlrev_b32_e32 v54, 16, v54
	v_lshlrev_b32_e32 v55, 16, v55
	v_lshlrev_b32_e32 v56, 16, v56
	v_lshlrev_b32_e32 v57, 16, v57
	v_lshlrev_b32_e32 v58, 16, v58
	v_lshlrev_b32_e32 v59, 16, v59
	v_lshlrev_b32_e32 v60, 16, v60
	v_lshlrev_b32_e32 v61, 16, v61
	v_lshlrev_b32_e32 v62, 16, v62
	v_lshlrev_b32_e32 v63, 16, v63
	v_exp_f32_e32 v0, v0
	v_exp_f32_e32 v1, v1
	v_exp_f32_e32 v2, v2
	v_exp_f32_e32 v3, v3
	v_exp_f32_e32 v4, v4
	v_exp_f32_e32 v5, v5
	v_exp_f32_e32 v6, v6
	v_exp_f32_e32 v7, v7
	v_exp_f32_e32 v8, v8
	v_exp_f32_e32 v9, v9
	v_exp_f32_e32 v10, v10
	v_exp_f32_e32 v11, v11
	v_exp_f32_e32 v12, v12
	v_exp_f32_e32 v13, v13
	v_exp_f32_e32 v14, v14
	v_exp_f32_e32 v15, v15
	v_fma_f32 v32, -v0, v0, 1.0 clamp
	v_fma_f32 v33, -v1, v1, 1.0 clamp
	v_fma_f32 v34, -v2, v2, 1.0 clamp
	v_fma_f32 v35, -v3, v3, 1.0 clamp
	v_fma_f32 v36, -v4, v4, 1.0 clamp
	v_fma_f32 v37, -v5, v5, 1.0 clamp
	v_fma_f32 v38, -v6, v6, 1.0 clamp
	v_fma_f32 v39, -v7, v7, 1.0 clamp
	v_fma_f32 v40, -v8, v8, 1.0 clamp
	v_fma_f32 v41, -v9, v9, 1.0 clamp
	v_fma_f32 v42, -v10, v10, 1.0 clamp
	v_fma_f32 v43, -v11, v11, 1.0 clamp
; __device__ __forceinline__ unsigned f2bf(float f) { unsigned r; asm("v_cvt_pk_bf16_f32 %0, %1, %1" : "=v"(r) : "v"(f)); return r & 0xffffu; }
; __device__ __forceinline__ float sigmoid_f(float x) { return rcpf_(1.f + __expf(-x)); }
; __device__ __forceinline__ float gelu_tanh_f(float x) { const float y = 0.7978845608028654f * (x + 0.044715f * x * x * x); return x * sigmoid_f(2.f * y); }
; template <bool FINAL, int D>
; __device__ __forceinline__ void rg_dir(PREF p, int l, int h, int ch, int sidx, int rowbase  , LAS bf16_t* sXc, LAS float* stg, int lane) {
;     ...
;         for (int ti = 0; ti < 16; ++ti) { const int tk = D ? 15 - ti : ti;
;             const float zr = stg[tk * 64 + lane] + ba, zi = stg[1024 + tk * 64 + lane] + bi;
;             const float r = sigmoid_f(zr), ig = sigmoid_f(zi);
;             const float a = __builtin_amdgcn_exp2f(r * sp8);
;             const float xc = bf2f(sXc[(mt * 16 + tk) * 72 + lane]);
;             av[ti] = a; iv[ti] = __builtin_amdgcn_sqrtf(fmaxf(1.f - a * a, 0.f)) * ig * xc;
;             if (FINAL && D == 1) grv[ti] = gelu_tanh_f(grv[ti]);
;         }
; #pragma unroll
;         for (int ti = 0; ti < 16; ++ti) { const int tk = D ? 15 - ti : ti;
;             hc = av[ti] * hc + iv[ti]; Ap *= av[ti];
;             if (FINAL) { const size_t row = (size_t)(rowbase + mt * 16 + tk);
;                 if (D == 0) TMP[row * 512 + ch] = (bf16_t)f2bf(hc);
;                 else MIX[row * DM + ch] = (bf16_t)f2bf(grv[ti] * (hfv[ti] + hc)); }
;         }
; __global__ void __launch_bounds__(NTHREADS, 2) mega_fwd(Params p_arg) {
;     ...
;             for (int item = gw; item < nrg; item += NGW) rg_item<true>(p, l, item, lds + wave * 18432, lane);
	v_fma_f32 v44, -v12, v12, 1.0 clamp
	v_fma_f32 v45, -v13, v13, 1.0 clamp
	v_fma_f32 v46, -v14, v14, 1.0 clamp
	v_fma_f32 v47, -v15, v15, 1.0 clamp
	v_sqrt_f32_e32 v32, v32
	v_sqrt_f32_e32 v33, v33
	v_sqrt_f32_e32 v34, v34
	v_sqrt_f32_e32 v35, v35
	v_sqrt_f32_e32 v36, v36
	v_sqrt_f32_e32 v37, v37
	v_sqrt_f32_e32 v38, v38
	v_sqrt_f32_e32 v39, v39
	v_sqrt_f32_e32 v40, v40
	v_sqrt_f32_e32 v41, v41
	v_sqrt_f32_e32 v42, v42
	v_sqrt_f32_e32 v43, v43
	v_sqrt_f32_e32 v44, v44
	v_sqrt_f32_e32 v45, v45
	v_sqrt_f32_e32 v46, v46
	v_sqrt_f32_e32 v47, v47
	s_nop 0
	v_pk_mul_f32 v[16:17], v[16:17], v[32:33]
	v_pk_mul_f32 v[18:19], v[18:19], v[34:35]
	v_pk_mul_f32 v[20:21], v[20:21], v[36:37]
	v_pk_mul_f32 v[22:23], v[22:23], v[38:39]
	v_pk_mul_f32 v[24:25], v[24:25], v[40:41]
	v_pk_mul_f32 v[26:27], v[26:27], v[42:43]
	v_pk_mul_f32 v[28:29], v[28:29], v[44:45]
	v_pk_mul_f32 v[30:31], v[30:31], v[46:47]
	v_pk_mul_f32 v[16:17], v[16:17], v[48:49]
	v_pk_mul_f32 v[18:19], v[18:19], v[50:51]
	v_pk_mul_f32 v[20:21], v[20:21], v[52:53]
	v_pk_mul_f32 v[22:23], v[22:23], v[54:55]
	v_pk_mul_f32 v[24:25], v[24:25], v[56:57]
	v_pk_mul_f32 v[26:27], v[26:27], v[58:59]
	v_pk_mul_f32 v[28:29], v[28:29], v[60:61]
	v_pk_mul_f32 v[30:31], v[30:31], v[62:63]
	s_add_i32 s39, s15, 14
	s_lshl_b32 s39, s39, 11
	s_add_u32 s90, s0, 0x7b00000
	s_addc_u32 s91, s1, 0
	s_add_u32 s90, s90, s39
	s_addc_u32 s91, s91, 0
	v_lshlrev_b32_e32 v48, 16, v158
	v_and_b32_e32 v49, 0xffff0000, v158
	v_lshlrev_b32_e32 v50, 16, v159
	v_and_b32_e32 v51, 0xffff0000, v159
	v_lshlrev_b32_e32 v52, 16, v160
	v_and_b32_e32 v53, 0xffff0000, v160
	v_lshlrev_b32_e32 v54, 16, v161
	v_and_b32_e32 v55, 0xffff0000, v161
	v_lshlrev_b32_e32 v56, 16, v162
	v_and_b32_e32 v57, 0xffff0000, v162
	v_lshlrev_b32_e32 v58, 16, v163
	v_and_b32_e32 v59, 0xffff0000, v163
	v_lshlrev_b32_e32 v60, 16, v164
	v_and_b32_e32 v61, 0xffff0000, v164
	v_lshlrev_b32_e32 v62, 16, v165
	v_and_b32_e32 v63, 0xffff0000, v165
	v_fma_f32 v47, v15, v250, v31
	v_fma_f32 v46, v14, v47, v30
	v_fma_f32 v45, v13, v46, v29
	v_fma_f32 v44, v12, v45, v28
	v_fma_f32 v43, v11, v44, v27
	v_fma_f32 v42, v10, v43, v26
	v_fma_f32 v41, v9, v42, v25
	v_fma_f32 v40, v8, v41, v24
	v_fma_f32 v39, v7, v40, v23
	v_fma_f32 v38, v6, v39, v22
	v_fma_f32 v37, v5, v38, v21
	v_fma_f32 v36, v4, v37, v20
	v_fma_f32 v35, v3, v36, v19
	v_fma_f32 v34, v2, v35, v18
	v_fma_f32 v33, v1, v34, v17
	v_fma_f32 v32, v0, v33, v16
	v_mov_b32_e32 v250, v32
	v_pk_add_f32 v[48:49], v[48:49], v[32:33]
	v_pk_add_f32 v[50:51], v[50:51], v[34:35]
	v_pk_add_f32 v[52:53], v[52:53], v[36:37]
	v_pk_add_f32 v[54:55], v[54:55], v[38:39]
	v_pk_add_f32 v[56:57], v[56:57], v[40:41]
	v_pk_add_f32 v[58:59], v[58:59], v[42:43]
	v_pk_add_f32 v[60:61], v[60:61], v[44:45]
	v_pk_add_f32 v[62:63], v[62:63], v[46:47]
	v_pk_mul_f32 v[48:49], v[206:207], v[48:49]
	v_pk_mul_f32 v[50:51], v[208:209], v[50:51]
	v_pk_mul_f32 v[52:53], v[210:211], v[52:53]
	v_pk_mul_f32 v[54:55], v[212:213], v[54:55]
	v_pk_mul_f32 v[56:57], v[214:215], v[56:57]
	v_pk_mul_f32 v[58:59], v[216:217], v[58:59]
	v_pk_mul_f32 v[60:61], v[218:219], v[60:61]
	v_pk_mul_f32 v[62:63], v[222:223], v[62:63]
	v_cvt_pk_bf16_f32 v48, v48, v49
	v_cvt_pk_bf16_f32 v50, v50, v51
	v_cvt_pk_bf16_f32 v52, v52, v53
	v_cvt_pk_bf16_f32 v54, v54, v55
	v_cvt_pk_bf16_f32 v56, v56, v57
	v_cvt_pk_bf16_f32 v58, v58, v59
	v_cvt_pk_bf16_f32 v60, v60, v61
	v_cvt_pk_bf16_f32 v62, v62, v63
	global_store_short_d16_hi v234, v62, s[90:91] offset:2048
	global_store_short v234, v62, s[90:91]
	s_sub_u32 s90, s90, 0x1000
	s_subb_u32 s91, s91, 0
	global_store_short_d16_hi v234, v60, s[90:91] offset:2048
	global_store_short v234, v60, s[90:91]
	s_sub_u32 s90, s90, 0x1000
	s_subb_u32 s91, s91, 0
	global_store_short_d16_hi v234, v58, s[90:91] offset:2048
	global_store_short v234, v58, s[90:91]
	s_sub_u32 s90, s90, 0x1000
	s_subb_u32 s91, s91, 0
	global_store_short_d16_hi v234, v56, s[90:91] offset:2048
	global_store_short v234, v56, s[90:91]
	s_sub_u32 s90, s90, 0x1000
	s_subb_u32 s91, s91, 0
	global_store_short_d16_hi v234, v54, s[90:91] offset:2048
	global_store_short v234, v54, s[90:91]
	s_sub_u32 s90, s90, 0x1000
	s_subb_u32 s91, s91, 0
	global_store_short_d16_hi v234, v52, s[90:91] offset:2048
	global_store_short v234, v52, s[90:91]
	s_sub_u32 s90, s90, 0x1000
	s_subb_u32 s91, s91, 0
	global_store_short_d16_hi v234, v50, s[90:91] offset:2048
	global_store_short v234, v50, s[90:91]
	s_sub_u32 s90, s90, 0x1000
	s_subb_u32 s91, s91, 0
	global_store_short_d16_hi v234, v48, s[90:91] offset:2048
	global_store_short v234, v48, s[90:91]
	s_waitcnt lgkmcnt(0)
	v_readlane_b32 s84, v253, 29
	s_add_i32 s12, s12, s84
	s_cmpk_lt_i32 s12, 0x1000
	s_cbranch_scc1 .Lrg7_keep
	s_sub_i32 s0, s12, 0x1000
	s_lshr_b32 s1, s0, 5
	s_and_b32 s0, s0, 31
	s_and_b32 s12, s1, 7
	s_add_i32 s1, s1, 0x1000
	s_cmp_eq_u32 s0, s12
	s_cselect_b32 s12, s1, 0x2000
